# pool tile loops: software-pipelined PT fragment reads in the MFMA phase (4 extra fragment buffers)
# speedup vs baseline: 1.0198x; 1.0026x over previous
.LBB0_124:
	s_cmp_lg_u32 s42, 0x1c0000
	s_cselect_b32 s0, s11, 7
	s_add_i32 s0, s0, s10
	s_lshl_b32 s0, s0, 6
	s_and_b32 s2, s0, 0xfc0
	s_and_b32 s0, s0, 0xfffff000
	s_ashr_i32 s1, s0, 31
	v_add_u32_e32 v84, s2, v144
	s_lshl_b64 s[0:1], s[0:1], 11
	v_ashrrev_i32_e32 v85, 31, v84
	v_lshl_add_u64 v[82:83], v[138:139], 0, s[0:1]
	v_lshlrev_b64 v[84:85], 11, v[84:85]
	s_waitcnt lgkmcnt(0)
	s_barrier
	v_lshl_add_u64 v[84:85], v[82:83], 0, v[84:85]
	global_load_dwordx4 v[102:105], v[84:85], off offset:1536
	v_add_u32_e32 v84, s2, v145
	v_ashrrev_i32_e32 v85, 31, v84
	v_lshlrev_b64 v[84:85], 11, v[84:85]
	v_lshl_add_u64 v[84:85], v[82:83], 0, v[84:85]
	global_load_dwordx4 v[106:109], v[84:85], off offset:1536
	v_add_u32_e32 v84, s2, v146
	v_ashrrev_i32_e32 v85, 31, v84
	v_lshlrev_b64 v[84:85], 11, v[84:85]
	v_lshl_add_u64 v[84:85], v[82:83], 0, v[84:85]
	global_load_dwordx4 v[110:113], v[84:85], off offset:1536
	v_add_u32_e32 v84, s2, v147
	ds_read_b128 v[118:121], v153 offset:33792
	ds_read_b128 v[134:137], v154 offset:528
	v_ashrrev_i32_e32 v85, 31, v84
	ds_read_b128 v[160:163], v154 offset:1056
	ds_read_b128 v[164:167], v154 offset:1584
	v_lshlrev_b64 v[84:85], 11, v[84:85]
	v_lshl_add_u64 v[82:83], v[82:83], 0, v[84:85]
	v_or_b32_e32 v0, s2, v148
	ds_read_b128 v[168:171], v154 offset:2112
	ds_read_b128 v[172:175], v154 offset:2640
	global_load_dwordx4 v[114:117], v[82:83], off offset:1536
	v_lshl_add_u64 v[82:83], v[140:141], 0, s[0:1]
	v_lshlrev_b32_e32 v0, 11, v0
	v_lshl_add_u64 v[94:95], v[82:83], 0, v[0:1]
	s_waitcnt lgkmcnt(4)
	v_lshlrev_b32_e32 v0, 16, v134
	ds_read_b128 v[176:179], v154 offset:3168
	ds_read_b128 v[180:183], v154 offset:3696
	v_add_f32_e32 v0, 0, v0
	s_waitcnt lgkmcnt(5)
	v_lshlrev_b32_e32 v159, 16, v160
	v_add_f32_e32 v0, v0, v159
	s_waitcnt lgkmcnt(4)
	v_lshlrev_b32_e32 v159, 16, v164
	ds_read_b128 v[190:193], v154 offset:4224
	ds_read_b128 v[200:203], v154 offset:4752
	v_add_f32_e32 v0, v0, v159
	s_waitcnt lgkmcnt(5)
	v_lshlrev_b32_e32 v159, 16, v168
	v_add_f32_e32 v0, v0, v159
	s_waitcnt lgkmcnt(4)
	v_lshlrev_b32_e32 v159, 16, v172
	ds_read_b128 v[204:207], v154 offset:5280
	ds_read_b128 v[208:211], v154 offset:5808
	v_add_f32_e32 v0, v0, v159
	s_waitcnt lgkmcnt(5)
	v_lshlrev_b32_e32 v159, 16, v176
	v_add_f32_e32 v0, v0, v159
	s_waitcnt lgkmcnt(4)
	v_lshlrev_b32_e32 v159, 16, v180
	ds_read_b128 v[212:215], v154 offset:6336
	ds_read_b128 v[216:219], v154 offset:6864
	v_add_f32_e32 v0, v0, v159
	s_waitcnt lgkmcnt(5)
	v_lshlrev_b32_e32 v159, 16, v190
	v_add_f32_e32 v0, v0, v159
	s_waitcnt lgkmcnt(4)
	v_lshlrev_b32_e32 v159, 16, v200
	ds_read_b128 v[220:223], v154 offset:7392
	ds_read_b128 v[224:227], v154 offset:7920
	v_add_f32_e32 v0, v0, v159
	s_waitcnt lgkmcnt(5)
	v_lshlrev_b32_e32 v159, 16, v204
	v_add_f32_e32 v0, v0, v159
	s_waitcnt lgkmcnt(4)
	v_lshlrev_b32_e32 v159, 16, v208
	v_add_f32_e32 v0, v0, v159
	s_waitcnt lgkmcnt(3)
	v_lshlrev_b32_e32 v159, 16, v212
	v_add_f32_e32 v0, v0, v159
	s_waitcnt lgkmcnt(2)
	v_lshlrev_b32_e32 v159, 16, v216
	v_add_f32_e32 v0, v0, v159
	s_waitcnt lgkmcnt(1)
	v_lshlrev_b32_e32 v159, 16, v220
	v_add_f32_e32 v0, v0, v159
	s_waitcnt lgkmcnt(0)
	v_lshlrev_b32_e32 v159, 16, v224
	v_and_b32_e32 v134, 0xffff0000, v134
	v_add_f32_e32 v0, v0, v159
	v_add_f32_e32 v134, 0, v134
	v_and_b32_e32 v159, 0xffff0000, v160
	v_add_f32_e32 v134, v134, v159
	v_and_b32_e32 v159, 0xffff0000, v164
	v_add_f32_e32 v134, v134, v159
	v_and_b32_e32 v159, 0xffff0000, v168
	v_add_f32_e32 v134, v134, v159
	v_and_b32_e32 v159, 0xffff0000, v172
	v_add_f32_e32 v134, v134, v159
	v_and_b32_e32 v159, 0xffff0000, v176
	v_add_f32_e32 v134, v134, v159
	v_and_b32_e32 v159, 0xffff0000, v180
	v_add_f32_e32 v134, v134, v159
	v_and_b32_e32 v159, 0xffff0000, v190
	v_add_f32_e32 v134, v134, v159
	v_and_b32_e32 v159, 0xffff0000, v200
	v_add_f32_e32 v134, v134, v159
	v_and_b32_e32 v159, 0xffff0000, v204
	v_add_f32_e32 v134, v134, v159
	v_and_b32_e32 v159, 0xffff0000, v208
	v_add_f32_e32 v134, v134, v159
	v_and_b32_e32 v159, 0xffff0000, v212
	v_add_f32_e32 v134, v134, v159
	v_and_b32_e32 v159, 0xffff0000, v216
	v_add_f32_e32 v134, v134, v159
	v_and_b32_e32 v159, 0xffff0000, v220
	v_add_f32_e32 v134, v134, v159
	v_and_b32_e32 v159, 0xffff0000, v224
	v_add_f32_e32 v159, v134, v159
	v_lshlrev_b32_e32 v134, 16, v135
	v_add_f32_e32 v134, 0, v134
	v_lshlrev_b32_e32 v160, 16, v161
	v_add_f32_e32 v134, v134, v160
	v_lshlrev_b32_e32 v160, 16, v165
	v_add_f32_e32 v134, v134, v160
	v_lshlrev_b32_e32 v160, 16, v169
	v_add_f32_e32 v134, v134, v160
	v_lshlrev_b32_e32 v160, 16, v173
	v_add_f32_e32 v134, v134, v160
	v_lshlrev_b32_e32 v160, 16, v177
	v_add_f32_e32 v134, v134, v160
	v_lshlrev_b32_e32 v160, 16, v181
	v_add_f32_e32 v134, v134, v160
	v_lshlrev_b32_e32 v160, 16, v191
	v_add_f32_e32 v134, v134, v160
	v_lshlrev_b32_e32 v160, 16, v201
	v_add_f32_e32 v134, v134, v160
	v_lshlrev_b32_e32 v160, 16, v205
	v_add_f32_e32 v134, v134, v160
	v_lshlrev_b32_e32 v160, 16, v209
	v_add_f32_e32 v134, v134, v160
	v_lshlrev_b32_e32 v160, 16, v213
	v_add_f32_e32 v134, v134, v160
	v_lshlrev_b32_e32 v160, 16, v217
	v_add_f32_e32 v134, v134, v160
	v_lshlrev_b32_e32 v160, 16, v221
	v_add_f32_e32 v134, v134, v160
	v_lshlrev_b32_e32 v160, 16, v225
	v_add_f32_e32 v160, v134, v160
	v_and_b32_e32 v134, 0xffff0000, v135
	v_add_f32_e32 v134, 0, v134
	v_and_b32_e32 v135, 0xffff0000, v161
	v_add_f32_e32 v134, v134, v135
	v_and_b32_e32 v135, 0xffff0000, v165
	v_add_f32_e32 v134, v134, v135
	v_and_b32_e32 v135, 0xffff0000, v169
	v_add_f32_e32 v134, v134, v135
	v_and_b32_e32 v135, 0xffff0000, v173
	v_add_f32_e32 v134, v134, v135
	v_and_b32_e32 v135, 0xffff0000, v177
	v_add_f32_e32 v134, v134, v135
	v_and_b32_e32 v135, 0xffff0000, v181
	v_add_f32_e32 v134, v134, v135
	v_and_b32_e32 v135, 0xffff0000, v191
	v_add_f32_e32 v134, v134, v135
	v_and_b32_e32 v135, 0xffff0000, v201
	v_add_f32_e32 v134, v134, v135
	v_and_b32_e32 v135, 0xffff0000, v205
	v_add_f32_e32 v134, v134, v135
	v_and_b32_e32 v135, 0xffff0000, v209
	v_add_f32_e32 v134, v134, v135
	v_and_b32_e32 v135, 0xffff0000, v213
	v_add_f32_e32 v134, v134, v135
	v_and_b32_e32 v135, 0xffff0000, v217
	v_add_f32_e32 v134, v134, v135
	v_and_b32_e32 v135, 0xffff0000, v221
	v_add_f32_e32 v134, v134, v135
	v_and_b32_e32 v135, 0xffff0000, v225
	v_add_f32_e32 v161, v134, v135
	v_lshlrev_b32_e32 v134, 16, v136
	v_add_f32_e32 v134, 0, v134
	v_lshlrev_b32_e32 v135, 16, v162
	v_add_f32_e32 v134, v134, v135
	v_lshlrev_b32_e32 v135, 16, v166
	v_add_f32_e32 v134, v134, v135
	v_lshlrev_b32_e32 v135, 16, v170
	v_add_f32_e32 v134, v134, v135
	v_lshlrev_b32_e32 v135, 16, v174
	v_add_f32_e32 v134, v134, v135
	v_lshlrev_b32_e32 v135, 16, v178
	v_add_f32_e32 v134, v134, v135
	v_lshlrev_b32_e32 v135, 16, v182
	v_add_f32_e32 v134, v134, v135
	v_lshlrev_b32_e32 v135, 16, v192
	v_add_f32_e32 v134, v134, v135
	v_lshlrev_b32_e32 v135, 16, v202
	v_add_f32_e32 v134, v134, v135
	v_lshlrev_b32_e32 v135, 16, v206
	v_add_f32_e32 v134, v134, v135
	v_lshlrev_b32_e32 v135, 16, v210
	v_add_f32_e32 v134, v134, v135
	v_lshlrev_b32_e32 v135, 16, v214
	v_add_f32_e32 v134, v134, v135
	v_lshlrev_b32_e32 v135, 16, v218
	v_add_f32_e32 v134, v134, v135
	v_lshlrev_b32_e32 v135, 16, v222
	v_add_f32_e32 v134, v134, v135
	v_lshlrev_b32_e32 v135, 16, v226
	v_add_f32_e32 v164, v134, v135
	v_and_b32_e32 v134, 0xffff0000, v136
	v_add_f32_e32 v134, 0, v134
	v_and_b32_e32 v135, 0xffff0000, v162
	v_add_f32_e32 v134, v134, v135
	v_and_b32_e32 v135, 0xffff0000, v166
	v_add_f32_e32 v134, v134, v135
	v_and_b32_e32 v135, 0xffff0000, v170
	v_add_f32_e32 v134, v134, v135
	v_and_b32_e32 v135, 0xffff0000, v174
	v_add_f32_e32 v134, v134, v135
	v_and_b32_e32 v135, 0xffff0000, v178
	v_add_f32_e32 v134, v134, v135
	v_and_b32_e32 v135, 0xffff0000, v182
	v_add_f32_e32 v134, v134, v135
	v_and_b32_e32 v135, 0xffff0000, v192
	v_add_f32_e32 v134, v134, v135
	v_and_b32_e32 v135, 0xffff0000, v202
	v_add_f32_e32 v134, v134, v135
	v_and_b32_e32 v135, 0xffff0000, v206
	v_add_f32_e32 v134, v134, v135
	v_and_b32_e32 v135, 0xffff0000, v210
	v_add_f32_e32 v134, v134, v135
	v_and_b32_e32 v135, 0xffff0000, v214
	v_add_f32_e32 v134, v134, v135
	v_and_b32_e32 v135, 0xffff0000, v218
	v_add_f32_e32 v134, v134, v135
	v_and_b32_e32 v135, 0xffff0000, v222
	v_add_f32_e32 v134, v134, v135
	v_and_b32_e32 v135, 0xffff0000, v226
	v_add_f32_e32 v162, v134, v135
	v_lshlrev_b32_e32 v134, 16, v137
	v_add_f32_e32 v134, 0, v134
	v_lshlrev_b32_e32 v135, 16, v163
	v_add_f32_e32 v134, v134, v135
	v_lshlrev_b32_e32 v135, 16, v167
	v_add_f32_e32 v134, v134, v135
	v_lshlrev_b32_e32 v135, 16, v171
	v_add_f32_e32 v134, v134, v135
	v_lshlrev_b32_e32 v135, 16, v175
	v_add_f32_e32 v134, v134, v135
	v_lshlrev_b32_e32 v135, 16, v179
	v_add_f32_e32 v134, v134, v135
	v_lshlrev_b32_e32 v135, 16, v183
	v_add_f32_e32 v134, v134, v135
	v_lshlrev_b32_e32 v135, 16, v193
	v_add_f32_e32 v134, v134, v135
	v_lshlrev_b32_e32 v135, 16, v203
	v_add_f32_e32 v134, v134, v135
	v_lshlrev_b32_e32 v135, 16, v207
	v_add_f32_e32 v134, v134, v135
	v_lshlrev_b32_e32 v135, 16, v211
	v_add_f32_e32 v134, v134, v135
	v_lshlrev_b32_e32 v135, 16, v215
	v_add_f32_e32 v134, v134, v135
	v_lshlrev_b32_e32 v135, 16, v219
	v_add_f32_e32 v134, v134, v135
	v_lshlrev_b32_e32 v135, 16, v223
	v_add_f32_e32 v134, v134, v135
	v_lshlrev_b32_e32 v135, 16, v227
	v_add_f32_e32 v165, v134, v135
	v_and_b32_e32 v134, 0xffff0000, v137
	v_add_f32_e32 v134, 0, v134
	v_and_b32_e32 v135, 0xffff0000, v163
	v_add_f32_e32 v134, v134, v135
	v_and_b32_e32 v135, 0xffff0000, v167
	v_add_f32_e32 v134, v134, v135
	v_and_b32_e32 v135, 0xffff0000, v171
	v_add_f32_e32 v134, v134, v135
	v_and_b32_e32 v135, 0xffff0000, v175
	v_add_f32_e32 v134, v134, v135
	v_and_b32_e32 v135, 0xffff0000, v179
	v_add_f32_e32 v134, v134, v135
	v_and_b32_e32 v135, 0xffff0000, v183
	v_add_f32_e32 v134, v134, v135
	v_and_b32_e32 v135, 0xffff0000, v193
	v_add_f32_e32 v134, v134, v135
	v_and_b32_e32 v135, 0xffff0000, v203
	v_add_f32_e32 v134, v134, v135
	v_and_b32_e32 v135, 0xffff0000, v207
	v_add_f32_e32 v134, v134, v135
	v_and_b32_e32 v135, 0xffff0000, v211
	v_add_f32_e32 v134, v134, v135
	v_and_b32_e32 v135, 0xffff0000, v215
	v_add_f32_e32 v134, v134, v135
	v_and_b32_e32 v135, 0xffff0000, v219
	v_min_i32_e32 v170, 15, v157
	v_add_f32_e32 v134, v134, v135
	v_and_b32_e32 v135, 0xffff0000, v223
	v_add_u32_e32 v170, 1, v170
	v_add_f32_e32 v134, v134, v135
	v_and_b32_e32 v135, 0xffff0000, v227
	v_cvt_f32_i32_e32 v170, v170
	v_add_f32_e32 v163, v134, v135
	ds_read_b128 v[134:137], v158 offset:8448
	v_add_co_u32_e32 v86, vcc, s97, v94
	v_rcp_iflag_f32_e32 v170, v170
	s_nop 0
	v_addc_co_u32_e32 v87, vcc, 0, v95, vcc
	v_add_co_u32_e32 v90, vcc, s4, v94
	s_waitcnt lgkmcnt(0)
	v_lshlrev_b32_e32 v166, 16, v134
	v_addc_co_u32_e32 v91, vcc, 0, v95, vcc
	v_and_b32_e32 v134, 0xffff0000, v134
	v_lshlrev_b32_e32 v167, 16, v135
	v_and_b32_e32 v135, 0xffff0000, v135
	v_lshlrev_b32_e32 v168, 16, v136
	v_and_b32_e32 v136, 0xffff0000, v136
	v_lshlrev_b32_e32 v169, 16, v137
	v_and_b32_e32 v137, 0xffff0000, v137
	global_load_dwordx4 v[82:85], v[94:95], off offset:1536
	v_add_co_u32_e32 v94, vcc, s96, v94
	v_add_f32_e32 v159, v159, v134
	v_add_f32_e32 v161, v161, v135
	v_add_f32_e32 v162, v162, v136
	v_add_f32_e32 v163, v163, v137
	v_addc_co_u32_e32 v95, vcc, 0, v95, vcc
	v_add_f32_e32 v0, v0, v166
	v_fma_f32 v134, v159, v170, -v134
	v_add_f32_e32 v160, v160, v167
	v_fma_f32 v135, v161, v170, -v135
	v_add_f32_e32 v164, v164, v168
	v_fma_f32 v136, v162, v170, -v136
	v_add_f32_e32 v165, v165, v169
	v_fma_f32 v137, v163, v170, -v137
	global_load_dwordx4 v[86:89], v[86:87], off offset:1536
	v_fma_f32 v166, v0, v170, -v166
	global_load_dwordx4 v[90:93], v[90:91], off offset:1536
	v_fma_f32 v167, v160, v170, -v167
	global_load_dwordx4 v[94:97], v[94:95], off offset:1536
	v_fma_f32 v168, v164, v170, -v168
	v_fma_f32 v169, v165, v170, -v169
	v_cvt_pk_bf16_f32 v134, v166, v134
	v_cvt_pk_bf16_f32 v135, v167, v135
	v_cvt_pk_bf16_f32 v136, v168, v136
	v_cvt_pk_bf16_f32 v137, v169, v137
	ds_write_b128 v154, v[134:137] offset:42240
	ds_read_b128 v[134:137], v158 offset:528
	v_add_u32_e32 v170, 1, v157
	v_min_i32_e32 v170, 15, v170
	v_add_u32_e32 v170, 1, v170
	v_cvt_f32_i32_e32 v170, v170
	s_waitcnt lgkmcnt(0)
	v_lshlrev_b32_e32 v166, 16, v134
	v_and_b32_e32 v134, 0xffff0000, v134
	v_sub_f32_e32 v159, v159, v134
	v_lshlrev_b32_e32 v134, 16, v135
	v_sub_f32_e32 v160, v160, v134
	v_and_b32_e32 v134, 0xffff0000, v135
	v_sub_f32_e32 v161, v161, v134
	v_lshlrev_b32_e32 v134, 16, v136
	v_sub_f32_e32 v164, v164, v134
	v_and_b32_e32 v134, 0xffff0000, v136
	v_sub_f32_e32 v162, v162, v134
	v_lshlrev_b32_e32 v134, 16, v137
	v_sub_f32_e32 v165, v165, v134
	v_and_b32_e32 v134, 0xffff0000, v137
	v_sub_f32_e32 v163, v163, v134
	ds_read_b128 v[134:137], v158 offset:8976
	v_rcp_iflag_f32_e32 v170, v170
	v_sub_f32_e32 v0, v0, v166
	s_waitcnt lgkmcnt(0)
	v_lshlrev_b32_e32 v166, 16, v134
	v_and_b32_e32 v134, 0xffff0000, v134
	v_lshlrev_b32_e32 v167, 16, v135
	v_and_b32_e32 v135, 0xffff0000, v135
	v_lshlrev_b32_e32 v168, 16, v136
	v_and_b32_e32 v136, 0xffff0000, v136
	v_lshlrev_b32_e32 v169, 16, v137
	v_and_b32_e32 v137, 0xffff0000, v137
	v_add_f32_e32 v159, v159, v134
	v_add_f32_e32 v161, v161, v135
	v_add_f32_e32 v162, v162, v136
	v_add_f32_e32 v163, v163, v137
	v_add_f32_e32 v0, v0, v166
	v_fma_f32 v134, v159, v170, -v134
	v_add_f32_e32 v160, v160, v167
	v_fma_f32 v135, v161, v170, -v135
	v_add_f32_e32 v164, v164, v168
	v_fma_f32 v136, v162, v170, -v136
	v_add_f32_e32 v165, v165, v169
	v_fma_f32 v137, v163, v170, -v137
	v_fma_f32 v166, v0, v170, -v166
	v_fma_f32 v167, v160, v170, -v167
	v_fma_f32 v168, v164, v170, -v168
	v_fma_f32 v169, v165, v170, -v169
	v_cvt_pk_bf16_f32 v134, v166, v134
	v_cvt_pk_bf16_f32 v135, v167, v135
	v_cvt_pk_bf16_f32 v136, v168, v136
	v_cvt_pk_bf16_f32 v137, v169, v137
	ds_write_b128 v154, v[134:137] offset:42768
	ds_read_b128 v[134:137], v158 offset:1056
	v_add_u32_e32 v170, 2, v157
	v_min_i32_e32 v170, 15, v170
	v_add_u32_e32 v170, 1, v170
	v_cvt_f32_i32_e32 v170, v170
	s_waitcnt lgkmcnt(0)
	v_lshlrev_b32_e32 v166, 16, v134
	v_and_b32_e32 v134, 0xffff0000, v134
	v_sub_f32_e32 v159, v159, v134
	v_lshlrev_b32_e32 v134, 16, v135
	v_sub_f32_e32 v160, v160, v134
	v_and_b32_e32 v134, 0xffff0000, v135
	v_sub_f32_e32 v161, v161, v134
	v_lshlrev_b32_e32 v134, 16, v136
	v_sub_f32_e32 v164, v164, v134
	v_and_b32_e32 v134, 0xffff0000, v136
	v_sub_f32_e32 v162, v162, v134
	v_lshlrev_b32_e32 v134, 16, v137
	v_sub_f32_e32 v165, v165, v134
	v_and_b32_e32 v134, 0xffff0000, v137
	v_sub_f32_e32 v163, v163, v134
	ds_read_b128 v[134:137], v158 offset:9504
	v_rcp_iflag_f32_e32 v170, v170
	v_sub_f32_e32 v0, v0, v166
	s_waitcnt lgkmcnt(0)
	v_lshlrev_b32_e32 v166, 16, v134
	v_and_b32_e32 v134, 0xffff0000, v134
	v_lshlrev_b32_e32 v167, 16, v135
	v_and_b32_e32 v135, 0xffff0000, v135
	v_lshlrev_b32_e32 v168, 16, v136
	v_and_b32_e32 v136, 0xffff0000, v136
	v_lshlrev_b32_e32 v169, 16, v137
	v_and_b32_e32 v137, 0xffff0000, v137
	v_add_f32_e32 v159, v159, v134
	v_add_f32_e32 v161, v161, v135
	v_add_f32_e32 v162, v162, v136
	v_add_f32_e32 v163, v163, v137
	v_add_f32_e32 v0, v0, v166
	v_fma_f32 v134, v159, v170, -v134
	v_add_f32_e32 v160, v160, v167
	v_fma_f32 v135, v161, v170, -v135
	v_add_f32_e32 v164, v164, v168
	v_fma_f32 v136, v162, v170, -v136
	v_add_f32_e32 v165, v165, v169
	v_fma_f32 v137, v163, v170, -v137
	v_fma_f32 v166, v0, v170, -v166
	v_fma_f32 v167, v160, v170, -v167
	v_fma_f32 v168, v164, v170, -v168
	v_fma_f32 v169, v165, v170, -v169
	v_cvt_pk_bf16_f32 v134, v166, v134
	v_cvt_pk_bf16_f32 v135, v167, v135
	v_cvt_pk_bf16_f32 v136, v168, v136
	v_cvt_pk_bf16_f32 v137, v169, v137
	ds_write_b128 v154, v[134:137] offset:43296
	ds_read_b128 v[134:137], v158 offset:1584
	v_add_u32_e32 v170, 3, v157
	v_min_i32_e32 v170, 15, v170
	v_add_u32_e32 v170, 1, v170
	v_cvt_f32_i32_e32 v170, v170
	s_waitcnt lgkmcnt(0)
	v_lshlrev_b32_e32 v166, 16, v134
	v_and_b32_e32 v134, 0xffff0000, v134
	v_sub_f32_e32 v159, v159, v134
	v_lshlrev_b32_e32 v134, 16, v135
	v_sub_f32_e32 v160, v160, v134
	v_and_b32_e32 v134, 0xffff0000, v135
	v_sub_f32_e32 v161, v161, v134
	v_lshlrev_b32_e32 v134, 16, v136
	v_sub_f32_e32 v164, v164, v134
	v_and_b32_e32 v134, 0xffff0000, v136
	v_sub_f32_e32 v162, v162, v134
	v_lshlrev_b32_e32 v134, 16, v137
	v_sub_f32_e32 v165, v165, v134
	v_and_b32_e32 v134, 0xffff0000, v137
	v_sub_f32_e32 v163, v163, v134
	ds_read_b128 v[134:137], v158 offset:10032
	v_rcp_iflag_f32_e32 v170, v170
	v_sub_f32_e32 v0, v0, v166
	v_add_u32_e32 v157, 64, v157
	s_waitcnt lgkmcnt(0)
	v_lshlrev_b32_e32 v166, 16, v134
	v_and_b32_e32 v134, 0xffff0000, v134
	v_lshlrev_b32_e32 v167, 16, v135
	v_and_b32_e32 v135, 0xffff0000, v135
	v_lshlrev_b32_e32 v168, 16, v136
	v_and_b32_e32 v136, 0xffff0000, v136
	v_lshlrev_b32_e32 v169, 16, v137
	v_and_b32_e32 v137, 0xffff0000, v137
	v_add_f32_e32 v159, v159, v134
	v_fma_f32 v134, v159, v170, -v134
	v_add_f32_e32 v159, v160, v167
	v_add_f32_e32 v160, v161, v135
	v_add_f32_e32 v161, v162, v136
	v_add_f32_e32 v162, v163, v137
	v_add_f32_e32 v0, v0, v166
	v_fma_f32 v135, v160, v170, -v135
	v_add_f32_e32 v160, v164, v168
	v_fma_f32 v136, v161, v170, -v136
	v_add_f32_e32 v161, v165, v169
	v_fma_f32 v137, v162, v170, -v137
	v_fma_f32 v0, v0, v170, -v166
	v_fma_f32 v159, v159, v170, -v167
	v_fma_f32 v160, v160, v170, -v168
	v_fma_f32 v161, v161, v170, -v169
	v_cvt_pk_bf16_f32 v134, v0, v134
	v_cvt_pk_bf16_f32 v135, v159, v135
	v_cvt_pk_bf16_f32 v136, v160, v136
	v_cvt_pk_bf16_f32 v137, v161, v137
	ds_write_b128 v154, v[134:137] offset:43824
	s_waitcnt lgkmcnt(0)
	s_barrier
	ds_read_b128 v[134:137], v155 offset:42240
	ds_read_b128 v[164:167], v155 offset:42304
	ds_read_b128 v[238:241], v155 offset:42368
	ds_read_b128 v[242:245], v155 offset:42432
	ds_read_b128 v[246:249], v155 offset:42496
	ds_read_b128 v[228:231], v155 offset:42560
	s_waitcnt lgkmcnt(5)
	v_mfma_f32_16x16x32_bf16 v[160:163], v[2:5], v[134:137], 0
	v_mfma_f32_16x16x32_bf16 v[134:137], v[34:37], v[134:137], 0
	s_waitcnt lgkmcnt(4)
	v_mfma_f32_16x16x32_bf16 v[160:163], v[6:9], v[164:167], v[160:163]
	v_mfma_f32_16x16x32_bf16 v[134:137], v[38:41], v[164:167], v[134:137]
	ds_read_b128 v[164:167], v155 offset:42624
	s_waitcnt lgkmcnt(4)
	v_mfma_f32_16x16x32_bf16 v[160:163], v[10:13], v[238:241], v[160:163]
	v_mfma_f32_16x16x32_bf16 v[134:137], v[42:45], v[238:241], v[134:137]
	ds_read_b128 v[238:241], v155 offset:42688
	s_waitcnt lgkmcnt(4)
	v_mfma_f32_16x16x32_bf16 v[160:163], v[14:17], v[242:245], v[160:163]
	v_mfma_f32_16x16x32_bf16 v[134:137], v[46:49], v[242:245], v[134:137]
	s_waitcnt lgkmcnt(3)
	v_mfma_f32_16x16x32_bf16 v[160:163], v[18:21], v[246:249], v[160:163]
	v_mfma_f32_16x16x32_bf16 v[134:137], v[50:53], v[246:249], v[134:137]
	s_waitcnt lgkmcnt(2)
	v_mfma_f32_16x16x32_bf16 v[160:163], v[22:25], v[228:231], v[160:163]
	v_mfma_f32_16x16x32_bf16 v[134:137], v[54:57], v[228:231], v[134:137]
	s_waitcnt lgkmcnt(1)
	v_mfma_f32_16x16x32_bf16 v[160:163], v[26:29], v[164:167], v[160:163]
	v_mfma_f32_16x16x32_bf16 v[134:137], v[58:61], v[164:167], v[134:137]
	s_waitcnt lgkmcnt(0)
	v_mfma_f32_16x16x32_bf16 v[160:163], v[30:33], v[238:241], v[160:163]
	v_mfma_f32_16x16x32_bf16 v[134:137], v[62:65], v[238:241], v[134:137]
	s_nop 6
	v_add_f32_e32 v163, v73, v163
	v_add_f32_e32 v0, v72, v162
	v_and_b32_e32 v162, 0xffff0000, v131
	v_add_f32_e32 v159, v71, v161
	v_mul_f32_e32 v161, v81, v163
	v_mul_f32_e32 v163, 0xbfb8aa3b, v162
	v_exp_f32_e32 v163, v163
	v_add_f32_e32 v160, v70, v160
	v_mul_f32_e32 v160, v78, v160
	v_mul_f32_e32 v159, v79, v159
	v_add_f32_e32 v163, 1.0, v163
	v_rcp_f32_e32 v163, v163
	v_lshlrev_b32_e32 v131, 16, v131
	v_mul_f32_e32 v0, v80, v0
	v_add_f32_e32 v134, v66, v134
	v_mul_f32_e32 v162, v163, v162
	v_mul_f32_e32 v161, v162, v161
	v_lshlrev_b32_e32 v162, 16, v130
	v_mul_f32_e32 v163, 0xbfb8aa3b, v162
	v_exp_f32_e32 v163, v163
	v_and_b32_e32 v130, 0xffff0000, v130
	v_mul_f32_e32 v134, v74, v134
	v_add_f32_e32 v135, v67, v135
	v_add_f32_e32 v163, 1.0, v163
	v_rcp_f32_e32 v163, v163
	v_mul_f32_e32 v135, v75, v135
	v_add_f32_e32 v136, v68, v136
	v_mul_f32_e32 v136, v76, v136
	v_mul_f32_e32 v162, v163, v162
	v_mul_f32_e32 v160, v162, v160
	v_mul_f32_e32 v162, 0xbfb8aa3b, v130
	v_exp_f32_e32 v162, v162
	s_nop 0
	v_add_f32_e32 v162, 1.0, v162
	v_rcp_f32_e32 v162, v162
	s_nop 0
	v_mul_f32_e32 v130, v162, v130
	v_mul_f32_e32 v130, v130, v159
	v_mul_f32_e32 v159, 0xbfb8aa3b, v131
	v_exp_f32_e32 v159, v159
	v_cvt_pk_bf16_f32 v130, v160, v130
	s_nop 0
	v_add_f32_e32 v159, 1.0, v159
	v_rcp_f32_e32 v159, v159
	s_nop 0
	v_mul_f32_e32 v131, v159, v131
	v_mul_f32_e32 v0, v131, v0
	v_cvt_pk_bf16_f32 v131, v0, v161
	v_add_f32_e32 v0, v69, v137
	v_and_b32_e32 v137, 0xffff0000, v133
	v_mul_f32_e32 v159, 0xbfb8aa3b, v137
	v_exp_f32_e32 v159, v159
	v_mul_f32_e32 v0, v77, v0
	v_lshlrev_b32_e32 v133, 16, v133
	v_add_f32_e32 v159, 1.0, v159
	v_rcp_f32_e32 v159, v159
	s_nop 0
	v_mul_f32_e32 v137, v159, v137
	v_mul_f32_e32 v0, v137, v0
	v_lshlrev_b32_e32 v137, 16, v132
	v_mul_f32_e32 v159, 0xbfb8aa3b, v137
	v_exp_f32_e32 v159, v159
	v_and_b32_e32 v132, 0xffff0000, v132
	v_add_f32_e32 v159, 1.0, v159
	v_rcp_f32_e32 v159, v159
	s_nop 0
	v_mul_f32_e32 v137, v159, v137
	v_mul_f32_e32 v134, v137, v134
	v_mul_f32_e32 v137, 0xbfb8aa3b, v132
	v_exp_f32_e32 v137, v137
	s_nop 0
	v_add_f32_e32 v137, 1.0, v137
	v_rcp_f32_e32 v137, v137
	s_nop 0
	v_mul_f32_e32 v132, v137, v132
	v_mul_f32_e32 v132, v132, v135
	v_mul_f32_e32 v135, 0xbfb8aa3b, v133
	v_exp_f32_e32 v135, v135
	v_cvt_pk_bf16_f32 v132, v134, v132
	s_nop 0
	v_add_f32_e32 v135, 1.0, v135
	v_rcp_f32_e32 v135, v135
	s_nop 0
	v_mul_f32_e32 v133, v135, v133
	v_lshl_add_u64 v[134:135], v[142:143], 0, s[42:43]
	v_mul_f32_e32 v133, v133, v136
	v_add_co_u32_e32 v136, vcc, s9, v134
	v_cvt_pk_bf16_f32 v133, v133, v0
	ds_read_b128 v[164:167], v155 offset:50752
	s_nop 0
	v_addc_co_u32_e32 v137, vcc, 0, v135, vcc
	global_store_dwordx4 v[136:137], v[130:133], off offset:3584
	ds_read_b128 v[130:133], v155 offset:50688
	ds_read_b128 v[238:241], v155 offset:50816
	ds_read_b128 v[242:245], v155 offset:50880
	ds_read_b128 v[246:249], v155 offset:50944
	ds_read_b128 v[228:231], v155 offset:51008
	s_waitcnt lgkmcnt(4)
	v_mfma_f32_16x16x32_bf16 v[160:163], v[2:5], v[130:133], 0
	s_add_u32 s42, s42, 0x40000
	s_addc_u32 s43, s43, 0
	s_add_i32 s11, s11, 1
	v_mfma_f32_16x16x32_bf16 v[130:133], v[34:37], v[130:133], 0
	s_cmp_lg_u32 s42, 0x200000
	s_waitcnt lgkmcnt(5)
	v_mfma_f32_16x16x32_bf16 v[160:163], v[6:9], v[164:167], v[160:163]
	v_mfma_f32_16x16x32_bf16 v[130:133], v[38:41], v[164:167], v[130:133]
	ds_read_b128 v[164:167], v155 offset:51072
	s_waitcnt lgkmcnt(4)
	v_mfma_f32_16x16x32_bf16 v[160:163], v[10:13], v[238:241], v[160:163]
	v_mfma_f32_16x16x32_bf16 v[130:133], v[42:45], v[238:241], v[130:133]
	ds_read_b128 v[238:241], v155 offset:51136
	s_waitcnt lgkmcnt(4)
	v_mfma_f32_16x16x32_bf16 v[160:163], v[14:17], v[242:245], v[160:163]
	v_mfma_f32_16x16x32_bf16 v[130:133], v[46:49], v[242:245], v[130:133]
	s_waitcnt lgkmcnt(3)
	v_mfma_f32_16x16x32_bf16 v[160:163], v[18:21], v[246:249], v[160:163]
	v_mfma_f32_16x16x32_bf16 v[130:133], v[50:53], v[246:249], v[130:133]
	s_waitcnt lgkmcnt(2)
	v_mfma_f32_16x16x32_bf16 v[160:163], v[22:25], v[228:231], v[160:163]
	v_mfma_f32_16x16x32_bf16 v[130:133], v[54:57], v[228:231], v[130:133]
	s_waitcnt lgkmcnt(1)
	v_mfma_f32_16x16x32_bf16 v[160:163], v[26:29], v[164:167], v[160:163]
	v_mfma_f32_16x16x32_bf16 v[130:133], v[58:61], v[164:167], v[130:133]
	s_waitcnt lgkmcnt(0)
	v_mfma_f32_16x16x32_bf16 v[160:163], v[30:33], v[238:241], v[160:163]
	v_mfma_f32_16x16x32_bf16 v[130:133], v[62:65], v[238:241], v[130:133]
	s_nop 6
	v_add_f32_e32 v136, v70, v160
	v_and_b32_e32 v160, 0xffff0000, v127
	v_add_f32_e32 v137, v71, v161
	v_mul_f32_e32 v161, 0xbfb8aa3b, v160
	v_exp_f32_e32 v161, v161
	v_add_f32_e32 v0, v73, v163
	v_mul_f32_e32 v0, v81, v0
	v_mul_f32_e32 v136, v78, v136
	v_add_f32_e32 v161, 1.0, v161
	v_rcp_f32_e32 v161, v161
	v_mul_f32_e32 v137, v79, v137
	v_lshlrev_b32_e32 v127, 16, v127
	v_add_f32_e32 v159, v72, v162
	v_mul_f32_e32 v160, v161, v160
	v_mul_f32_e32 v0, v160, v0
	v_lshlrev_b32_e32 v160, 16, v126
	v_mul_f32_e32 v161, 0xbfb8aa3b, v160
	v_exp_f32_e32 v161, v161
	v_and_b32_e32 v126, 0xffff0000, v126
	v_mul_f32_e32 v159, v80, v159
	v_add_f32_e32 v130, v66, v130
	v_add_f32_e32 v161, 1.0, v161
	v_rcp_f32_e32 v161, v161
	v_mul_f32_e32 v130, v74, v130
	v_add_f32_e32 v131, v67, v131
	v_mul_f32_e32 v131, v75, v131
	v_mul_f32_e32 v160, v161, v160
	v_mul_f32_e32 v136, v160, v136
	v_mul_f32_e32 v160, 0xbfb8aa3b, v126
	v_exp_f32_e32 v160, v160
	v_add_f32_e32 v132, v68, v132
	v_mul_f32_e32 v132, v76, v132
	v_add_f32_e32 v160, 1.0, v160
	v_rcp_f32_e32 v160, v160
	s_nop 0
	v_mul_f32_e32 v126, v160, v126
	v_mul_f32_e32 v126, v126, v137
	v_mul_f32_e32 v137, 0xbfb8aa3b, v127
	v_exp_f32_e32 v137, v137
	v_cvt_pk_bf16_f32 v126, v136, v126
	s_nop 0
	v_add_f32_e32 v137, 1.0, v137
	v_rcp_f32_e32 v137, v137
	s_nop 0
	v_mul_f32_e32 v127, v137, v127
	v_mul_f32_e32 v127, v127, v159
	v_cvt_pk_bf16_f32 v127, v127, v0
	v_add_f32_e32 v0, v69, v133
	v_and_b32_e32 v133, 0xffff0000, v129
	v_mul_f32_e32 v136, 0xbfb8aa3b, v133
	v_exp_f32_e32 v136, v136
	v_mul_f32_e32 v0, v77, v0
	v_lshlrev_b32_e32 v129, 16, v129
	v_add_f32_e32 v136, 1.0, v136
	v_rcp_f32_e32 v136, v136
	s_nop 0
	v_mul_f32_e32 v133, v136, v133
	v_mul_f32_e32 v0, v133, v0
	v_lshlrev_b32_e32 v133, 16, v128
	v_mul_f32_e32 v136, 0xbfb8aa3b, v133
	v_exp_f32_e32 v136, v136
	v_and_b32_e32 v128, 0xffff0000, v128
	v_add_f32_e32 v136, 1.0, v136
	v_rcp_f32_e32 v136, v136
	s_nop 0
	v_mul_f32_e32 v133, v136, v133
	v_mul_f32_e32 v130, v133, v130
	v_mul_f32_e32 v133, 0xbfb8aa3b, v128
	v_exp_f32_e32 v133, v133
	s_nop 0
	v_add_f32_e32 v133, 1.0, v133
	v_rcp_f32_e32 v133, v133
	s_nop 0
	v_mul_f32_e32 v128, v133, v128
	v_mul_f32_e32 v128, v128, v131
	v_mul_f32_e32 v131, 0xbfb8aa3b, v129
	v_exp_f32_e32 v131, v131
	v_cvt_pk_bf16_f32 v128, v130, v128
	v_add_co_u32_e32 v130, vcc, s24, v134
	v_add_f32_e32 v131, 1.0, v131
	v_rcp_f32_e32 v131, v131
	s_nop 0
	v_mul_f32_e32 v129, v131, v129
	v_mul_f32_e32 v129, v129, v132
	v_cvt_pk_bf16_f32 v129, v129, v0
	v_addc_co_u32_e32 v131, vcc, 0, v135, vcc
	global_store_dwordx4 v[130:131], v[126:129], off offset:3584
	ds_read_b128 v[126:129], v155 offset:59136
	ds_read_b128 v[160:163], v155 offset:59200
	ds_read_b128 v[238:241], v155 offset:59264
	ds_read_b128 v[242:245], v155 offset:59328
	ds_read_b128 v[246:249], v155 offset:59392
	ds_read_b128 v[228:231], v155 offset:59456
	s_waitcnt lgkmcnt(5)
	v_mfma_f32_16x16x32_bf16 v[130:133], v[2:5], v[126:129], 0
	v_mfma_f32_16x16x32_bf16 v[126:129], v[34:37], v[126:129], 0
	s_waitcnt lgkmcnt(4)
	v_mfma_f32_16x16x32_bf16 v[130:133], v[6:9], v[160:163], v[130:133]
	v_mfma_f32_16x16x32_bf16 v[126:129], v[38:41], v[160:163], v[126:129]
	ds_read_b128 v[160:163], v155 offset:59520
	s_waitcnt lgkmcnt(4)
	v_mfma_f32_16x16x32_bf16 v[130:133], v[10:13], v[238:241], v[130:133]
	v_mfma_f32_16x16x32_bf16 v[126:129], v[42:45], v[238:241], v[126:129]
	ds_read_b128 v[238:241], v155 offset:59584
	s_waitcnt lgkmcnt(4)
	v_mfma_f32_16x16x32_bf16 v[130:133], v[14:17], v[242:245], v[130:133]
	v_mfma_f32_16x16x32_bf16 v[126:129], v[46:49], v[242:245], v[126:129]
	s_waitcnt lgkmcnt(3)
	v_mfma_f32_16x16x32_bf16 v[130:133], v[18:21], v[246:249], v[130:133]
	v_mfma_f32_16x16x32_bf16 v[126:129], v[50:53], v[246:249], v[126:129]
	s_waitcnt lgkmcnt(2)
	v_mfma_f32_16x16x32_bf16 v[130:133], v[22:25], v[228:231], v[130:133]
	v_mfma_f32_16x16x32_bf16 v[126:129], v[54:57], v[228:231], v[126:129]
	s_waitcnt lgkmcnt(1)
	v_mfma_f32_16x16x32_bf16 v[130:133], v[26:29], v[160:163], v[130:133]
	v_mfma_f32_16x16x32_bf16 v[126:129], v[58:61], v[160:163], v[126:129]
	s_waitcnt lgkmcnt(0)
	v_mfma_f32_16x16x32_bf16 v[130:133], v[30:33], v[238:241], v[130:133]
	v_mfma_f32_16x16x32_bf16 v[126:129], v[62:65], v[238:241], v[126:129]
	s_nop 6
	v_add_f32_e32 v0, v73, v133
	v_and_b32_e32 v133, 0xffff0000, v123
	v_mul_f32_e32 v136, 0xbfb8aa3b, v133
	v_exp_f32_e32 v136, v136
	v_mul_f32_e32 v0, v81, v0
	v_add_f32_e32 v130, v70, v130
	v_mul_f32_e32 v130, v78, v130
	v_add_f32_e32 v136, 1.0, v136
	v_rcp_f32_e32 v136, v136
	v_add_f32_e32 v131, v71, v131
	v_mul_f32_e32 v131, v79, v131
	v_lshlrev_b32_e32 v123, 16, v123
	v_mul_f32_e32 v133, v136, v133
	v_mul_f32_e32 v0, v133, v0
	v_lshlrev_b32_e32 v133, 16, v122
	v_mul_f32_e32 v136, 0xbfb8aa3b, v133
	v_exp_f32_e32 v136, v136
	v_and_b32_e32 v122, 0xffff0000, v122
	v_add_f32_e32 v132, v72, v132
	v_mul_f32_e32 v132, v80, v132
	v_add_f32_e32 v136, 1.0, v136
	v_rcp_f32_e32 v136, v136
	v_add_f32_e32 v126, v66, v126
	v_mul_f32_e32 v126, v74, v126
	v_add_f32_e32 v127, v67, v127
	v_mul_f32_e32 v133, v136, v133
	v_mul_f32_e32 v130, v133, v130
	v_mul_f32_e32 v133, 0xbfb8aa3b, v122
	v_exp_f32_e32 v133, v133
	v_mul_f32_e32 v127, v75, v127
	v_add_f32_e32 v128, v68, v128
	v_mul_f32_e32 v128, v76, v128
	v_add_f32_e32 v133, 1.0, v133
	v_rcp_f32_e32 v133, v133
	s_nop 0
	v_mul_f32_e32 v122, v133, v122
	v_mul_f32_e32 v122, v122, v131
	v_mul_f32_e32 v131, 0xbfb8aa3b, v123
	v_exp_f32_e32 v131, v131
	v_cvt_pk_bf16_f32 v122, v130, v122
	s_nop 0
	v_add_f32_e32 v131, 1.0, v131
	v_rcp_f32_e32 v131, v131
	s_nop 0
	v_mul_f32_e32 v123, v131, v123
	v_mul_f32_e32 v123, v123, v132
	v_cvt_pk_bf16_f32 v123, v123, v0
	v_add_f32_e32 v0, v69, v129
	v_and_b32_e32 v129, 0xffff0000, v125
	v_mul_f32_e32 v130, 0xbfb8aa3b, v129
	v_exp_f32_e32 v130, v130
	v_mul_f32_e32 v0, v77, v0
	v_lshlrev_b32_e32 v125, 16, v125
	v_add_f32_e32 v130, 1.0, v130
	v_rcp_f32_e32 v130, v130
	s_nop 0
	v_mul_f32_e32 v129, v130, v129
	v_mul_f32_e32 v0, v129, v0
	v_lshlrev_b32_e32 v129, 16, v124
	v_mul_f32_e32 v130, 0xbfb8aa3b, v129
	v_exp_f32_e32 v130, v130
	v_and_b32_e32 v124, 0xffff0000, v124
	v_add_f32_e32 v130, 1.0, v130
	v_rcp_f32_e32 v130, v130
	s_nop 0
	v_mul_f32_e32 v129, v130, v129
	v_mul_f32_e32 v126, v129, v126
	v_mul_f32_e32 v129, 0xbfb8aa3b, v124
	v_exp_f32_e32 v129, v129
	s_nop 0
	v_add_f32_e32 v129, 1.0, v129
	v_rcp_f32_e32 v129, v129
	s_nop 0
	v_mul_f32_e32 v124, v129, v124
	v_mul_f32_e32 v124, v124, v127
	v_mul_f32_e32 v127, 0xbfb8aa3b, v125
	v_exp_f32_e32 v127, v127
	v_cvt_pk_bf16_f32 v124, v126, v124
	v_add_co_u32_e32 v126, vcc, s25, v134
	v_add_f32_e32 v127, 1.0, v127
	v_rcp_f32_e32 v127, v127
	s_nop 0
	v_mul_f32_e32 v125, v127, v125
	v_mul_f32_e32 v125, v125, v128
	v_cvt_pk_bf16_f32 v125, v125, v0
	v_addc_co_u32_e32 v127, vcc, 0, v135, vcc
	global_store_dwordx4 v[126:127], v[122:125], off offset:3584
	ds_read_b128 v[122:125], v156 offset:25344
	ds_read_b128 v[130:133], v156 offset:25408
	ds_read_b128 v[238:241], v156 offset:25472
	ds_read_b128 v[242:245], v156 offset:25536
	ds_read_b128 v[246:249], v156 offset:25600
	ds_read_b128 v[228:231], v156 offset:25664
	s_waitcnt lgkmcnt(5)
	v_mfma_f32_16x16x32_bf16 v[126:129], v[2:5], v[122:125], 0
	v_mfma_f32_16x16x32_bf16 v[122:125], v[34:37], v[122:125], 0
	s_waitcnt lgkmcnt(4)
	v_mfma_f32_16x16x32_bf16 v[126:129], v[6:9], v[130:133], v[126:129]
	v_mfma_f32_16x16x32_bf16 v[122:125], v[38:41], v[130:133], v[122:125]
	ds_read_b128 v[130:133], v156 offset:25728
	s_waitcnt lgkmcnt(4)
	v_mfma_f32_16x16x32_bf16 v[126:129], v[10:13], v[238:241], v[126:129]
	v_mfma_f32_16x16x32_bf16 v[122:125], v[42:45], v[238:241], v[122:125]
	ds_read_b128 v[238:241], v156 offset:25792
	s_waitcnt lgkmcnt(4)
	v_mfma_f32_16x16x32_bf16 v[126:129], v[14:17], v[242:245], v[126:129]
	v_mfma_f32_16x16x32_bf16 v[122:125], v[46:49], v[242:245], v[122:125]
	s_waitcnt lgkmcnt(3)
	v_mfma_f32_16x16x32_bf16 v[126:129], v[18:21], v[246:249], v[126:129]
	v_mfma_f32_16x16x32_bf16 v[122:125], v[50:53], v[246:249], v[122:125]
	s_waitcnt lgkmcnt(2)
	v_mfma_f32_16x16x32_bf16 v[126:129], v[22:25], v[228:231], v[126:129]
	v_mfma_f32_16x16x32_bf16 v[122:125], v[54:57], v[228:231], v[122:125]
	s_waitcnt lgkmcnt(1)
	v_mfma_f32_16x16x32_bf16 v[126:129], v[26:29], v[130:133], v[126:129]
	v_mfma_f32_16x16x32_bf16 v[122:125], v[58:61], v[130:133], v[122:125]
	s_waitcnt lgkmcnt(0)
	v_mfma_f32_16x16x32_bf16 v[126:129], v[30:33], v[238:241], v[126:129]
	v_mfma_f32_16x16x32_bf16 v[122:125], v[62:65], v[238:241], v[122:125]
	s_nop 6
	v_add_f32_e32 v0, v73, v129
	v_and_b32_e32 v129, 0xffff0000, v99
	v_mul_f32_e32 v130, 0xbfb8aa3b, v129
	v_exp_f32_e32 v130, v130
	v_mul_f32_e32 v0, v81, v0
	v_add_f32_e32 v126, v70, v126
	v_mul_f32_e32 v126, v78, v126
	v_add_f32_e32 v130, 1.0, v130
	v_rcp_f32_e32 v130, v130
	v_add_f32_e32 v127, v71, v127
	v_mul_f32_e32 v127, v79, v127
	v_lshlrev_b32_e32 v99, 16, v99
	v_mul_f32_e32 v129, v130, v129
	v_mul_f32_e32 v0, v129, v0
	v_lshlrev_b32_e32 v129, 16, v98
	v_mul_f32_e32 v130, 0xbfb8aa3b, v129
	v_exp_f32_e32 v130, v130
	v_and_b32_e32 v98, 0xffff0000, v98
	v_add_f32_e32 v128, v72, v128
	v_mul_f32_e32 v128, v80, v128
	v_add_f32_e32 v130, 1.0, v130
	v_rcp_f32_e32 v130, v130
	v_add_f32_e32 v122, v66, v122
	v_mul_f32_e32 v122, v74, v122
	v_add_f32_e32 v123, v67, v123
	v_mul_f32_e32 v129, v130, v129
	v_mul_f32_e32 v126, v129, v126
	v_mul_f32_e32 v129, 0xbfb8aa3b, v98
	v_exp_f32_e32 v129, v129
	v_mul_f32_e32 v123, v75, v123
	v_add_f32_e32 v124, v68, v124
	v_mul_f32_e32 v124, v76, v124
	v_add_f32_e32 v129, 1.0, v129
	v_rcp_f32_e32 v129, v129
	s_waitcnt vmcnt(6)
	v_mov_b64_e32 v[132:133], v[84:85]
	v_mov_b64_e32 v[130:131], v[82:83]
	v_mul_f32_e32 v98, v129, v98
	v_mul_f32_e32 v98, v98, v127
	v_mul_f32_e32 v127, 0xbfb8aa3b, v99
	v_exp_f32_e32 v127, v127
	v_cvt_pk_bf16_f32 v98, v126, v98
	s_nop 0
	v_add_f32_e32 v127, 1.0, v127
	v_rcp_f32_e32 v127, v127
	s_nop 0
	v_mul_f32_e32 v99, v127, v99
	v_mul_f32_e32 v99, v99, v128
	v_cvt_pk_bf16_f32 v99, v99, v0
	v_add_f32_e32 v0, v69, v125
	v_and_b32_e32 v125, 0xffff0000, v101
	v_mul_f32_e32 v126, 0xbfb8aa3b, v125
	v_exp_f32_e32 v126, v126
	v_mul_f32_e32 v0, v77, v0
	v_lshlrev_b32_e32 v101, 16, v101
	v_add_f32_e32 v126, 1.0, v126
	v_rcp_f32_e32 v126, v126
	s_nop 0
	v_mul_f32_e32 v125, v126, v125
	v_mul_f32_e32 v0, v125, v0
	v_lshlrev_b32_e32 v125, 16, v100
	v_mul_f32_e32 v126, 0xbfb8aa3b, v125
	v_exp_f32_e32 v126, v126
	v_and_b32_e32 v100, 0xffff0000, v100
	v_add_f32_e32 v126, 1.0, v126
	v_rcp_f32_e32 v126, v126
	s_nop 0
	v_mul_f32_e32 v125, v126, v125
	v_mul_f32_e32 v122, v125, v122
	v_mul_f32_e32 v125, 0xbfb8aa3b, v100
	v_exp_f32_e32 v125, v125
	s_waitcnt vmcnt(5)
	v_mov_b64_e32 v[128:129], v[88:89]
	v_mov_b64_e32 v[126:127], v[86:87]
	v_add_f32_e32 v125, 1.0, v125
	v_rcp_f32_e32 v125, v125
	s_nop 0
	v_mul_f32_e32 v100, v125, v100
	v_mul_f32_e32 v100, v100, v123
	v_mul_f32_e32 v123, 0xbfb8aa3b, v101
	v_exp_f32_e32 v123, v123
	v_cvt_pk_bf16_f32 v100, v122, v100
	v_add_co_u32_e32 v122, vcc, s14, v134
	v_add_f32_e32 v123, 1.0, v123
	v_rcp_f32_e32 v123, v123
	s_nop 0
	v_mul_f32_e32 v101, v123, v101
	v_mul_f32_e32 v101, v101, v124
	v_cvt_pk_bf16_f32 v101, v101, v0
	v_addc_co_u32_e32 v123, vcc, 0, v135, vcc
	global_store_dwordx4 v[122:123], v[98:101], off offset:3584
	s_waitcnt vmcnt(5)
	v_mov_b64_e32 v[124:125], v[92:93]
	v_mov_b64_e32 v[122:123], v[90:91]
	s_waitcnt vmcnt(4)
	v_mov_b64_e32 v[100:101], v[96:97]
	v_mov_b64_e32 v[98:99], v[94:95]
	ds_write_b128 v149, v[102:105] offset:8448
	ds_write_b128 v150, v[106:109] offset:8448
	ds_write_b128 v151, v[110:113] offset:8448
	ds_write_b128 v152, v[114:117] offset:8448
	ds_write_b128 v153, v[118:121]
	s_cbranch_scc1 .LBB0_124
	s_waitcnt lgkmcnt(0)
	s_barrier
	s_mov_b64 s[0:1], 0

.LBB0_130:
	s_cmp_lg_u32 s42, 0x1c0000
	s_cselect_b32 s0, s11, 7
	s_add_i32 s0, s0, s10
	s_lshl_b32 s0, s0, 6
	s_and_b32 s2, s0, 0xfc0
	s_and_b32 s0, s0, 0xfffff000
	s_ashr_i32 s1, s0, 31
	v_add_u32_e32 v84, s2, v144
	s_lshl_b64 s[0:1], s[0:1], 11
	v_ashrrev_i32_e32 v85, 31, v84
	v_lshl_add_u64 v[82:83], v[138:139], 0, s[0:1]
	v_lshlrev_b64 v[84:85], 11, v[84:85]
	s_waitcnt lgkmcnt(0)
	s_barrier
	v_lshl_add_u64 v[84:85], v[82:83], 0, v[84:85]
	global_load_dwordx4 v[102:105], v[84:85], off offset:1024
	v_add_u32_e32 v84, s2, v145
	v_ashrrev_i32_e32 v85, 31, v84
	v_lshlrev_b64 v[84:85], 11, v[84:85]
	v_lshl_add_u64 v[84:85], v[82:83], 0, v[84:85]
	global_load_dwordx4 v[106:109], v[84:85], off offset:1024
	v_add_u32_e32 v84, s2, v146
	v_ashrrev_i32_e32 v85, 31, v84
	v_lshlrev_b64 v[84:85], 11, v[84:85]
	v_lshl_add_u64 v[84:85], v[82:83], 0, v[84:85]
	global_load_dwordx4 v[110:113], v[84:85], off offset:1024
	v_add_u32_e32 v84, s2, v147
	ds_read_b128 v[118:121], v153 offset:33792
	ds_read_b128 v[134:137], v154 offset:4752
	v_ashrrev_i32_e32 v85, 31, v84
	v_lshlrev_b64 v[84:85], 11, v[84:85]
	v_lshl_add_u64 v[82:83], v[82:83], 0, v[84:85]
	v_or_b32_e32 v0, s2, v148
	global_load_dwordx4 v[114:117], v[82:83], off offset:1024
	v_lshl_add_u64 v[82:83], v[140:141], 0, s[0:1]
	v_lshlrev_b32_e32 v0, 11, v0
	v_lshl_add_u64 v[94:95], v[82:83], 0, v[0:1]
	s_waitcnt lgkmcnt(0)
	v_lshlrev_b32_e32 v0, 16, v134
	v_and_b32_e32 v134, 0xffff0000, v134
	v_add_f32_e32 v159, 0, v134
	v_lshlrev_b32_e32 v134, 16, v135
	v_add_f32_e32 v160, 0, v134
	v_and_b32_e32 v134, 0xffff0000, v135
	v_add_f32_e32 v161, 0, v134
	v_lshlrev_b32_e32 v134, 16, v136
	v_add_f32_e32 v162, 0, v134
	v_and_b32_e32 v134, 0xffff0000, v136
	v_add_f32_e32 v163, 0, v134
	v_lshlrev_b32_e32 v134, 16, v137
	v_add_f32_e32 v164, 0, v134
	v_and_b32_e32 v134, 0xffff0000, v137
	v_add_f32_e32 v165, 0, v134
	ds_read_b128 v[134:137], v154 offset:5280
	ds_read_b128 v[170:173], v158 offset:8448
	v_add_f32_e32 v0, 0, v0
	v_add_co_u32_e32 v86, vcc, s97, v94
	s_waitcnt lgkmcnt(1)
	v_lshlrev_b32_e32 v166, 16, v134
	v_and_b32_e32 v134, 0xffff0000, v134
	v_add_f32_e32 v159, v159, v134
	v_lshlrev_b32_e32 v134, 16, v135
	v_add_f32_e32 v160, v160, v134
	v_and_b32_e32 v134, 0xffff0000, v135
	v_add_f32_e32 v161, v161, v134
	v_lshlrev_b32_e32 v134, 16, v136
	v_add_f32_e32 v162, v162, v134
	v_and_b32_e32 v134, 0xffff0000, v136
	v_add_f32_e32 v163, v163, v134
	v_lshlrev_b32_e32 v134, 16, v137
	v_add_f32_e32 v164, v164, v134
	v_and_b32_e32 v134, 0xffff0000, v137
	v_add_f32_e32 v165, v165, v134
	ds_read_b128 v[134:137], v154 offset:5808
	v_add_f32_e32 v0, v0, v166
	s_waitcnt lgkmcnt(1)
	v_lshlrev_b32_e32 v169, 16, v170
	v_addc_co_u32_e32 v87, vcc, 0, v95, vcc
	s_waitcnt lgkmcnt(0)
	v_lshlrev_b32_e32 v166, 16, v134
	v_and_b32_e32 v134, 0xffff0000, v134
	v_add_f32_e32 v159, v159, v134
	v_lshlrev_b32_e32 v134, 16, v135
	v_add_f32_e32 v160, v160, v134
	v_and_b32_e32 v134, 0xffff0000, v135
	v_add_f32_e32 v161, v161, v134
	v_lshlrev_b32_e32 v134, 16, v136
	v_add_f32_e32 v162, v162, v134
	v_and_b32_e32 v134, 0xffff0000, v136
	v_add_f32_e32 v163, v163, v134
	v_lshlrev_b32_e32 v134, 16, v137
	v_add_f32_e32 v164, v164, v134
	v_and_b32_e32 v134, 0xffff0000, v137
	v_add_f32_e32 v165, v165, v134
	ds_read_b128 v[134:137], v154 offset:6336
	v_add_f32_e32 v0, v0, v166
	v_add_co_u32_e32 v90, vcc, s4, v94
	global_load_dwordx4 v[82:85], v[94:95], off offset:1024
	s_waitcnt lgkmcnt(0)
	v_lshlrev_b32_e32 v166, 16, v134
	v_and_b32_e32 v134, 0xffff0000, v134
	v_add_f32_e32 v159, v159, v134
	v_lshlrev_b32_e32 v134, 16, v135
	v_add_f32_e32 v160, v160, v134
	v_and_b32_e32 v134, 0xffff0000, v135
	v_add_f32_e32 v161, v161, v134
	v_lshlrev_b32_e32 v134, 16, v136
	v_add_f32_e32 v162, v162, v134
	v_and_b32_e32 v134, 0xffff0000, v136
	v_add_f32_e32 v163, v163, v134
	v_lshlrev_b32_e32 v134, 16, v137
	v_add_f32_e32 v164, v164, v134
	v_and_b32_e32 v134, 0xffff0000, v137
	v_add_f32_e32 v165, v165, v134
	ds_read_b128 v[134:137], v154 offset:6864
	v_add_f32_e32 v0, v0, v166
	v_addc_co_u32_e32 v91, vcc, 0, v95, vcc
	v_add_co_u32_e32 v94, vcc, s96, v94
	s_waitcnt lgkmcnt(0)
	v_lshlrev_b32_e32 v166, 16, v134
	v_and_b32_e32 v134, 0xffff0000, v134
	v_add_f32_e32 v159, v159, v134
	v_lshlrev_b32_e32 v134, 16, v135
	v_add_f32_e32 v160, v160, v134
	v_and_b32_e32 v134, 0xffff0000, v135
	v_add_f32_e32 v161, v161, v134
	v_lshlrev_b32_e32 v134, 16, v136
	v_add_f32_e32 v162, v162, v134
	v_and_b32_e32 v134, 0xffff0000, v136
	v_add_f32_e32 v163, v163, v134
	v_lshlrev_b32_e32 v134, 16, v137
	v_add_f32_e32 v164, v164, v134
	v_and_b32_e32 v134, 0xffff0000, v137
	v_add_f32_e32 v165, v165, v134
	ds_read_b128 v[134:137], v154 offset:7392
	v_add_f32_e32 v0, v0, v166
	v_addc_co_u32_e32 v95, vcc, 0, v95, vcc
	global_load_dwordx4 v[86:89], v[86:87], off offset:1024
	s_waitcnt lgkmcnt(0)
	v_lshlrev_b32_e32 v166, 16, v134
	v_and_b32_e32 v134, 0xffff0000, v134
	v_add_f32_e32 v134, v159, v134
	v_lshlrev_b32_e32 v159, 16, v135
	v_and_b32_e32 v135, 0xffff0000, v135
	v_add_f32_e32 v0, v0, v166
	v_add_f32_e32 v166, v161, v135
	v_lshlrev_b32_e32 v135, 16, v136
	v_add_f32_e32 v167, v162, v135
	v_and_b32_e32 v135, 0xffff0000, v136
	v_add_f32_e32 v159, v160, v159
	v_add_f32_e32 v168, v163, v135
	ds_read_b128 v[160:163], v154 offset:7920
	v_lshlrev_b32_e32 v135, 16, v137
	v_add_f32_e32 v164, v164, v135
	v_and_b32_e32 v135, 0xffff0000, v137
	v_add_f32_e32 v165, v165, v135
	s_waitcnt lgkmcnt(0)
	v_lshlrev_b32_e32 v135, 16, v160
	v_add_f32_e32 v0, v0, v135
	v_and_b32_e32 v135, 0xffff0000, v160
	v_add_f32_e32 v134, v134, v135
	v_lshlrev_b32_e32 v135, 16, v161
	v_add_f32_e32 v135, v159, v135
	v_and_b32_e32 v159, 0xffff0000, v162
	v_add_f32_e32 v159, v168, v159
	v_and_b32_e32 v168, 0xffff0000, v170
	v_min_i32_e32 v170, 7, v157
	v_add_u32_e32 v170, 1, v170
	v_cvt_f32_i32_e32 v170, v170
	v_and_b32_e32 v136, 0xffff0000, v161
	v_lshlrev_b32_e32 v137, 16, v162
	v_add_f32_e32 v136, v166, v136
	v_rcp_iflag_f32_e32 v170, v170
	v_add_f32_e32 v137, v167, v137
	v_lshlrev_b32_e32 v167, 16, v171
	v_and_b32_e32 v166, 0xffff0000, v171
	v_add_f32_e32 v171, v134, v168
	v_and_b32_e32 v161, 0xffff0000, v163
	v_fma_f32 v134, v171, v170, -v168
	v_add_f32_e32 v168, v135, v167
	v_lshlrev_b32_e32 v160, 16, v163
	v_add_f32_e32 v161, v165, v161
	v_lshlrev_b32_e32 v165, 16, v172
	v_fma_f32 v135, v168, v170, -v167
	v_add_f32_e32 v167, v136, v166
	v_add_f32_e32 v160, v164, v160
	v_and_b32_e32 v164, 0xffff0000, v172
	v_lshlrev_b32_e32 v163, 16, v173
	v_and_b32_e32 v162, 0xffff0000, v173
	v_fma_f32 v136, v167, v170, -v166
	v_add_f32_e32 v166, v137, v165
	v_add_f32_e32 v0, v0, v169
	v_fma_f32 v137, v166, v170, -v165
	v_add_f32_e32 v159, v159, v164
	v_add_f32_e32 v160, v160, v163
	v_add_f32_e32 v161, v161, v162
	global_load_dwordx4 v[90:93], v[90:91], off offset:1024
	v_fma_f32 v169, v0, v170, -v169
	global_load_dwordx4 v[94:97], v[94:95], off offset:1024
	v_fma_f32 v164, v159, v170, -v164
	v_fma_f32 v163, v160, v170, -v163
	v_fma_f32 v162, v161, v170, -v162
	v_cvt_pk_bf16_f32 v134, v169, v134
	v_cvt_pk_bf16_f32 v135, v135, v136
	v_cvt_pk_bf16_f32 v136, v137, v164
	v_cvt_pk_bf16_f32 v137, v163, v162
	ds_write_b128 v154, v[134:137] offset:42240
	ds_read_b128 v[134:137], v158 offset:4752
	v_add_u32_e32 v170, 1, v157
	v_min_i32_e32 v170, 7, v170
	v_add_u32_e32 v170, 1, v170
	v_cvt_f32_i32_e32 v170, v170
	s_waitcnt lgkmcnt(0)
	v_lshlrev_b32_e32 v162, 16, v134
	v_and_b32_e32 v134, 0xffff0000, v134
	v_sub_f32_e32 v0, v0, v162
	v_sub_f32_e32 v162, v171, v134
	v_lshlrev_b32_e32 v134, 16, v135
	v_sub_f32_e32 v163, v168, v134
	v_and_b32_e32 v134, 0xffff0000, v135
	v_sub_f32_e32 v164, v167, v134
	v_lshlrev_b32_e32 v134, 16, v136
	v_sub_f32_e32 v165, v166, v134
	v_and_b32_e32 v134, 0xffff0000, v136
	v_sub_f32_e32 v159, v159, v134
	v_lshlrev_b32_e32 v134, 16, v137
	v_sub_f32_e32 v160, v160, v134
	v_and_b32_e32 v134, 0xffff0000, v137
	v_sub_f32_e32 v161, v161, v134
	ds_read_b128 v[134:137], v158 offset:8976
	v_rcp_iflag_f32_e32 v170, v170
	s_waitcnt lgkmcnt(0)
	v_lshlrev_b32_e32 v166, 16, v134
	v_and_b32_e32 v134, 0xffff0000, v134
	v_lshlrev_b32_e32 v167, 16, v135
	v_and_b32_e32 v135, 0xffff0000, v135
	v_lshlrev_b32_e32 v168, 16, v136
	v_and_b32_e32 v136, 0xffff0000, v136
	v_lshlrev_b32_e32 v169, 16, v137
	v_and_b32_e32 v137, 0xffff0000, v137
	v_add_f32_e32 v162, v162, v134
	v_add_f32_e32 v164, v164, v135
	v_add_f32_e32 v159, v159, v136
	v_add_f32_e32 v161, v161, v137
	v_add_f32_e32 v0, v0, v166
	v_fma_f32 v134, v162, v170, -v134
	v_add_f32_e32 v163, v163, v167
	v_fma_f32 v135, v164, v170, -v135
	v_add_f32_e32 v165, v165, v168
	v_fma_f32 v136, v159, v170, -v136
	v_add_f32_e32 v160, v160, v169
	v_fma_f32 v137, v161, v170, -v137
	v_fma_f32 v166, v0, v170, -v166
	v_fma_f32 v167, v163, v170, -v167
	v_fma_f32 v168, v165, v170, -v168
	v_fma_f32 v169, v160, v170, -v169
	v_cvt_pk_bf16_f32 v134, v166, v134
	v_cvt_pk_bf16_f32 v135, v167, v135
	v_cvt_pk_bf16_f32 v136, v168, v136
	v_cvt_pk_bf16_f32 v137, v169, v137
	ds_write_b128 v154, v[134:137] offset:42768
	ds_read_b128 v[134:137], v158 offset:5280
	v_add_u32_e32 v170, 2, v157
	v_min_i32_e32 v170, 7, v170
	v_add_u32_e32 v170, 1, v170
	v_cvt_f32_i32_e32 v170, v170
	s_waitcnt lgkmcnt(0)
	v_lshlrev_b32_e32 v166, 16, v134
	v_and_b32_e32 v134, 0xffff0000, v134
	v_sub_f32_e32 v162, v162, v134
	v_lshlrev_b32_e32 v134, 16, v135
	v_sub_f32_e32 v163, v163, v134
	v_and_b32_e32 v134, 0xffff0000, v135
	v_sub_f32_e32 v164, v164, v134
	v_lshlrev_b32_e32 v134, 16, v136
	v_sub_f32_e32 v165, v165, v134
	v_and_b32_e32 v134, 0xffff0000, v136
	v_sub_f32_e32 v159, v159, v134
	v_lshlrev_b32_e32 v134, 16, v137
	v_sub_f32_e32 v160, v160, v134
	v_and_b32_e32 v134, 0xffff0000, v137
	v_sub_f32_e32 v161, v161, v134
	ds_read_b128 v[134:137], v158 offset:9504
	v_rcp_iflag_f32_e32 v170, v170
	v_sub_f32_e32 v0, v0, v166
	s_waitcnt lgkmcnt(0)
	v_lshlrev_b32_e32 v166, 16, v134
	v_and_b32_e32 v134, 0xffff0000, v134
	v_lshlrev_b32_e32 v167, 16, v135
	v_and_b32_e32 v135, 0xffff0000, v135
	v_lshlrev_b32_e32 v168, 16, v136
	v_and_b32_e32 v136, 0xffff0000, v136
	v_lshlrev_b32_e32 v169, 16, v137
	v_and_b32_e32 v137, 0xffff0000, v137
	v_add_f32_e32 v162, v162, v134
	v_add_f32_e32 v164, v164, v135
	v_add_f32_e32 v159, v159, v136
	v_add_f32_e32 v161, v161, v137
	v_add_f32_e32 v0, v0, v166
	v_fma_f32 v134, v162, v170, -v134
	v_add_f32_e32 v163, v163, v167
	v_fma_f32 v135, v164, v170, -v135
	v_add_f32_e32 v165, v165, v168
	v_fma_f32 v136, v159, v170, -v136
	v_add_f32_e32 v160, v160, v169
	v_fma_f32 v137, v161, v170, -v137
	v_fma_f32 v166, v0, v170, -v166
	v_fma_f32 v167, v163, v170, -v167
	v_fma_f32 v168, v165, v170, -v168
	v_fma_f32 v169, v160, v170, -v169
	v_cvt_pk_bf16_f32 v134, v166, v134
	v_cvt_pk_bf16_f32 v135, v167, v135
	v_cvt_pk_bf16_f32 v136, v168, v136
	v_cvt_pk_bf16_f32 v137, v169, v137
	ds_write_b128 v154, v[134:137] offset:43296
	ds_read_b128 v[134:137], v158 offset:5808
	v_add_u32_e32 v170, 3, v157
	v_min_i32_e32 v170, 7, v170
	v_add_u32_e32 v170, 1, v170
	v_cvt_f32_i32_e32 v170, v170
	s_waitcnt lgkmcnt(0)
	v_lshlrev_b32_e32 v166, 16, v134
	v_and_b32_e32 v134, 0xffff0000, v134
	v_sub_f32_e32 v162, v162, v134
	v_lshlrev_b32_e32 v134, 16, v135
	v_sub_f32_e32 v163, v163, v134
	v_and_b32_e32 v134, 0xffff0000, v135
	v_sub_f32_e32 v164, v164, v134
	v_lshlrev_b32_e32 v134, 16, v136
	v_sub_f32_e32 v165, v165, v134
	v_and_b32_e32 v134, 0xffff0000, v136
	v_sub_f32_e32 v159, v159, v134
	v_lshlrev_b32_e32 v134, 16, v137
	v_sub_f32_e32 v160, v160, v134
	v_and_b32_e32 v134, 0xffff0000, v137
	v_sub_f32_e32 v161, v161, v134
	ds_read_b128 v[134:137], v158 offset:10032
	v_rcp_iflag_f32_e32 v170, v170
	v_sub_f32_e32 v0, v0, v166
	v_add_u32_e32 v157, 64, v157
	s_waitcnt lgkmcnt(0)
	v_lshlrev_b32_e32 v166, 16, v134
	v_and_b32_e32 v134, 0xffff0000, v134
	v_lshlrev_b32_e32 v168, 16, v136
	v_and_b32_e32 v136, 0xffff0000, v136
	v_lshlrev_b32_e32 v167, 16, v135
	v_and_b32_e32 v135, 0xffff0000, v135
	v_lshlrev_b32_e32 v169, 16, v137
	v_and_b32_e32 v137, 0xffff0000, v137
	v_add_f32_e32 v162, v162, v134
	v_add_f32_e32 v159, v159, v136
	v_fma_f32 v134, v162, v170, -v134
	v_add_f32_e32 v162, v163, v167
	v_add_f32_e32 v163, v164, v135
	v_fma_f32 v136, v159, v170, -v136
	v_add_f32_e32 v159, v160, v169
	v_add_f32_e32 v160, v161, v137
	v_add_f32_e32 v0, v0, v166
	v_fma_f32 v135, v163, v170, -v135
	v_add_f32_e32 v163, v165, v168
	v_fma_f32 v137, v160, v170, -v137
	v_fma_f32 v0, v0, v170, -v166
	v_fma_f32 v162, v162, v170, -v167
	v_fma_f32 v163, v163, v170, -v168
	v_fma_f32 v159, v159, v170, -v169
	v_cvt_pk_bf16_f32 v134, v0, v134
	v_cvt_pk_bf16_f32 v135, v162, v135
	v_cvt_pk_bf16_f32 v136, v163, v136
	v_cvt_pk_bf16_f32 v137, v159, v137
	ds_write_b128 v154, v[134:137] offset:43824
	s_waitcnt lgkmcnt(0)
	s_barrier
	ds_read_b128 v[134:137], v155 offset:42240
	ds_read_b128 v[164:167], v155 offset:42304
	ds_read_b128 v[238:241], v155 offset:42368
	ds_read_b128 v[242:245], v155 offset:42432
	ds_read_b128 v[246:249], v155 offset:42496
	ds_read_b128 v[228:231], v155 offset:42560
	s_waitcnt lgkmcnt(5)
	v_mfma_f32_16x16x32_bf16 v[160:163], v[2:5], v[134:137], 0
	v_mfma_f32_16x16x32_bf16 v[134:137], v[34:37], v[134:137], 0
	s_waitcnt lgkmcnt(4)
	v_mfma_f32_16x16x32_bf16 v[160:163], v[6:9], v[164:167], v[160:163]
	v_mfma_f32_16x16x32_bf16 v[134:137], v[38:41], v[164:167], v[134:137]
	ds_read_b128 v[164:167], v155 offset:42624
	s_waitcnt lgkmcnt(4)
	v_mfma_f32_16x16x32_bf16 v[160:163], v[10:13], v[238:241], v[160:163]
	v_mfma_f32_16x16x32_bf16 v[134:137], v[42:45], v[238:241], v[134:137]
	ds_read_b128 v[238:241], v155 offset:42688
	s_waitcnt lgkmcnt(4)
	v_mfma_f32_16x16x32_bf16 v[160:163], v[14:17], v[242:245], v[160:163]
	v_mfma_f32_16x16x32_bf16 v[134:137], v[46:49], v[242:245], v[134:137]
	s_waitcnt lgkmcnt(3)
	v_mfma_f32_16x16x32_bf16 v[160:163], v[18:21], v[246:249], v[160:163]
	v_mfma_f32_16x16x32_bf16 v[134:137], v[50:53], v[246:249], v[134:137]
	s_waitcnt lgkmcnt(2)
	v_mfma_f32_16x16x32_bf16 v[160:163], v[22:25], v[228:231], v[160:163]
	v_mfma_f32_16x16x32_bf16 v[134:137], v[54:57], v[228:231], v[134:137]
	s_waitcnt lgkmcnt(1)
	v_mfma_f32_16x16x32_bf16 v[160:163], v[26:29], v[164:167], v[160:163]
	v_mfma_f32_16x16x32_bf16 v[134:137], v[58:61], v[164:167], v[134:137]
	s_waitcnt lgkmcnt(0)
	v_mfma_f32_16x16x32_bf16 v[160:163], v[30:33], v[238:241], v[160:163]
	v_mfma_f32_16x16x32_bf16 v[134:137], v[62:65], v[238:241], v[134:137]
	s_nop 6
	v_add_f32_e32 v159, v70, v160
	v_add_f32_e32 v160, v71, v161
	v_add_f32_e32 v161, v72, v162
	v_and_b32_e32 v162, 0xffff0000, v131
	v_add_f32_e32 v0, v73, v163
	v_mul_f32_e32 v163, 0xbfb8aa3b, v162
	v_exp_f32_e32 v163, v163
	v_mul_f32_e32 v0, v81, v0
	v_mul_f32_e32 v159, v78, v159
	v_mul_f32_e32 v160, v79, v160
	v_add_f32_e32 v163, 1.0, v163
	v_rcp_f32_e32 v163, v163
	v_lshlrev_b32_e32 v131, 16, v131
	v_mul_f32_e32 v161, v80, v161
	v_add_f32_e32 v134, v66, v134
	v_mul_f32_e32 v162, v163, v162
	v_mul_f32_e32 v0, v162, v0
	v_lshlrev_b32_e32 v162, 16, v130
	v_mul_f32_e32 v163, 0xbfb8aa3b, v162
	v_exp_f32_e32 v163, v163
	v_and_b32_e32 v130, 0xffff0000, v130
	v_mul_f32_e32 v134, v74, v134
	v_add_f32_e32 v135, v67, v135
	v_add_f32_e32 v163, 1.0, v163
	v_rcp_f32_e32 v163, v163
	v_mul_f32_e32 v135, v75, v135
	v_add_f32_e32 v136, v68, v136
	v_mul_f32_e32 v136, v76, v136
	v_mul_f32_e32 v162, v163, v162
	v_mul_f32_e32 v159, v162, v159
	v_mul_f32_e32 v162, 0xbfb8aa3b, v130
	v_exp_f32_e32 v162, v162
	s_nop 0
	v_add_f32_e32 v162, 1.0, v162
	v_rcp_f32_e32 v162, v162
	s_nop 0
	v_mul_f32_e32 v130, v162, v130
	v_mul_f32_e32 v130, v130, v160
	v_mul_f32_e32 v160, 0xbfb8aa3b, v131
	v_exp_f32_e32 v160, v160
	v_cvt_pk_bf16_f32 v130, v159, v130
	s_nop 0
	v_add_f32_e32 v160, 1.0, v160
	v_rcp_f32_e32 v160, v160
	s_nop 0
	v_mul_f32_e32 v131, v160, v131
	v_mul_f32_e32 v131, v131, v161
	v_cvt_pk_bf16_f32 v131, v131, v0
	v_add_f32_e32 v0, v69, v137
	v_and_b32_e32 v137, 0xffff0000, v133
	v_mul_f32_e32 v159, 0xbfb8aa3b, v137
	v_exp_f32_e32 v159, v159
	v_mul_f32_e32 v0, v77, v0
	v_lshlrev_b32_e32 v133, 16, v133
	v_add_f32_e32 v159, 1.0, v159
	v_rcp_f32_e32 v159, v159
	s_nop 0
	v_mul_f32_e32 v137, v159, v137
	v_mul_f32_e32 v0, v137, v0
	v_lshlrev_b32_e32 v137, 16, v132
	v_mul_f32_e32 v159, 0xbfb8aa3b, v137
	v_exp_f32_e32 v159, v159
	v_and_b32_e32 v132, 0xffff0000, v132
	v_add_f32_e32 v159, 1.0, v159
	v_rcp_f32_e32 v159, v159
	s_nop 0
	v_mul_f32_e32 v137, v159, v137
	v_mul_f32_e32 v134, v137, v134
	v_mul_f32_e32 v137, 0xbfb8aa3b, v132
	v_exp_f32_e32 v137, v137
	s_nop 0
	v_add_f32_e32 v137, 1.0, v137
	v_rcp_f32_e32 v137, v137
	s_nop 0
	v_mul_f32_e32 v132, v137, v132
	v_mul_f32_e32 v132, v132, v135
	v_mul_f32_e32 v135, 0xbfb8aa3b, v133
	v_exp_f32_e32 v135, v135
	v_cvt_pk_bf16_f32 v132, v134, v132
	s_nop 0
	v_add_f32_e32 v135, 1.0, v135
	v_rcp_f32_e32 v135, v135
	s_nop 0
	v_mul_f32_e32 v133, v135, v133
	v_lshl_add_u64 v[134:135], v[142:143], 0, s[42:43]
	v_mul_f32_e32 v133, v133, v136
	v_add_co_u32_e32 v136, vcc, s9, v134
	v_cvt_pk_bf16_f32 v133, v133, v0
	ds_read_b128 v[164:167], v155 offset:50752
	s_nop 0
	v_addc_co_u32_e32 v137, vcc, 0, v135, vcc
	global_store_dwordx4 v[136:137], v[130:133], off offset:3072
	ds_read_b128 v[130:133], v155 offset:50688
	ds_read_b128 v[238:241], v155 offset:50816
	ds_read_b128 v[242:245], v155 offset:50880
	ds_read_b128 v[246:249], v155 offset:50944
	ds_read_b128 v[228:231], v155 offset:51008
	s_waitcnt lgkmcnt(4)
	v_mfma_f32_16x16x32_bf16 v[160:163], v[2:5], v[130:133], 0
	s_add_u32 s42, s42, 0x40000
	s_addc_u32 s43, s43, 0
	s_add_i32 s11, s11, 1
	v_mfma_f32_16x16x32_bf16 v[130:133], v[34:37], v[130:133], 0
	s_cmp_lg_u32 s42, 0x200000
	s_waitcnt lgkmcnt(5)
	v_mfma_f32_16x16x32_bf16 v[160:163], v[6:9], v[164:167], v[160:163]
	v_mfma_f32_16x16x32_bf16 v[130:133], v[38:41], v[164:167], v[130:133]
	ds_read_b128 v[164:167], v155 offset:51072
	s_waitcnt lgkmcnt(4)
	v_mfma_f32_16x16x32_bf16 v[160:163], v[10:13], v[238:241], v[160:163]
	v_mfma_f32_16x16x32_bf16 v[130:133], v[42:45], v[238:241], v[130:133]
	ds_read_b128 v[238:241], v155 offset:51136
	s_waitcnt lgkmcnt(4)
	v_mfma_f32_16x16x32_bf16 v[160:163], v[14:17], v[242:245], v[160:163]
	v_mfma_f32_16x16x32_bf16 v[130:133], v[46:49], v[242:245], v[130:133]
	s_waitcnt lgkmcnt(3)
	v_mfma_f32_16x16x32_bf16 v[160:163], v[18:21], v[246:249], v[160:163]
	v_mfma_f32_16x16x32_bf16 v[130:133], v[50:53], v[246:249], v[130:133]
	s_waitcnt lgkmcnt(2)
	v_mfma_f32_16x16x32_bf16 v[160:163], v[22:25], v[228:231], v[160:163]
	v_mfma_f32_16x16x32_bf16 v[130:133], v[54:57], v[228:231], v[130:133]
	s_waitcnt lgkmcnt(1)
	v_mfma_f32_16x16x32_bf16 v[160:163], v[26:29], v[164:167], v[160:163]
	v_mfma_f32_16x16x32_bf16 v[130:133], v[58:61], v[164:167], v[130:133]
	s_waitcnt lgkmcnt(0)
	v_mfma_f32_16x16x32_bf16 v[160:163], v[30:33], v[238:241], v[160:163]
	v_mfma_f32_16x16x32_bf16 v[130:133], v[62:65], v[238:241], v[130:133]
	s_nop 6
	v_add_f32_e32 v136, v70, v160
	v_and_b32_e32 v160, 0xffff0000, v127
	v_add_f32_e32 v137, v71, v161
	v_mul_f32_e32 v161, 0xbfb8aa3b, v160
	v_exp_f32_e32 v161, v161
	v_add_f32_e32 v0, v73, v163
	v_mul_f32_e32 v0, v81, v0
	v_mul_f32_e32 v136, v78, v136
	v_add_f32_e32 v161, 1.0, v161
	v_rcp_f32_e32 v161, v161
	v_mul_f32_e32 v137, v79, v137
	v_lshlrev_b32_e32 v127, 16, v127
	v_add_f32_e32 v159, v72, v162
	v_mul_f32_e32 v160, v161, v160
	v_mul_f32_e32 v0, v160, v0
	v_lshlrev_b32_e32 v160, 16, v126
	v_mul_f32_e32 v161, 0xbfb8aa3b, v160
	v_exp_f32_e32 v161, v161
	v_and_b32_e32 v126, 0xffff0000, v126
	v_mul_f32_e32 v159, v80, v159
	v_add_f32_e32 v130, v66, v130
	v_add_f32_e32 v161, 1.0, v161
	v_rcp_f32_e32 v161, v161
	v_mul_f32_e32 v130, v74, v130
	v_add_f32_e32 v131, v67, v131
	v_mul_f32_e32 v131, v75, v131
	v_mul_f32_e32 v160, v161, v160
	v_mul_f32_e32 v136, v160, v136
	v_mul_f32_e32 v160, 0xbfb8aa3b, v126
	v_exp_f32_e32 v160, v160
	v_add_f32_e32 v132, v68, v132
	v_mul_f32_e32 v132, v76, v132
	v_add_f32_e32 v160, 1.0, v160
	v_rcp_f32_e32 v160, v160
	s_nop 0
	v_mul_f32_e32 v126, v160, v126
	v_mul_f32_e32 v126, v126, v137
	v_mul_f32_e32 v137, 0xbfb8aa3b, v127
	v_exp_f32_e32 v137, v137
	v_cvt_pk_bf16_f32 v126, v136, v126
	s_nop 0
	v_add_f32_e32 v137, 1.0, v137
	v_rcp_f32_e32 v137, v137
	s_nop 0
	v_mul_f32_e32 v127, v137, v127
	v_mul_f32_e32 v127, v127, v159
	v_cvt_pk_bf16_f32 v127, v127, v0
	v_add_f32_e32 v0, v69, v133
	v_and_b32_e32 v133, 0xffff0000, v129
	v_mul_f32_e32 v136, 0xbfb8aa3b, v133
	v_exp_f32_e32 v136, v136
	v_mul_f32_e32 v0, v77, v0
	v_lshlrev_b32_e32 v129, 16, v129
	v_add_f32_e32 v136, 1.0, v136
	v_rcp_f32_e32 v136, v136
	s_nop 0
	v_mul_f32_e32 v133, v136, v133
	v_mul_f32_e32 v0, v133, v0
	v_lshlrev_b32_e32 v133, 16, v128
	v_mul_f32_e32 v136, 0xbfb8aa3b, v133
	v_exp_f32_e32 v136, v136
	v_and_b32_e32 v128, 0xffff0000, v128
	v_add_f32_e32 v136, 1.0, v136
	v_rcp_f32_e32 v136, v136
	s_nop 0
	v_mul_f32_e32 v133, v136, v133
	v_mul_f32_e32 v130, v133, v130
	v_mul_f32_e32 v133, 0xbfb8aa3b, v128
	v_exp_f32_e32 v133, v133
	s_nop 0
	v_add_f32_e32 v133, 1.0, v133
	v_rcp_f32_e32 v133, v133
	s_nop 0
	v_mul_f32_e32 v128, v133, v128
	v_mul_f32_e32 v128, v128, v131
	v_mul_f32_e32 v131, 0xbfb8aa3b, v129
	v_exp_f32_e32 v131, v131
	v_cvt_pk_bf16_f32 v128, v130, v128
	v_add_co_u32_e32 v130, vcc, s24, v134
	v_add_f32_e32 v131, 1.0, v131
	v_rcp_f32_e32 v131, v131
	s_nop 0
	v_mul_f32_e32 v129, v131, v129
	v_mul_f32_e32 v129, v129, v132
	v_cvt_pk_bf16_f32 v129, v129, v0
	v_addc_co_u32_e32 v131, vcc, 0, v135, vcc
	global_store_dwordx4 v[130:131], v[126:129], off offset:3072
	ds_read_b128 v[126:129], v155 offset:59136
	ds_read_b128 v[160:163], v155 offset:59200
	ds_read_b128 v[238:241], v155 offset:59264
	ds_read_b128 v[242:245], v155 offset:59328
	ds_read_b128 v[246:249], v155 offset:59392
	ds_read_b128 v[228:231], v155 offset:59456
	s_waitcnt lgkmcnt(5)
	v_mfma_f32_16x16x32_bf16 v[130:133], v[2:5], v[126:129], 0
	v_mfma_f32_16x16x32_bf16 v[126:129], v[34:37], v[126:129], 0
	s_waitcnt lgkmcnt(4)
	v_mfma_f32_16x16x32_bf16 v[130:133], v[6:9], v[160:163], v[130:133]
	v_mfma_f32_16x16x32_bf16 v[126:129], v[38:41], v[160:163], v[126:129]
	ds_read_b128 v[160:163], v155 offset:59520
	s_waitcnt lgkmcnt(4)
	v_mfma_f32_16x16x32_bf16 v[130:133], v[10:13], v[238:241], v[130:133]
	v_mfma_f32_16x16x32_bf16 v[126:129], v[42:45], v[238:241], v[126:129]
	ds_read_b128 v[238:241], v155 offset:59584
	s_waitcnt lgkmcnt(4)
	v_mfma_f32_16x16x32_bf16 v[130:133], v[14:17], v[242:245], v[130:133]
	v_mfma_f32_16x16x32_bf16 v[126:129], v[46:49], v[242:245], v[126:129]
	s_waitcnt lgkmcnt(3)
	v_mfma_f32_16x16x32_bf16 v[130:133], v[18:21], v[246:249], v[130:133]
	v_mfma_f32_16x16x32_bf16 v[126:129], v[50:53], v[246:249], v[126:129]
	s_waitcnt lgkmcnt(2)
	v_mfma_f32_16x16x32_bf16 v[130:133], v[22:25], v[228:231], v[130:133]
	v_mfma_f32_16x16x32_bf16 v[126:129], v[54:57], v[228:231], v[126:129]
	s_waitcnt lgkmcnt(1)
	v_mfma_f32_16x16x32_bf16 v[130:133], v[26:29], v[160:163], v[130:133]
	v_mfma_f32_16x16x32_bf16 v[126:129], v[58:61], v[160:163], v[126:129]
	s_waitcnt lgkmcnt(0)
	v_mfma_f32_16x16x32_bf16 v[130:133], v[30:33], v[238:241], v[130:133]
	v_mfma_f32_16x16x32_bf16 v[126:129], v[62:65], v[238:241], v[126:129]
	s_nop 6
	v_add_f32_e32 v0, v73, v133
	v_and_b32_e32 v133, 0xffff0000, v123
	v_mul_f32_e32 v136, 0xbfb8aa3b, v133
	v_exp_f32_e32 v136, v136
	v_mul_f32_e32 v0, v81, v0
	v_add_f32_e32 v130, v70, v130
	v_mul_f32_e32 v130, v78, v130
	v_add_f32_e32 v136, 1.0, v136
	v_rcp_f32_e32 v136, v136
	v_add_f32_e32 v131, v71, v131
	v_mul_f32_e32 v131, v79, v131
	v_lshlrev_b32_e32 v123, 16, v123
	v_mul_f32_e32 v133, v136, v133
	v_mul_f32_e32 v0, v133, v0
	v_lshlrev_b32_e32 v133, 16, v122
	v_mul_f32_e32 v136, 0xbfb8aa3b, v133
	v_exp_f32_e32 v136, v136
	v_and_b32_e32 v122, 0xffff0000, v122
	v_add_f32_e32 v132, v72, v132
	v_mul_f32_e32 v132, v80, v132
	v_add_f32_e32 v136, 1.0, v136
	v_rcp_f32_e32 v136, v136
	v_add_f32_e32 v126, v66, v126
	v_mul_f32_e32 v126, v74, v126
	v_add_f32_e32 v127, v67, v127
	v_mul_f32_e32 v133, v136, v133
	v_mul_f32_e32 v130, v133, v130
	v_mul_f32_e32 v133, 0xbfb8aa3b, v122
	v_exp_f32_e32 v133, v133
	v_mul_f32_e32 v127, v75, v127
	v_add_f32_e32 v128, v68, v128
	v_mul_f32_e32 v128, v76, v128
	v_add_f32_e32 v133, 1.0, v133
	v_rcp_f32_e32 v133, v133
	s_nop 0
	v_mul_f32_e32 v122, v133, v122
	v_mul_f32_e32 v122, v122, v131
	v_mul_f32_e32 v131, 0xbfb8aa3b, v123
	v_exp_f32_e32 v131, v131
	v_cvt_pk_bf16_f32 v122, v130, v122
	s_nop 0
	v_add_f32_e32 v131, 1.0, v131
	v_rcp_f32_e32 v131, v131
	s_nop 0
	v_mul_f32_e32 v123, v131, v123
	v_mul_f32_e32 v123, v123, v132
	v_cvt_pk_bf16_f32 v123, v123, v0
	v_add_f32_e32 v0, v69, v129
	v_and_b32_e32 v129, 0xffff0000, v125
	v_mul_f32_e32 v130, 0xbfb8aa3b, v129
	v_exp_f32_e32 v130, v130
	v_mul_f32_e32 v0, v77, v0
	v_lshlrev_b32_e32 v125, 16, v125
	v_add_f32_e32 v130, 1.0, v130
	v_rcp_f32_e32 v130, v130
	s_nop 0
	v_mul_f32_e32 v129, v130, v129
	v_mul_f32_e32 v0, v129, v0
	v_lshlrev_b32_e32 v129, 16, v124
	v_mul_f32_e32 v130, 0xbfb8aa3b, v129
	v_exp_f32_e32 v130, v130
	v_and_b32_e32 v124, 0xffff0000, v124
	v_add_f32_e32 v130, 1.0, v130
	v_rcp_f32_e32 v130, v130
	s_nop 0
	v_mul_f32_e32 v129, v130, v129
	v_mul_f32_e32 v126, v129, v126
	v_mul_f32_e32 v129, 0xbfb8aa3b, v124
	v_exp_f32_e32 v129, v129
	s_nop 0
	v_add_f32_e32 v129, 1.0, v129
	v_rcp_f32_e32 v129, v129
	s_nop 0
	v_mul_f32_e32 v124, v129, v124
	v_mul_f32_e32 v124, v124, v127
	v_mul_f32_e32 v127, 0xbfb8aa3b, v125
	v_exp_f32_e32 v127, v127
	v_cvt_pk_bf16_f32 v124, v126, v124
	v_add_co_u32_e32 v126, vcc, s25, v134
	v_add_f32_e32 v127, 1.0, v127
	v_rcp_f32_e32 v127, v127
	s_nop 0
	v_mul_f32_e32 v125, v127, v125
	v_mul_f32_e32 v125, v125, v128
	v_cvt_pk_bf16_f32 v125, v125, v0
	v_addc_co_u32_e32 v127, vcc, 0, v135, vcc
	global_store_dwordx4 v[126:127], v[122:125], off offset:3072
	ds_read_b128 v[122:125], v156 offset:25344
	ds_read_b128 v[130:133], v156 offset:25408
	ds_read_b128 v[238:241], v156 offset:25472
	ds_read_b128 v[242:245], v156 offset:25536
	ds_read_b128 v[246:249], v156 offset:25600
	ds_read_b128 v[228:231], v156 offset:25664
	s_waitcnt lgkmcnt(5)
	v_mfma_f32_16x16x32_bf16 v[126:129], v[2:5], v[122:125], 0
	v_mfma_f32_16x16x32_bf16 v[122:125], v[34:37], v[122:125], 0
	s_waitcnt lgkmcnt(4)
	v_mfma_f32_16x16x32_bf16 v[126:129], v[6:9], v[130:133], v[126:129]
	v_mfma_f32_16x16x32_bf16 v[122:125], v[38:41], v[130:133], v[122:125]
	ds_read_b128 v[130:133], v156 offset:25728
	s_waitcnt lgkmcnt(4)
	v_mfma_f32_16x16x32_bf16 v[126:129], v[10:13], v[238:241], v[126:129]
	v_mfma_f32_16x16x32_bf16 v[122:125], v[42:45], v[238:241], v[122:125]
	ds_read_b128 v[238:241], v156 offset:25792
	s_waitcnt lgkmcnt(4)
	v_mfma_f32_16x16x32_bf16 v[126:129], v[14:17], v[242:245], v[126:129]
	v_mfma_f32_16x16x32_bf16 v[122:125], v[46:49], v[242:245], v[122:125]
	s_waitcnt lgkmcnt(3)
	v_mfma_f32_16x16x32_bf16 v[126:129], v[18:21], v[246:249], v[126:129]
	v_mfma_f32_16x16x32_bf16 v[122:125], v[50:53], v[246:249], v[122:125]
	s_waitcnt lgkmcnt(2)
	v_mfma_f32_16x16x32_bf16 v[126:129], v[22:25], v[228:231], v[126:129]
	v_mfma_f32_16x16x32_bf16 v[122:125], v[54:57], v[228:231], v[122:125]
	s_waitcnt lgkmcnt(1)
	v_mfma_f32_16x16x32_bf16 v[126:129], v[26:29], v[130:133], v[126:129]
	v_mfma_f32_16x16x32_bf16 v[122:125], v[58:61], v[130:133], v[122:125]
	s_waitcnt lgkmcnt(0)
	v_mfma_f32_16x16x32_bf16 v[126:129], v[30:33], v[238:241], v[126:129]
	v_mfma_f32_16x16x32_bf16 v[122:125], v[62:65], v[238:241], v[122:125]
	s_nop 6
	v_add_f32_e32 v0, v73, v129
	v_and_b32_e32 v129, 0xffff0000, v99
	v_mul_f32_e32 v130, 0xbfb8aa3b, v129
	v_exp_f32_e32 v130, v130
	v_mul_f32_e32 v0, v81, v0
	v_add_f32_e32 v126, v70, v126
	v_mul_f32_e32 v126, v78, v126
	v_add_f32_e32 v130, 1.0, v130
	v_rcp_f32_e32 v130, v130
	v_add_f32_e32 v127, v71, v127
	v_mul_f32_e32 v127, v79, v127
	v_lshlrev_b32_e32 v99, 16, v99
	v_mul_f32_e32 v129, v130, v129
	v_mul_f32_e32 v0, v129, v0
	v_lshlrev_b32_e32 v129, 16, v98
	v_mul_f32_e32 v130, 0xbfb8aa3b, v129
	v_exp_f32_e32 v130, v130
	v_and_b32_e32 v98, 0xffff0000, v98
	v_add_f32_e32 v128, v72, v128
	v_mul_f32_e32 v128, v80, v128
	v_add_f32_e32 v130, 1.0, v130
	v_rcp_f32_e32 v130, v130
	v_add_f32_e32 v122, v66, v122
	v_mul_f32_e32 v122, v74, v122
	v_add_f32_e32 v123, v67, v123
	v_mul_f32_e32 v129, v130, v129
	v_mul_f32_e32 v126, v129, v126
	v_mul_f32_e32 v129, 0xbfb8aa3b, v98
	v_exp_f32_e32 v129, v129
	v_mul_f32_e32 v123, v75, v123
	v_add_f32_e32 v124, v68, v124
	v_mul_f32_e32 v124, v76, v124
	v_add_f32_e32 v129, 1.0, v129
	v_rcp_f32_e32 v129, v129
	s_waitcnt vmcnt(6)
	v_mov_b64_e32 v[132:133], v[84:85]
	v_mov_b64_e32 v[130:131], v[82:83]
	v_mul_f32_e32 v98, v129, v98
	v_mul_f32_e32 v98, v98, v127
	v_mul_f32_e32 v127, 0xbfb8aa3b, v99
	v_exp_f32_e32 v127, v127
	v_cvt_pk_bf16_f32 v98, v126, v98
	s_nop 0
	v_add_f32_e32 v127, 1.0, v127
	v_rcp_f32_e32 v127, v127
	s_nop 0
	v_mul_f32_e32 v99, v127, v99
	v_mul_f32_e32 v99, v99, v128
	v_cvt_pk_bf16_f32 v99, v99, v0
	v_add_f32_e32 v0, v69, v125
	v_and_b32_e32 v125, 0xffff0000, v101
	v_mul_f32_e32 v126, 0xbfb8aa3b, v125
	v_exp_f32_e32 v126, v126
	v_mul_f32_e32 v0, v77, v0
	v_lshlrev_b32_e32 v101, 16, v101
	v_add_f32_e32 v126, 1.0, v126
	v_rcp_f32_e32 v126, v126
	s_nop 0
	v_mul_f32_e32 v125, v126, v125
	v_mul_f32_e32 v0, v125, v0
	v_lshlrev_b32_e32 v125, 16, v100
	v_mul_f32_e32 v126, 0xbfb8aa3b, v125
	v_exp_f32_e32 v126, v126
	v_and_b32_e32 v100, 0xffff0000, v100
	v_add_f32_e32 v126, 1.0, v126
	v_rcp_f32_e32 v126, v126
	s_nop 0
	v_mul_f32_e32 v125, v126, v125
	v_mul_f32_e32 v122, v125, v122
	v_mul_f32_e32 v125, 0xbfb8aa3b, v100
	v_exp_f32_e32 v125, v125
	s_waitcnt vmcnt(5)
	v_mov_b64_e32 v[128:129], v[88:89]
	v_mov_b64_e32 v[126:127], v[86:87]
	v_add_f32_e32 v125, 1.0, v125
	v_rcp_f32_e32 v125, v125
	s_nop 0
	v_mul_f32_e32 v100, v125, v100
	v_mul_f32_e32 v100, v100, v123
	v_mul_f32_e32 v123, 0xbfb8aa3b, v101
	v_exp_f32_e32 v123, v123
	v_cvt_pk_bf16_f32 v100, v122, v100
	v_add_co_u32_e32 v122, vcc, s14, v134
	v_add_f32_e32 v123, 1.0, v123
	v_rcp_f32_e32 v123, v123
	s_nop 0
	v_mul_f32_e32 v101, v123, v101
	v_mul_f32_e32 v101, v101, v124
	v_cvt_pk_bf16_f32 v101, v101, v0
	v_addc_co_u32_e32 v123, vcc, 0, v135, vcc
	global_store_dwordx4 v[122:123], v[98:101], off offset:3072
	s_waitcnt vmcnt(5)
	v_mov_b64_e32 v[124:125], v[92:93]
	v_mov_b64_e32 v[122:123], v[90:91]
	s_waitcnt vmcnt(4)
	v_mov_b64_e32 v[100:101], v[96:97]
	v_mov_b64_e32 v[98:99], v[94:95]
	ds_write_b128 v149, v[102:105] offset:8448
	ds_write_b128 v150, v[106:109] offset:8448
	ds_write_b128 v151, v[110:113] offset:8448
	ds_write_b128 v152, v[114:117] offset:8448
	ds_write_b128 v153, v[118:121]
	s_cbranch_scc1 .LBB0_130
	s_waitcnt lgkmcnt(0)
	s_barrier

.LBB0_138:
	s_waitcnt lgkmcnt(0)
	s_barrier
	ds_read_b128 v[122:125], v168 offset:33792
	ds_read_b128 v[134:137], v0 offset:7920
	s_and_b32 s6, s11, 0xfffff000
	s_ashr_i32 s7, s6, 31
	s_lshl_b64 s[6:7], s[6:7], 11
	s_add_u32 s2, s90, s44
	s_addc_u32 s19, s91, s45
	s_waitcnt lgkmcnt(0)
	v_lshlrev_b32_e32 v143, 16, v134
	v_and_b32_e32 v134, 0xffff0000, v134
	s_add_u32 s18, s2, s6
	v_add_f32_e32 v177, 0, v134
	v_lshlrev_b32_e32 v134, 16, v135
	s_waitcnt vmcnt(4)
	v_mov_b64_e32 v[104:105], v[84:85]
	s_addc_u32 s19, s19, s7
	v_add_f32_e32 v178, 0, v134
	v_and_b32_e32 v134, 0xffff0000, v135
	v_mov_b64_e32 v[102:103], v[82:83]
	v_lshl_add_u64 v[82:83], s[18:19], 0, v[160:161]
	v_add_f32_e32 v179, 0, v134
	v_lshlrev_b32_e32 v134, 16, v136
	v_add_u32_e32 v184, s10, v141
	global_load_dwordx4 v[106:109], v[82:83], off
	v_lshl_add_u64 v[82:83], s[18:19], 0, v[158:159]
	v_add_f32_e32 v180, 0, v134
	v_and_b32_e32 v134, 0xffff0000, v136
	v_min_i32_e32 v193, 1, v184
	global_load_dwordx4 v[110:113], v[82:83], off
	v_lshl_add_u64 v[82:83], s[18:19], 0, v[156:157]
	s_add_u32 s6, s44, s6
	v_add_f32_e32 v181, 0, v134
	v_lshlrev_b32_e32 v134, 16, v137
	v_add_u32_e32 v193, 1, v193
	global_load_dwordx4 v[114:117], v[82:83], off
	v_lshl_add_u64 v[82:83], s[18:19], 0, v[154:155]
	s_addc_u32 s7, s45, s7
	v_add_f32_e32 v182, 0, v134
	v_and_b32_e32 v134, 0xffff0000, v137
	v_cvt_f32_i32_e32 v193, v193
	global_load_dwordx4 v[118:121], v[82:83], off
	v_lshl_add_u64 v[82:83], s[6:7], 0, v[144:145]
	v_add_f32_e32 v183, 0, v134
	ds_read_b128 v[134:137], v176 offset:8448
	v_lshl_add_u64 v[82:83], v[146:147], 0, v[82:83]
	global_load_dwordx4 v[94:97], v[82:83], off
	v_lshl_add_u64 v[82:83], s[6:7], 0, v[148:149]
	v_mov_b64_e32 v[132:133], v[92:93]
	v_lshl_add_u64 v[82:83], v[146:147], 0, v[82:83]
	v_rcp_iflag_f32_e32 v193, v193
	v_mov_b64_e32 v[130:131], v[90:91]
	global_load_dwordx4 v[90:93], v[82:83], off
	v_lshl_add_u64 v[82:83], s[6:7], 0, v[150:151]
	v_mov_b64_e32 v[128:129], v[88:89]
	v_lshl_add_u64 v[82:83], v[146:147], 0, v[82:83]
	s_waitcnt lgkmcnt(0)
	v_lshlrev_b32_e32 v185, 16, v134
	v_and_b32_e32 v134, 0xffff0000, v134
	v_lshlrev_b32_e32 v190, 16, v135
	v_and_b32_e32 v135, 0xffff0000, v135
	v_lshlrev_b32_e32 v191, 16, v136
	v_and_b32_e32 v136, 0xffff0000, v136
	v_lshlrev_b32_e32 v192, 16, v137
	v_and_b32_e32 v137, 0xffff0000, v137
	v_mov_b64_e32 v[126:127], v[86:87]
	global_load_dwordx4 v[86:89], v[82:83], off
	v_lshl_add_u64 v[82:83], s[6:7], 0, v[152:153]
	v_add_f32_e32 v143, 0, v143
	v_add_f32_e32 v177, v177, v134
	v_add_f32_e32 v179, v179, v135
	v_add_f32_e32 v181, v181, v136
	v_add_f32_e32 v183, v183, v137
	v_lshl_add_u64 v[82:83], v[146:147], 0, v[82:83]
	v_add_f32_e32 v143, v143, v185
	v_fma_f32 v134, v177, v193, -v134
	v_add_f32_e32 v178, v178, v190
	v_fma_f32 v135, v179, v193, -v135
	v_add_f32_e32 v180, v180, v191
	v_fma_f32 v136, v181, v193, -v136
	v_add_f32_e32 v182, v182, v192
	v_fma_f32 v137, v183, v193, -v137
	global_load_dwordx4 v[82:85], v[82:83], off
	v_fma_f32 v185, v143, v193, -v185
	v_fma_f32 v190, v178, v193, -v190
	v_fma_f32 v191, v180, v193, -v191
	v_fma_f32 v192, v182, v193, -v192
	v_cvt_pk_bf16_f32 v134, v185, v134
	v_cvt_pk_bf16_f32 v135, v190, v135
	v_cvt_pk_bf16_f32 v136, v191, v136
	v_cvt_pk_bf16_f32 v137, v192, v137
	ds_write_b128 v0, v[134:137] offset:42240
	ds_read_b128 v[134:137], v176 offset:7920
	v_add_u32_e32 v193, 1, v184
	v_min_i32_e32 v193, 1, v193
	v_add_u32_e32 v193, 1, v193
	v_cvt_f32_i32_e32 v193, v193
	s_waitcnt lgkmcnt(0)
	v_lshlrev_b32_e32 v185, 16, v134
	v_and_b32_e32 v134, 0xffff0000, v134
	v_sub_f32_e32 v177, v177, v134
	v_lshlrev_b32_e32 v134, 16, v135
	v_sub_f32_e32 v178, v178, v134
	v_and_b32_e32 v134, 0xffff0000, v135
	v_sub_f32_e32 v179, v179, v134
	v_lshlrev_b32_e32 v134, 16, v136
	v_sub_f32_e32 v180, v180, v134
	v_and_b32_e32 v134, 0xffff0000, v136
	v_sub_f32_e32 v181, v181, v134
	v_lshlrev_b32_e32 v134, 16, v137
	v_sub_f32_e32 v182, v182, v134
	v_and_b32_e32 v134, 0xffff0000, v137
	v_sub_f32_e32 v183, v183, v134
	ds_read_b128 v[134:137], v176 offset:8976
	v_rcp_iflag_f32_e32 v193, v193
	v_sub_f32_e32 v143, v143, v185
	s_add_u32 s44, s44, 0x20000
	s_addc_u32 s45, s45, 0
	s_waitcnt lgkmcnt(0)
	v_lshlrev_b32_e32 v185, 16, v134
	v_and_b32_e32 v134, 0xffff0000, v134
	v_lshlrev_b32_e32 v190, 16, v135
	v_and_b32_e32 v135, 0xffff0000, v135
	v_lshlrev_b32_e32 v191, 16, v136
	v_and_b32_e32 v136, 0xffff0000, v136
	v_lshlrev_b32_e32 v192, 16, v137
	v_and_b32_e32 v137, 0xffff0000, v137
	v_add_f32_e32 v177, v177, v134
	v_add_f32_e32 v179, v179, v135
	v_add_f32_e32 v181, v181, v136
	v_add_f32_e32 v183, v183, v137
	v_add_f32_e32 v143, v143, v185
	v_fma_f32 v134, v177, v193, -v134
	v_add_f32_e32 v178, v178, v190
	v_fma_f32 v135, v179, v193, -v135
	v_add_f32_e32 v180, v180, v191
	v_fma_f32 v136, v181, v193, -v136
	v_add_f32_e32 v182, v182, v192
	v_fma_f32 v137, v183, v193, -v137
	v_fma_f32 v185, v143, v193, -v185
	v_fma_f32 v190, v178, v193, -v190
	v_fma_f32 v191, v180, v193, -v191
	v_fma_f32 v192, v182, v193, -v192
	v_cvt_pk_bf16_f32 v134, v185, v134
	v_cvt_pk_bf16_f32 v135, v190, v135
	v_cvt_pk_bf16_f32 v136, v191, v136
	v_cvt_pk_bf16_f32 v137, v192, v137
	ds_write_b128 v0, v[134:137] offset:42768
	ds_read_b128 v[134:137], v176 offset:8448
	v_add_u32_e32 v193, 2, v184
	v_min_i32_e32 v193, 1, v193
	v_add_u32_e32 v193, 1, v193
	v_cvt_f32_i32_e32 v193, v193
	s_waitcnt lgkmcnt(0)
	v_lshlrev_b32_e32 v185, 16, v134
	v_and_b32_e32 v134, 0xffff0000, v134
	v_sub_f32_e32 v177, v177, v134
	v_lshlrev_b32_e32 v134, 16, v135
	v_sub_f32_e32 v178, v178, v134
	v_and_b32_e32 v134, 0xffff0000, v135
	v_sub_f32_e32 v179, v179, v134
	v_lshlrev_b32_e32 v134, 16, v136
	v_sub_f32_e32 v180, v180, v134
	v_and_b32_e32 v134, 0xffff0000, v136
	v_sub_f32_e32 v181, v181, v134
	v_lshlrev_b32_e32 v134, 16, v137
	v_sub_f32_e32 v182, v182, v134
	v_and_b32_e32 v134, 0xffff0000, v137
	v_sub_f32_e32 v183, v183, v134
	ds_read_b128 v[134:137], v176 offset:9504
	v_rcp_iflag_f32_e32 v193, v193
	v_sub_f32_e32 v143, v143, v185
	v_add_u32_e32 v184, 3, v184
	v_min_i32_e32 v184, 1, v184
	s_waitcnt lgkmcnt(0)
	v_lshlrev_b32_e32 v185, 16, v134
	v_and_b32_e32 v134, 0xffff0000, v134
	v_lshlrev_b32_e32 v190, 16, v135
	v_and_b32_e32 v135, 0xffff0000, v135
	v_lshlrev_b32_e32 v191, 16, v136
	v_and_b32_e32 v136, 0xffff0000, v136
	v_lshlrev_b32_e32 v192, 16, v137
	v_and_b32_e32 v137, 0xffff0000, v137
	v_add_f32_e32 v177, v177, v134
	v_add_f32_e32 v179, v179, v135
	v_add_f32_e32 v181, v181, v136
	v_add_f32_e32 v183, v183, v137
	v_add_f32_e32 v143, v143, v185
	v_fma_f32 v134, v177, v193, -v134
	v_add_f32_e32 v178, v178, v190
	v_fma_f32 v135, v179, v193, -v135
	v_add_f32_e32 v180, v180, v191
	v_fma_f32 v136, v181, v193, -v136
	v_add_f32_e32 v182, v182, v192
	v_fma_f32 v137, v183, v193, -v137
	v_fma_f32 v185, v143, v193, -v185
	v_fma_f32 v190, v178, v193, -v190
	v_fma_f32 v191, v180, v193, -v191
	v_fma_f32 v192, v182, v193, -v192
	v_cvt_pk_bf16_f32 v134, v185, v134
	v_cvt_pk_bf16_f32 v135, v190, v135
	v_cvt_pk_bf16_f32 v136, v191, v136
	v_cvt_pk_bf16_f32 v137, v192, v137
	ds_write_b128 v0, v[134:137] offset:43296
	ds_read_b128 v[134:137], v176 offset:8976
	v_add_u32_e32 v184, 1, v184
	v_cvt_f32_i32_e32 v184, v184
	s_add_i32 s10, s10, 64
	s_add_i32 s11, s11, 64
	s_waitcnt lgkmcnt(0)
	v_lshlrev_b32_e32 v185, 16, v134
	v_and_b32_e32 v134, 0xffff0000, v134
	v_sub_f32_e32 v177, v177, v134
	v_lshlrev_b32_e32 v134, 16, v135
	v_sub_f32_e32 v178, v178, v134
	v_and_b32_e32 v134, 0xffff0000, v135
	v_sub_f32_e32 v179, v179, v134
	v_lshlrev_b32_e32 v134, 16, v136
	v_sub_f32_e32 v180, v180, v134
	v_and_b32_e32 v134, 0xffff0000, v136
	v_sub_f32_e32 v181, v181, v134
	v_lshlrev_b32_e32 v134, 16, v137
	v_sub_f32_e32 v182, v182, v134
	v_and_b32_e32 v134, 0xffff0000, v137
	v_sub_f32_e32 v183, v183, v134
	ds_read_b128 v[134:137], v176 offset:10032
	v_rcp_iflag_f32_e32 v184, v184
	v_sub_f32_e32 v143, v143, v185
	s_cmp_lg_u32 s44, 0xe0000
	s_waitcnt lgkmcnt(0)
	v_lshlrev_b32_e32 v185, 16, v134
	v_and_b32_e32 v134, 0xffff0000, v134
	v_lshlrev_b32_e32 v190, 16, v135
	v_and_b32_e32 v135, 0xffff0000, v135
	v_add_f32_e32 v177, v177, v134
	v_lshlrev_b32_e32 v191, 16, v136
	v_and_b32_e32 v136, 0xffff0000, v136
	v_lshlrev_b32_e32 v192, 16, v137
	v_and_b32_e32 v137, 0xffff0000, v137
	v_fma_f32 v134, v177, v184, -v134
	v_add_f32_e32 v177, v178, v190
	v_add_f32_e32 v178, v179, v135
	v_fma_f32 v135, v178, v184, -v135
	v_add_f32_e32 v178, v180, v191
	v_add_f32_e32 v179, v181, v136
	v_add_f32_e32 v180, v183, v137
	v_add_f32_e32 v143, v143, v185
	v_fma_f32 v136, v179, v184, -v136
	v_add_f32_e32 v179, v182, v192
	v_fma_f32 v137, v180, v184, -v137
	v_fma_f32 v143, v143, v184, -v185
	v_fma_f32 v177, v177, v184, -v190
	v_fma_f32 v178, v178, v184, -v191
	v_fma_f32 v179, v179, v184, -v192
	v_cvt_pk_bf16_f32 v134, v143, v134
	v_cvt_pk_bf16_f32 v135, v177, v135
	v_cvt_pk_bf16_f32 v136, v178, v136
	v_cvt_pk_bf16_f32 v137, v179, v137
	ds_write_b128 v0, v[134:137] offset:43824
	s_waitcnt lgkmcnt(0)
	s_barrier
	ds_read_b128 v[134:137], v170 offset:42240
	ds_read_b128 v[182:185], v170 offset:42304
	ds_read_b128 v[238:241], v170 offset:42368
	ds_read_b128 v[242:245], v170 offset:42432
	ds_read_b128 v[246:249], v170 offset:42496
	ds_read_b128 v[228:231], v170 offset:42560
	s_waitcnt lgkmcnt(5)
	v_mfma_f32_16x16x32_bf16 v[178:181], v[74:77], v[134:137], 0
	v_mfma_f32_16x16x32_bf16 v[134:137], v[78:81], v[134:137], 0
	s_waitcnt lgkmcnt(4)
	v_mfma_f32_16x16x32_bf16 v[178:181], v[62:65], v[182:185], v[178:181]
	v_mfma_f32_16x16x32_bf16 v[134:137], v[70:73], v[182:185], v[134:137]
	ds_read_b128 v[182:185], v170 offset:42624
	s_waitcnt lgkmcnt(4)
	v_mfma_f32_16x16x32_bf16 v[178:181], v[58:61], v[238:241], v[178:181]
	v_mfma_f32_16x16x32_bf16 v[134:137], v[66:69], v[238:241], v[134:137]
	ds_read_b128 v[238:241], v170 offset:42688
	s_waitcnt lgkmcnt(4)
	v_mfma_f32_16x16x32_bf16 v[178:181], v[46:49], v[242:245], v[178:181]
	v_mfma_f32_16x16x32_bf16 v[134:137], v[54:57], v[242:245], v[134:137]
	s_waitcnt lgkmcnt(3)
	v_mfma_f32_16x16x32_bf16 v[178:181], v[42:45], v[246:249], v[178:181]
	v_mfma_f32_16x16x32_bf16 v[134:137], v[50:53], v[246:249], v[134:137]
	s_waitcnt lgkmcnt(2)
	v_mfma_f32_16x16x32_bf16 v[178:181], v[30:33], v[228:231], v[178:181]
	v_mfma_f32_16x16x32_bf16 v[134:137], v[38:41], v[228:231], v[134:137]
	s_waitcnt lgkmcnt(1)
	v_mfma_f32_16x16x32_bf16 v[178:181], v[26:29], v[182:185], v[178:181]
	v_mfma_f32_16x16x32_bf16 v[134:137], v[34:37], v[182:185], v[134:137]
	s_waitcnt lgkmcnt(0)
	v_mfma_f32_16x16x32_bf16 v[178:181], v[10:13], v[238:241], v[178:181]
	v_mfma_f32_16x16x32_bf16 v[134:137], v[14:17], v[238:241], v[134:137]
	s_nop 6
	v_add_f32_e32 v181, v25, v181
	v_add_f32_e32 v143, v24, v180
	v_and_b32_e32 v180, 0xffff0000, v99
	v_add_f32_e32 v177, v23, v179
	v_mul_f32_e32 v179, v21, v181
	v_mul_f32_e32 v181, 0xbfb8aa3b, v180
	v_exp_f32_e32 v181, v181
	v_add_f32_e32 v178, v22, v178
	v_mul_f32_e32 v178, v18, v178
	v_mul_f32_e32 v177, v19, v177
	v_add_f32_e32 v181, 1.0, v181
	v_rcp_f32_e32 v181, v181
	v_lshlrev_b32_e32 v99, 16, v99
	v_mul_f32_e32 v143, v20, v143
	v_mul_f32_e32 v180, v181, v180
	v_mul_f32_e32 v179, v180, v179
	v_lshlrev_b32_e32 v180, 16, v98
	v_mul_f32_e32 v181, 0xbfb8aa3b, v180
	v_exp_f32_e32 v181, v181
	v_and_b32_e32 v98, 0xffff0000, v98
	v_add_f32_e32 v181, 1.0, v181
	v_rcp_f32_e32 v181, v181
	s_nop 0
	v_mul_f32_e32 v180, v181, v180
	v_mul_f32_e32 v178, v180, v178
	v_mul_f32_e32 v180, 0xbfb8aa3b, v98
	v_exp_f32_e32 v180, v180
	s_nop 0
	v_add_f32_e32 v180, 1.0, v180
	v_rcp_f32_e32 v180, v180
	s_nop 0
	v_mul_f32_e32 v98, v180, v98
	v_mul_f32_e32 v98, v98, v177
	v_mul_f32_e32 v177, 0xbfb8aa3b, v99
	v_exp_f32_e32 v177, v177
	v_cvt_pk_bf16_f32 v178, v178, v98
	v_add_f32_e32 v98, v9, v137
	v_mul_f32_e32 v98, v5, v98
	v_add_f32_e32 v177, 1.0, v177
	v_rcp_f32_e32 v177, v177
	s_nop 0
	v_mul_f32_e32 v99, v177, v99
	v_mul_f32_e32 v99, v99, v143
	v_cvt_pk_bf16_f32 v179, v99, v179
	v_add_f32_e32 v99, v6, v134
	v_add_f32_e32 v134, v7, v135
	v_add_f32_e32 v135, v8, v136
	v_and_b32_e32 v136, 0xffff0000, v101
	v_mul_f32_e32 v137, 0xbfb8aa3b, v136
	v_exp_f32_e32 v137, v137
	v_mul_f32_e32 v99, v2, v99
	v_mul_f32_e32 v134, v3, v134
	v_lshlrev_b32_e32 v101, 16, v101
	v_add_f32_e32 v137, 1.0, v137
	v_rcp_f32_e32 v137, v137
	v_mul_f32_e32 v135, v4, v135
	v_mul_f32_e32 v136, v137, v136
	v_mul_f32_e32 v98, v136, v98
	v_lshlrev_b32_e32 v136, 16, v100
	v_mul_f32_e32 v137, 0xbfb8aa3b, v136
	v_exp_f32_e32 v137, v137
	v_and_b32_e32 v100, 0xffff0000, v100
	v_add_f32_e32 v137, 1.0, v137
	v_rcp_f32_e32 v137, v137
	s_nop 0
	v_mul_f32_e32 v136, v137, v136
	v_mul_f32_e32 v99, v136, v99
	v_mul_f32_e32 v136, 0xbfb8aa3b, v100
	v_exp_f32_e32 v136, v136
	s_nop 0
	v_add_f32_e32 v136, 1.0, v136
	v_rcp_f32_e32 v136, v136
	s_nop 0
	v_mul_f32_e32 v100, v136, v100
	v_mul_f32_e32 v100, v100, v134
	v_mul_f32_e32 v134, 0xbfb8aa3b, v101
	v_exp_f32_e32 v134, v134
	v_cvt_pk_bf16_f32 v180, v99, v100
	s_nop 0
	v_add_f32_e32 v134, 1.0, v134
	v_rcp_f32_e32 v134, v134
	s_nop 0
	v_mul_f32_e32 v101, v134, v101
	v_mul_f32_e32 v101, v101, v135
	v_cvt_pk_bf16_f32 v181, v101, v98
	ds_read_b128 v[134:137], v170 offset:50688
	ds_read_b128 v[182:185], v170 offset:50752
	ds_read_b128 v[238:241], v170 offset:50816
	ds_read_b128 v[242:245], v170 offset:50880
	ds_read_b128 v[246:249], v170 offset:50944
	ds_read_b128 v[228:231], v170 offset:51008
	v_lshl_add_u64 v[98:99], s[90:91], 0, v[162:163]
	v_add_co_u32_e32 v100, vcc, s9, v98
	v_lshl_add_u64 v[162:163], v[162:163], 0, s[36:37]
	s_nop 0
	v_addc_co_u32_e32 v101, vcc, 0, v99, vcc
	global_store_dwordx4 v[100:101], v[178:181], off offset:2048
	s_nop 0
	s_waitcnt lgkmcnt(5)
	v_mfma_f32_16x16x32_bf16 v[178:181], v[74:77], v[134:137], 0
	v_mfma_f32_16x16x32_bf16 v[134:137], v[78:81], v[134:137], 0
	s_waitcnt lgkmcnt(4)
	v_mfma_f32_16x16x32_bf16 v[178:181], v[62:65], v[182:185], v[178:181]
	v_mfma_f32_16x16x32_bf16 v[134:137], v[70:73], v[182:185], v[134:137]
	ds_read_b128 v[182:185], v170 offset:51072
	s_waitcnt lgkmcnt(4)
	v_mfma_f32_16x16x32_bf16 v[178:181], v[58:61], v[238:241], v[178:181]
	v_mfma_f32_16x16x32_bf16 v[134:137], v[66:69], v[238:241], v[134:137]
	ds_read_b128 v[238:241], v170 offset:51136
	s_waitcnt lgkmcnt(4)
	v_mfma_f32_16x16x32_bf16 v[178:181], v[46:49], v[242:245], v[178:181]
	v_mfma_f32_16x16x32_bf16 v[134:137], v[54:57], v[242:245], v[134:137]
	s_waitcnt lgkmcnt(3)
	v_mfma_f32_16x16x32_bf16 v[178:181], v[42:45], v[246:249], v[178:181]
	v_mfma_f32_16x16x32_bf16 v[134:137], v[50:53], v[246:249], v[134:137]
	s_waitcnt lgkmcnt(2)
	v_mfma_f32_16x16x32_bf16 v[178:181], v[30:33], v[228:231], v[178:181]
	v_mfma_f32_16x16x32_bf16 v[134:137], v[38:41], v[228:231], v[134:137]
	s_waitcnt lgkmcnt(1)
	v_mfma_f32_16x16x32_bf16 v[178:181], v[26:29], v[182:185], v[178:181]
	v_mfma_f32_16x16x32_bf16 v[134:137], v[34:37], v[182:185], v[134:137]
	s_waitcnt lgkmcnt(0)
	v_mfma_f32_16x16x32_bf16 v[178:181], v[10:13], v[238:241], v[178:181]
	v_mfma_f32_16x16x32_bf16 v[134:137], v[14:17], v[238:241], v[134:137]
	s_nop 6
	v_add_f32_e32 v101, v22, v178
	v_and_b32_e32 v178, 0xffff0000, v131
	v_add_f32_e32 v143, v23, v179
	v_mul_f32_e32 v179, 0xbfb8aa3b, v178
	v_exp_f32_e32 v179, v179
	v_add_f32_e32 v100, v25, v181
	v_mul_f32_e32 v100, v21, v100
	v_mul_f32_e32 v101, v18, v101
	v_add_f32_e32 v179, 1.0, v179
	v_rcp_f32_e32 v179, v179
	v_mul_f32_e32 v143, v19, v143
	v_lshlrev_b32_e32 v131, 16, v131
	v_add_f32_e32 v177, v24, v180
	v_mul_f32_e32 v178, v179, v178
	v_mul_f32_e32 v100, v178, v100
	v_lshlrev_b32_e32 v178, 16, v130
	v_mul_f32_e32 v179, 0xbfb8aa3b, v178
	v_exp_f32_e32 v179, v179
	v_and_b32_e32 v130, 0xffff0000, v130
	v_mul_f32_e32 v177, v20, v177
	v_add_f32_e32 v179, 1.0, v179
	v_rcp_f32_e32 v179, v179
	s_nop 0
	v_mul_f32_e32 v178, v179, v178
	v_mul_f32_e32 v101, v178, v101
	v_mul_f32_e32 v178, 0xbfb8aa3b, v130
	v_exp_f32_e32 v178, v178
	s_nop 0
	v_add_f32_e32 v178, 1.0, v178
	v_rcp_f32_e32 v178, v178
	s_nop 0
	v_mul_f32_e32 v130, v178, v130
	v_mul_f32_e32 v130, v130, v143
	v_mul_f32_e32 v143, 0xbfb8aa3b, v131
	v_exp_f32_e32 v143, v143
	v_cvt_pk_bf16_f32 v130, v101, v130
	v_add_f32_e32 v101, v6, v134
	v_add_f32_e32 v134, v7, v135
	v_add_f32_e32 v143, 1.0, v143
	v_rcp_f32_e32 v143, v143
	v_add_f32_e32 v135, v8, v136
	v_and_b32_e32 v136, 0xffff0000, v133
	v_mul_f32_e32 v101, v2, v101
	v_mul_f32_e32 v131, v143, v131
	v_mul_f32_e32 v131, v131, v177
	v_cvt_pk_bf16_f32 v131, v131, v100
	v_add_f32_e32 v100, v9, v137
	v_mul_f32_e32 v137, 0xbfb8aa3b, v136
	v_exp_f32_e32 v137, v137
	v_mul_f32_e32 v100, v5, v100
	v_mul_f32_e32 v134, v3, v134
	v_lshlrev_b32_e32 v133, 16, v133
	v_add_f32_e32 v137, 1.0, v137
	v_rcp_f32_e32 v137, v137
	v_mul_f32_e32 v135, v4, v135
	v_mul_f32_e32 v136, v137, v136
	v_mul_f32_e32 v100, v136, v100
	v_lshlrev_b32_e32 v136, 16, v132
	v_mul_f32_e32 v137, 0xbfb8aa3b, v136
	v_exp_f32_e32 v137, v137
	v_and_b32_e32 v132, 0xffff0000, v132
	v_add_f32_e32 v137, 1.0, v137
	v_rcp_f32_e32 v137, v137
	s_nop 0
	v_mul_f32_e32 v136, v137, v136
	v_mul_f32_e32 v101, v136, v101
	v_mul_f32_e32 v136, 0xbfb8aa3b, v132
	v_exp_f32_e32 v136, v136
	s_nop 0
	v_add_f32_e32 v136, 1.0, v136
	v_rcp_f32_e32 v136, v136
	s_nop 0
	v_mul_f32_e32 v132, v136, v132
	v_mul_f32_e32 v132, v132, v134
	v_mul_f32_e32 v134, 0xbfb8aa3b, v133
	v_exp_f32_e32 v134, v134
	v_cvt_pk_bf16_f32 v132, v101, v132
	s_nop 0
	v_add_f32_e32 v134, 1.0, v134
	v_rcp_f32_e32 v134, v134
	s_nop 0
	v_mul_f32_e32 v133, v134, v133
	v_mul_f32_e32 v133, v133, v135
	v_cvt_pk_bf16_f32 v133, v133, v100
	v_add_co_u32_e32 v100, vcc, s24, v98
	ds_read_b128 v[178:181], v170 offset:59200
	s_nop 0
	v_addc_co_u32_e32 v101, vcc, 0, v99, vcc
	global_store_dwordx4 v[100:101], v[130:133], off offset:2048
	ds_read_b128 v[130:133], v170 offset:59136
	ds_read_b128 v[238:241], v170 offset:59264
	ds_read_b128 v[242:245], v170 offset:59328
	ds_read_b128 v[246:249], v170 offset:59392
	ds_read_b128 v[228:231], v170 offset:59456
	s_waitcnt lgkmcnt(4)
	v_mfma_f32_16x16x32_bf16 v[134:137], v[74:77], v[130:133], 0
	v_mfma_f32_16x16x32_bf16 v[130:133], v[78:81], v[130:133], 0
	s_waitcnt lgkmcnt(5)
	v_mfma_f32_16x16x32_bf16 v[134:137], v[62:65], v[178:181], v[134:137]
	v_mfma_f32_16x16x32_bf16 v[130:133], v[70:73], v[178:181], v[130:133]
	ds_read_b128 v[178:181], v170 offset:59520
	s_waitcnt lgkmcnt(4)
	v_mfma_f32_16x16x32_bf16 v[134:137], v[58:61], v[238:241], v[134:137]
	v_mfma_f32_16x16x32_bf16 v[130:133], v[66:69], v[238:241], v[130:133]
	ds_read_b128 v[238:241], v170 offset:59584
	s_waitcnt lgkmcnt(4)
	v_mfma_f32_16x16x32_bf16 v[134:137], v[46:49], v[242:245], v[134:137]
	v_mfma_f32_16x16x32_bf16 v[130:133], v[54:57], v[242:245], v[130:133]
	s_waitcnt lgkmcnt(3)
	v_mfma_f32_16x16x32_bf16 v[134:137], v[42:45], v[246:249], v[134:137]
	v_mfma_f32_16x16x32_bf16 v[130:133], v[50:53], v[246:249], v[130:133]
	s_waitcnt lgkmcnt(2)
	v_mfma_f32_16x16x32_bf16 v[134:137], v[30:33], v[228:231], v[134:137]
	v_mfma_f32_16x16x32_bf16 v[130:133], v[38:41], v[228:231], v[130:133]
	s_waitcnt lgkmcnt(1)
	v_mfma_f32_16x16x32_bf16 v[134:137], v[26:29], v[178:181], v[134:137]
	v_mfma_f32_16x16x32_bf16 v[130:133], v[34:37], v[178:181], v[130:133]
	s_waitcnt lgkmcnt(0)
	v_mfma_f32_16x16x32_bf16 v[134:137], v[10:13], v[238:241], v[134:137]
	v_mfma_f32_16x16x32_bf16 v[130:133], v[14:17], v[238:241], v[130:133]
	s_nop 6
	v_add_f32_e32 v101, v22, v134
	v_add_f32_e32 v134, v23, v135
	v_add_f32_e32 v135, v24, v136
	v_and_b32_e32 v136, 0xffff0000, v127
	v_add_f32_e32 v100, v25, v137
	v_mul_f32_e32 v137, 0xbfb8aa3b, v136
	v_exp_f32_e32 v137, v137
	v_mul_f32_e32 v100, v21, v100
	v_mul_f32_e32 v101, v18, v101
	v_mul_f32_e32 v134, v19, v134
	v_add_f32_e32 v137, 1.0, v137
	v_rcp_f32_e32 v137, v137
	v_lshlrev_b32_e32 v127, 16, v127
	v_mul_f32_e32 v135, v20, v135
	v_mul_f32_e32 v136, v137, v136
	v_mul_f32_e32 v100, v136, v100
	v_lshlrev_b32_e32 v136, 16, v126
	v_mul_f32_e32 v137, 0xbfb8aa3b, v136
	v_exp_f32_e32 v137, v137
	v_and_b32_e32 v126, 0xffff0000, v126
	v_add_f32_e32 v137, 1.0, v137
	v_rcp_f32_e32 v137, v137
	s_nop 0
	v_mul_f32_e32 v136, v137, v136
	v_mul_f32_e32 v101, v136, v101
	v_mul_f32_e32 v136, 0xbfb8aa3b, v126
	v_exp_f32_e32 v136, v136
	s_nop 0
	v_add_f32_e32 v136, 1.0, v136
	v_rcp_f32_e32 v136, v136
	s_nop 0
	v_mul_f32_e32 v126, v136, v126
	v_mul_f32_e32 v126, v126, v134
	v_mul_f32_e32 v134, 0xbfb8aa3b, v127
	v_exp_f32_e32 v134, v134
	v_cvt_pk_bf16_f32 v126, v101, v126
	v_add_f32_e32 v101, v6, v130
	v_add_f32_e32 v130, v7, v131
	v_add_f32_e32 v134, 1.0, v134
	v_rcp_f32_e32 v134, v134
	v_add_f32_e32 v131, v8, v132
	v_and_b32_e32 v132, 0xffff0000, v129
	v_mul_f32_e32 v101, v2, v101
	v_mul_f32_e32 v127, v134, v127
	v_mul_f32_e32 v127, v127, v135
	v_cvt_pk_bf16_f32 v127, v127, v100
	v_add_f32_e32 v100, v9, v133
	v_mul_f32_e32 v133, 0xbfb8aa3b, v132
	v_exp_f32_e32 v133, v133
	v_mul_f32_e32 v100, v5, v100
	v_mul_f32_e32 v130, v3, v130
	v_lshlrev_b32_e32 v129, 16, v129
	v_add_f32_e32 v133, 1.0, v133
	v_rcp_f32_e32 v133, v133
	v_mul_f32_e32 v131, v4, v131
	v_mul_f32_e32 v132, v133, v132
	v_mul_f32_e32 v100, v132, v100
	v_lshlrev_b32_e32 v132, 16, v128
	v_mul_f32_e32 v133, 0xbfb8aa3b, v132
	v_exp_f32_e32 v133, v133
	v_and_b32_e32 v128, 0xffff0000, v128
	v_add_f32_e32 v133, 1.0, v133
	v_rcp_f32_e32 v133, v133
	s_nop 0
	v_mul_f32_e32 v132, v133, v132
	v_mul_f32_e32 v101, v132, v101
	v_mul_f32_e32 v132, 0xbfb8aa3b, v128
	v_exp_f32_e32 v132, v132
	s_nop 0
	v_add_f32_e32 v132, 1.0, v132
	v_rcp_f32_e32 v132, v132
	s_nop 0
	v_mul_f32_e32 v128, v132, v128
	v_mul_f32_e32 v128, v128, v130
	v_mul_f32_e32 v130, 0xbfb8aa3b, v129
	v_exp_f32_e32 v130, v130
	v_cvt_pk_bf16_f32 v128, v101, v128
	s_nop 0
	v_add_f32_e32 v130, 1.0, v130
	v_rcp_f32_e32 v130, v130
	s_nop 0
	v_mul_f32_e32 v129, v130, v129
	v_mul_f32_e32 v129, v129, v131
	v_cvt_pk_bf16_f32 v129, v129, v100
	v_add_co_u32_e32 v100, vcc, s25, v98
	ds_read_b128 v[134:137], v169 offset:25408
	s_nop 0
	v_addc_co_u32_e32 v101, vcc, 0, v99, vcc
	global_store_dwordx4 v[100:101], v[126:129], off offset:2048
	ds_read_b128 v[126:129], v169 offset:25344
	ds_read_b128 v[238:241], v169 offset:25472
	ds_read_b128 v[242:245], v169 offset:25536
	ds_read_b128 v[246:249], v169 offset:25600
	ds_read_b128 v[228:231], v169 offset:25664
	s_waitcnt lgkmcnt(4)
	v_mfma_f32_16x16x32_bf16 v[130:133], v[74:77], v[126:129], 0
	v_add_co_u32_e32 v98, vcc, s14, v98
	v_mfma_f32_16x16x32_bf16 v[126:129], v[78:81], v[126:129], 0
	s_nop 0
	v_addc_co_u32_e32 v99, vcc, 0, v99, vcc
	s_waitcnt lgkmcnt(5)
	v_mfma_f32_16x16x32_bf16 v[130:133], v[62:65], v[134:137], v[130:133]
	v_mfma_f32_16x16x32_bf16 v[126:129], v[70:73], v[134:137], v[126:129]
	ds_read_b128 v[134:137], v169 offset:25728
	s_waitcnt lgkmcnt(4)
	v_mfma_f32_16x16x32_bf16 v[130:133], v[58:61], v[238:241], v[130:133]
	v_mfma_f32_16x16x32_bf16 v[126:129], v[66:69], v[238:241], v[126:129]
	ds_read_b128 v[238:241], v169 offset:25792
	s_waitcnt lgkmcnt(4)
	v_mfma_f32_16x16x32_bf16 v[130:133], v[46:49], v[242:245], v[130:133]
	v_mfma_f32_16x16x32_bf16 v[126:129], v[54:57], v[242:245], v[126:129]
	s_waitcnt lgkmcnt(3)
	v_mfma_f32_16x16x32_bf16 v[130:133], v[42:45], v[246:249], v[130:133]
	v_mfma_f32_16x16x32_bf16 v[126:129], v[50:53], v[246:249], v[126:129]
	s_waitcnt lgkmcnt(2)
	v_mfma_f32_16x16x32_bf16 v[130:133], v[30:33], v[228:231], v[130:133]
	v_mfma_f32_16x16x32_bf16 v[126:129], v[38:41], v[228:231], v[126:129]
	s_waitcnt lgkmcnt(1)
	v_mfma_f32_16x16x32_bf16 v[130:133], v[26:29], v[134:137], v[130:133]
	v_mfma_f32_16x16x32_bf16 v[126:129], v[34:37], v[134:137], v[126:129]
	s_waitcnt lgkmcnt(0)
	v_mfma_f32_16x16x32_bf16 v[130:133], v[10:13], v[238:241], v[130:133]
	v_mfma_f32_16x16x32_bf16 v[126:129], v[14:17], v[238:241], v[126:129]
	s_nop 6
	v_add_f32_e32 v101, v22, v130
	v_add_f32_e32 v130, v23, v131
	v_add_f32_e32 v131, v24, v132
	v_and_b32_e32 v132, 0xffff0000, v103
	v_add_f32_e32 v100, v25, v133
	v_mul_f32_e32 v133, 0xbfb8aa3b, v132
	v_exp_f32_e32 v133, v133
	v_mul_f32_e32 v100, v21, v100
	v_mul_f32_e32 v101, v18, v101
	v_mul_f32_e32 v131, v20, v131
	v_add_f32_e32 v133, 1.0, v133
	v_rcp_f32_e32 v133, v133
	v_mul_f32_e32 v130, v19, v130
	v_mul_f32_e32 v132, v133, v132
	v_mul_f32_e32 v132, v132, v100
	v_lshlrev_b32_e32 v100, 16, v102
	v_mul_f32_e32 v133, 0xbfb8aa3b, v100
	v_exp_f32_e32 v133, v133
	s_nop 0
	v_add_f32_e32 v133, 1.0, v133
	v_rcp_f32_e32 v133, v133
	s_nop 0
	v_mul_f32_e32 v100, v133, v100
	v_mul_f32_e32 v100, v100, v101
	v_and_b32_e32 v101, 0xffff0000, v102
	v_mul_f32_e32 v102, 0xbfb8aa3b, v101
	v_exp_f32_e32 v102, v102
	s_nop 0
	v_add_f32_e32 v102, 1.0, v102
	v_rcp_f32_e32 v102, v102
	s_nop 0
	v_mul_f32_e32 v101, v102, v101
	v_lshlrev_b32_e32 v102, 16, v103
	v_mul_f32_e32 v103, 0xbfb8aa3b, v102
	v_exp_f32_e32 v103, v103
	v_mul_f32_e32 v101, v101, v130
	v_cvt_pk_bf16_f32 v100, v100, v101
	v_add_f32_e32 v103, 1.0, v103
	v_rcp_f32_e32 v103, v103
	s_nop 0
	v_mul_f32_e32 v102, v103, v102
	v_mul_f32_e32 v102, v102, v131
	v_add_f32_e32 v103, v6, v126
	v_add_f32_e32 v126, v7, v127
	v_add_f32_e32 v127, v8, v128
	v_and_b32_e32 v128, 0xffff0000, v105
	v_cvt_pk_bf16_f32 v101, v102, v132
	v_add_f32_e32 v102, v9, v129
	v_mul_f32_e32 v129, 0xbfb8aa3b, v128
	v_exp_f32_e32 v129, v129
	v_mul_f32_e32 v102, v5, v102
	v_mul_f32_e32 v103, v2, v103
	v_mul_f32_e32 v126, v3, v126
	v_add_f32_e32 v129, 1.0, v129
	v_rcp_f32_e32 v129, v129
	v_mul_f32_e32 v127, v4, v127
	v_mul_f32_e32 v128, v129, v128
	v_mul_f32_e32 v128, v128, v102
	v_lshlrev_b32_e32 v102, 16, v104
	v_mul_f32_e32 v129, 0xbfb8aa3b, v102
	v_exp_f32_e32 v129, v129
	s_nop 0
	v_add_f32_e32 v129, 1.0, v129
	v_rcp_f32_e32 v129, v129
	s_nop 0
	v_mul_f32_e32 v102, v129, v102
	v_mul_f32_e32 v102, v102, v103
	v_and_b32_e32 v103, 0xffff0000, v104
	v_mul_f32_e32 v104, 0xbfb8aa3b, v103
	v_exp_f32_e32 v104, v104
	s_nop 0
	v_add_f32_e32 v104, 1.0, v104
	v_rcp_f32_e32 v104, v104
	s_nop 0
	v_mul_f32_e32 v103, v104, v103
	v_lshlrev_b32_e32 v104, 16, v105
	v_mul_f32_e32 v105, 0xbfb8aa3b, v104
	v_exp_f32_e32 v105, v105
	v_mul_f32_e32 v103, v103, v126
	v_cvt_pk_bf16_f32 v102, v102, v103
	v_add_f32_e32 v105, 1.0, v105
	v_rcp_f32_e32 v105, v105
	s_nop 0
	v_mul_f32_e32 v104, v105, v104
	v_mul_f32_e32 v104, v104, v127
	v_cvt_pk_bf16_f32 v103, v104, v128
	global_store_dwordx4 v[98:99], v[100:103], off offset:2048
	s_waitcnt vmcnt(11)
	ds_write_b128 v164, v[106:109] offset:8448
	s_waitcnt vmcnt(10)
	ds_write_b128 v165, v[110:113] offset:8448
	s_waitcnt vmcnt(9)
	ds_write_b128 v166, v[114:117] offset:8448
	s_waitcnt vmcnt(8)
	ds_write_b128 v167, v[118:121] offset:8448
	ds_write_b128 v168, v[122:125]
	s_waitcnt vmcnt(7)
	v_mov_b64_e32 v[100:101], v[96:97]
	v_mov_b64_e32 v[98:99], v[94:95]
	s_cbranch_scc1 .LBB0_138
	s_add_u32 s0, s90, s0
	s_addc_u32 s1, s91, s1
	v_readlane_b32 s6, v253, 40
	s_or_b32 s2, s15, 0x1c0
	v_mov_b32_e32 v141, v1
	v_readlane_b32 s7, v253, 41
	v_add_u32_e32 v124, s2, v172
	v_add_u32_e32 v102, s2, v174
	v_add_u32_e32 v106, s2, v175
	v_add_u32_e32 v112, s2, v173
	v_lshl_add_u64 v[98:99], s[6:7], 0, v[140:141]
	v_lshl_add_u64 v[100:101], v[138:139], 1, s[0:1]
	s_lshl_b64 s[0:1], s[42:43], 11
	v_ashrrev_i32_e32 v125, 31, v124
	v_ashrrev_i32_e32 v103, 31, v102
	v_ashrrev_i32_e32 v107, 31, v106
	v_ashrrev_i32_e32 v113, 31, v112
	v_lshl_add_u64 v[110:111], v[98:99], 0, s[0:1]
	v_lshlrev_b64 v[98:99], 11, v[124:125]
	v_lshlrev_b64 v[102:103], 11, v[102:103]
	v_lshlrev_b64 v[106:107], 11, v[106:107]
	v_lshlrev_b64 v[112:113], 11, v[112:113]
	v_mov_b32_e32 v143, v1
	s_waitcnt lgkmcnt(0)
	s_barrier
	v_lshl_add_u64 v[98:99], v[110:111], 0, v[98:99]
	v_lshl_add_u64 v[102:103], v[110:111], 0, v[102:103]
	v_lshl_add_u64 v[106:107], v[110:111], 0, v[106:107]
	v_lshl_add_u64 v[110:111], v[110:111], 0, v[112:113]
	v_lshl_add_u64 v[118:119], v[100:101], 0, v[142:143]
	global_load_dwordx4 v[98:101], v[98:99], off
	s_nop 0
	global_load_dwordx4 v[102:105], v[102:103], off
	s_nop 0
	global_load_dwordx4 v[106:109], v[106:107], off
	s_nop 0
	global_load_dwordx4 v[110:113], v[110:111], off
	ds_read_b128 v[114:117], v168 offset:33792
	ds_read_b128 v[120:123], v0 offset:7920
	s_waitcnt lgkmcnt(0)
	v_lshlrev_b32_e32 v125, 16, v120
	v_and_b32_e32 v120, 0xffff0000, v120
	v_add_f32_e32 v127, 0, v120
	v_lshlrev_b32_e32 v120, 16, v121
	v_add_f32_e32 v128, 0, v120
	v_and_b32_e32 v120, 0xffff0000, v121
	v_add_f32_e32 v129, 0, v120
	v_lshlrev_b32_e32 v120, 16, v122
	v_add_f32_e32 v130, 0, v120
	v_and_b32_e32 v120, 0xffff0000, v122
	v_add_f32_e32 v131, 0, v120
	v_lshlrev_b32_e32 v120, 16, v123
	v_add_f32_e32 v132, 0, v120
	v_and_b32_e32 v120, 0xffff0000, v123
	v_add_f32_e32 v133, 0, v120
	v_mad_u64_u32 v[120:121], s[0:1], v172, 3, v[124:125]
	v_min_i32_e32 v137, 1, v120
	v_add_u32_e32 v137, 1, v137
	v_cvt_f32_i32_e32 v137, v137
	v_add_f32_e32 v126, 0, v125
	ds_read_b128 v[122:125], v176 offset:8448
	s_lshl_b32 s0, s20, 19
	v_rcp_iflag_f32_e32 v137, v137
	s_and_b32 s0, s0, 0xe00000
	s_waitcnt lgkmcnt(0)
	v_lshlrev_b32_e32 v121, 16, v122
	v_and_b32_e32 v122, 0xffff0000, v122
	v_lshlrev_b32_e32 v134, 16, v123
	v_and_b32_e32 v123, 0xffff0000, v123
	v_lshlrev_b32_e32 v135, 16, v124
	v_and_b32_e32 v124, 0xffff0000, v124
	v_lshlrev_b32_e32 v136, 16, v125
	v_and_b32_e32 v125, 0xffff0000, v125
	v_add_f32_e32 v127, v127, v122
	v_add_f32_e32 v129, v129, v123
	v_add_f32_e32 v131, v131, v124
	v_add_f32_e32 v133, v133, v125
	v_add_f32_e32 v126, v126, v121
	v_fma_f32 v122, v127, v137, -v122
	v_add_f32_e32 v128, v128, v134
	v_fma_f32 v123, v129, v137, -v123
	v_add_f32_e32 v130, v130, v135
	v_fma_f32 v124, v131, v137, -v124
	v_add_f32_e32 v132, v132, v136
	v_fma_f32 v125, v133, v137, -v125
	v_fma_f32 v121, v126, v137, -v121
	v_fma_f32 v134, v128, v137, -v134
	v_fma_f32 v135, v130, v137, -v135
	v_fma_f32 v136, v132, v137, -v136
	v_cvt_pk_bf16_f32 v122, v121, v122
	v_cvt_pk_bf16_f32 v123, v134, v123
	v_cvt_pk_bf16_f32 v124, v135, v124
	v_cvt_pk_bf16_f32 v125, v136, v125
	ds_write_b128 v0, v[122:125] offset:42240
	ds_read_b128 v[122:125], v176 offset:7920
	v_or_b32_e32 v137, 1, v120
	v_min_i32_e32 v137, 1, v137
	v_add_u32_e32 v137, 1, v137
	v_cvt_f32_i32_e32 v137, v137
	s_waitcnt lgkmcnt(0)
	v_lshlrev_b32_e32 v121, 16, v122
	v_and_b32_e32 v122, 0xffff0000, v122
	v_sub_f32_e32 v121, v126, v121
	v_sub_f32_e32 v126, v127, v122
	v_lshlrev_b32_e32 v122, 16, v123
	v_sub_f32_e32 v127, v128, v122
	v_and_b32_e32 v122, 0xffff0000, v123
	v_sub_f32_e32 v128, v129, v122
	v_lshlrev_b32_e32 v122, 16, v124
	v_sub_f32_e32 v129, v130, v122
	v_and_b32_e32 v122, 0xffff0000, v124
	v_sub_f32_e32 v130, v131, v122
	v_lshlrev_b32_e32 v122, 16, v125
	v_sub_f32_e32 v131, v132, v122
	v_and_b32_e32 v122, 0xffff0000, v125
	v_sub_f32_e32 v132, v133, v122
	ds_read_b128 v[122:125], v176 offset:8976
	v_rcp_iflag_f32_e32 v137, v137
	s_waitcnt lgkmcnt(0)
	v_lshlrev_b32_e32 v133, 16, v122
	v_and_b32_e32 v122, 0xffff0000, v122
	v_lshlrev_b32_e32 v134, 16, v123
	v_and_b32_e32 v123, 0xffff0000, v123
	v_lshlrev_b32_e32 v135, 16, v124
	v_and_b32_e32 v124, 0xffff0000, v124
	v_lshlrev_b32_e32 v136, 16, v125
	v_and_b32_e32 v125, 0xffff0000, v125
	v_add_f32_e32 v126, v126, v122
	v_add_f32_e32 v128, v128, v123
	v_add_f32_e32 v130, v130, v124
	v_add_f32_e32 v132, v132, v125
	v_add_f32_e32 v121, v121, v133
	v_fma_f32 v122, v126, v137, -v122
	v_add_f32_e32 v127, v127, v134
	v_fma_f32 v123, v128, v137, -v123
	v_add_f32_e32 v129, v129, v135
	v_fma_f32 v124, v130, v137, -v124
	v_add_f32_e32 v131, v131, v136
	v_fma_f32 v125, v132, v137, -v125
	v_fma_f32 v133, v121, v137, -v133
	v_fma_f32 v134, v127, v137, -v134
	v_fma_f32 v135, v129, v137, -v135
	v_fma_f32 v136, v131, v137, -v136
	v_cvt_pk_bf16_f32 v122, v133, v122
	v_cvt_pk_bf16_f32 v123, v134, v123
	v_cvt_pk_bf16_f32 v124, v135, v124
	v_cvt_pk_bf16_f32 v125, v136, v125
	ds_write_b128 v0, v[122:125] offset:42768
	ds_read_b128 v[122:125], v176 offset:8448
	v_or_b32_e32 v137, 2, v120
	v_min_i32_e32 v137, 1, v137
	v_add_u32_e32 v137, 1, v137
	v_cvt_f32_i32_e32 v137, v137
	s_waitcnt lgkmcnt(0)
	v_lshlrev_b32_e32 v133, 16, v122
	v_and_b32_e32 v122, 0xffff0000, v122
	v_sub_f32_e32 v126, v126, v122
	v_lshlrev_b32_e32 v122, 16, v123
	v_sub_f32_e32 v127, v127, v122
	v_and_b32_e32 v122, 0xffff0000, v123
	v_sub_f32_e32 v128, v128, v122
	v_lshlrev_b32_e32 v122, 16, v124
	v_sub_f32_e32 v129, v129, v122
	v_and_b32_e32 v122, 0xffff0000, v124
	v_sub_f32_e32 v130, v130, v122
	v_lshlrev_b32_e32 v122, 16, v125
	v_sub_f32_e32 v131, v131, v122
	v_and_b32_e32 v122, 0xffff0000, v125
	v_sub_f32_e32 v132, v132, v122
	ds_read_b128 v[122:125], v176 offset:9504
	v_rcp_iflag_f32_e32 v137, v137
	v_sub_f32_e32 v121, v121, v133
	v_or_b32_e32 v120, 3, v120
	v_min_i32_e32 v120, 1, v120
	s_waitcnt lgkmcnt(0)
	v_lshlrev_b32_e32 v133, 16, v122
	v_and_b32_e32 v122, 0xffff0000, v122
	v_lshlrev_b32_e32 v134, 16, v123
	v_and_b32_e32 v123, 0xffff0000, v123
	v_lshlrev_b32_e32 v135, 16, v124
	v_and_b32_e32 v124, 0xffff0000, v124
	v_lshlrev_b32_e32 v136, 16, v125
	v_and_b32_e32 v125, 0xffff0000, v125
	v_add_f32_e32 v126, v126, v122
	v_add_f32_e32 v128, v128, v123
	v_add_f32_e32 v130, v130, v124
	v_add_f32_e32 v132, v132, v125
	v_add_f32_e32 v121, v121, v133
	v_fma_f32 v122, v126, v137, -v122
	v_add_f32_e32 v127, v127, v134
	v_fma_f32 v123, v128, v137, -v123
	v_add_f32_e32 v129, v129, v135
	v_fma_f32 v124, v130, v137, -v124
	v_add_f32_e32 v131, v131, v136
	v_fma_f32 v125, v132, v137, -v125
	v_fma_f32 v133, v121, v137, -v133
	v_fma_f32 v134, v127, v137, -v134
	v_fma_f32 v135, v129, v137, -v135
	v_fma_f32 v136, v131, v137, -v136
	v_cvt_pk_bf16_f32 v122, v133, v122
	v_cvt_pk_bf16_f32 v123, v134, v123
	v_cvt_pk_bf16_f32 v124, v135, v124
	v_cvt_pk_bf16_f32 v125, v136, v125
	ds_write_b128 v0, v[122:125] offset:43296
	ds_read_b128 v[122:125], v176 offset:8976
	v_add_u32_e32 v120, 1, v120
	v_cvt_f32_i32_e32 v120, v120
	s_waitcnt lgkmcnt(0)
	v_lshlrev_b32_e32 v133, 16, v122
	v_and_b32_e32 v122, 0xffff0000, v122
	v_sub_f32_e32 v126, v126, v122
	v_lshlrev_b32_e32 v122, 16, v123
	v_sub_f32_e32 v127, v127, v122
	v_and_b32_e32 v122, 0xffff0000, v123
	v_sub_f32_e32 v128, v128, v122
	v_lshlrev_b32_e32 v122, 16, v124
	v_sub_f32_e32 v129, v129, v122
	v_and_b32_e32 v122, 0xffff0000, v124
	v_sub_f32_e32 v130, v130, v122
	v_lshlrev_b32_e32 v122, 16, v125
	v_sub_f32_e32 v131, v131, v122
	v_and_b32_e32 v122, 0xffff0000, v125
	v_sub_f32_e32 v132, v132, v122
	ds_read_b128 v[122:125], v176 offset:10032
	v_rcp_iflag_f32_e32 v120, v120
	v_sub_f32_e32 v121, v121, v133
	s_waitcnt lgkmcnt(0)
	v_lshlrev_b32_e32 v133, 16, v122
	v_and_b32_e32 v122, 0xffff0000, v122
	v_lshlrev_b32_e32 v134, 16, v123
	v_and_b32_e32 v123, 0xffff0000, v123
	v_lshlrev_b32_e32 v135, 16, v124
	v_and_b32_e32 v124, 0xffff0000, v124
	v_add_f32_e32 v126, v126, v122
	v_lshlrev_b32_e32 v136, 16, v125
	v_and_b32_e32 v125, 0xffff0000, v125
	v_add_f32_e32 v121, v121, v133
	v_fma_f32 v122, v126, v120, -v122
	v_add_f32_e32 v126, v127, v134
	v_add_f32_e32 v127, v128, v123
	v_add_f32_e32 v128, v130, v124
	v_fma_f32 v121, v121, v120, -v133
	v_fma_f32 v123, v127, v120, -v123
	v_add_f32_e32 v127, v129, v135
	v_fma_f32 v124, v128, v120, -v124
	v_add_f32_e32 v128, v131, v136
	v_add_f32_e32 v129, v132, v125
	v_fma_f32 v126, v126, v120, -v134
	v_fma_f32 v127, v127, v120, -v135
	v_fma_f32 v128, v128, v120, -v136
	v_fma_f32 v125, v129, v120, -v125
	v_cvt_pk_bf16_f32 v120, v121, v122
	v_cvt_pk_bf16_f32 v121, v126, v123
	v_cvt_pk_bf16_f32 v122, v127, v124
	v_cvt_pk_bf16_f32 v123, v128, v125
	ds_write_b128 v0, v[120:123] offset:43824
	s_waitcnt lgkmcnt(0)
	s_barrier
	ds_read_b128 v[120:123], v170 offset:42240
	ds_read_b128 v[128:131], v170 offset:42304
	s_waitcnt lgkmcnt(1)
	v_mfma_f32_16x16x32_bf16 v[124:127], v[74:77], v[120:123], 0
	v_mfma_f32_16x16x32_bf16 v[120:123], v[78:81], v[120:123], 0
	s_waitcnt lgkmcnt(0)
	v_mfma_f32_16x16x32_bf16 v[124:127], v[62:65], v[128:131], v[124:127]
	v_mfma_f32_16x16x32_bf16 v[120:123], v[70:73], v[128:131], v[120:123]
	ds_read_b128 v[128:131], v170 offset:42368
	s_waitcnt lgkmcnt(0)
	v_mfma_f32_16x16x32_bf16 v[124:127], v[58:61], v[128:131], v[124:127]
	v_mfma_f32_16x16x32_bf16 v[120:123], v[66:69], v[128:131], v[120:123]
	ds_read_b128 v[128:131], v170 offset:42432
	s_waitcnt lgkmcnt(0)
	v_mfma_f32_16x16x32_bf16 v[124:127], v[46:49], v[128:131], v[124:127]
	v_mfma_f32_16x16x32_bf16 v[120:123], v[54:57], v[128:131], v[120:123]
	ds_read_b128 v[128:131], v170 offset:42496
	s_waitcnt lgkmcnt(0)
	v_mfma_f32_16x16x32_bf16 v[124:127], v[42:45], v[128:131], v[124:127]
	v_mfma_f32_16x16x32_bf16 v[120:123], v[50:53], v[128:131], v[120:123]
	ds_read_b128 v[128:131], v170 offset:42560
	s_waitcnt lgkmcnt(0)
	v_mfma_f32_16x16x32_bf16 v[124:127], v[30:33], v[128:131], v[124:127]
	v_mfma_f32_16x16x32_bf16 v[120:123], v[38:41], v[128:131], v[120:123]
	ds_read_b128 v[128:131], v170 offset:42624
	s_waitcnt lgkmcnt(0)
	v_mfma_f32_16x16x32_bf16 v[124:127], v[26:29], v[128:131], v[124:127]
	v_mfma_f32_16x16x32_bf16 v[120:123], v[34:37], v[128:131], v[120:123]
	ds_read_b128 v[128:131], v170 offset:42688
	s_waitcnt lgkmcnt(0)
	v_mfma_f32_16x16x32_bf16 v[124:127], v[10:13], v[128:131], v[124:127]
	v_mfma_f32_16x16x32_bf16 v[120:123], v[14:17], v[128:131], v[120:123]
	s_nop 6
	v_add_f32_e32 v0, v25, v127
	v_and_b32_e32 v127, 0xffff0000, v95
	v_mul_f32_e32 v128, 0xbfb8aa3b, v127
	v_exp_f32_e32 v128, v128
	v_mul_f32_e32 v0, v21, v0
	v_add_f32_e32 v124, v22, v124
	v_mul_f32_e32 v124, v18, v124
	v_add_f32_e32 v128, 1.0, v128
	v_rcp_f32_e32 v128, v128
	v_add_f32_e32 v125, v23, v125
	v_mul_f32_e32 v125, v19, v125
	v_lshlrev_b32_e32 v95, 16, v95
	v_mul_f32_e32 v127, v128, v127
	v_mul_f32_e32 v0, v127, v0
	v_lshlrev_b32_e32 v127, 16, v94
	v_mul_f32_e32 v128, 0xbfb8aa3b, v127
	v_exp_f32_e32 v128, v128
	v_and_b32_e32 v94, 0xffff0000, v94
	v_add_f32_e32 v126, v24, v126
	v_mul_f32_e32 v126, v20, v126
	v_add_f32_e32 v128, 1.0, v128
	v_rcp_f32_e32 v128, v128
	s_nop 0
	v_mul_f32_e32 v127, v128, v127
	v_mul_f32_e32 v124, v127, v124
	v_mul_f32_e32 v127, 0xbfb8aa3b, v94
	v_exp_f32_e32 v127, v127
	s_nop 0
	v_add_f32_e32 v127, 1.0, v127
	v_rcp_f32_e32 v127, v127
	s_nop 0
	v_mul_f32_e32 v94, v127, v94
	v_mul_f32_e32 v94, v94, v125
	v_mul_f32_e32 v125, 0xbfb8aa3b, v95
	v_exp_f32_e32 v125, v125
	v_cvt_pk_bf16_f32 v124, v124, v94
	v_add_f32_e32 v94, v6, v120
	v_add_f32_e32 v120, v8, v122
	v_add_f32_e32 v125, 1.0, v125
	v_rcp_f32_e32 v125, v125
	v_mul_f32_e32 v94, v2, v94
	v_mul_f32_e32 v120, v4, v120
	v_mul_f32_e32 v95, v125, v95
	v_mul_f32_e32 v95, v95, v126
	v_cvt_pk_bf16_f32 v125, v95, v0
	v_add_f32_e32 v95, v7, v121
	v_and_b32_e32 v121, 0xffff0000, v97
	v_mul_f32_e32 v122, 0xbfb8aa3b, v121
	v_exp_f32_e32 v122, v122
	v_add_f32_e32 v0, v9, v123
	v_mul_f32_e32 v0, v5, v0
	v_mul_f32_e32 v95, v3, v95
	v_add_f32_e32 v122, 1.0, v122
	v_rcp_f32_e32 v122, v122
	s_nop 0
	v_mul_f32_e32 v121, v122, v121
	v_mul_f32_e32 v0, v121, v0
	v_lshlrev_b32_e32 v121, 16, v96
	v_mul_f32_e32 v122, 0xbfb8aa3b, v121
	v_exp_f32_e32 v122, v122
	v_and_b32_e32 v96, 0xffff0000, v96
	v_add_f32_e32 v122, 1.0, v122
	v_rcp_f32_e32 v122, v122
	s_nop 0
	v_mul_f32_e32 v121, v122, v121
	v_mul_f32_e32 v94, v121, v94
	v_mul_f32_e32 v121, 0xbfb8aa3b, v96
	v_exp_f32_e32 v121, v121
	s_nop 0
	v_add_f32_e32 v121, 1.0, v121
	v_rcp_f32_e32 v121, v121
	s_nop 0
	v_mul_f32_e32 v96, v121, v96
	v_mul_f32_e32 v95, v96, v95
	v_lshlrev_b32_e32 v96, 16, v97
	v_mul_f32_e32 v97, 0xbfb8aa3b, v96
	v_exp_f32_e32 v97, v97
	v_cvt_pk_bf16_f32 v126, v94, v95
	s_nop 0
	v_add_f32_e32 v97, 1.0, v97
	v_rcp_f32_e32 v97, v97
	s_nop 0
	v_mul_f32_e32 v96, v97, v96
	v_mul_f32_e32 v96, v96, v120
	v_cvt_pk_bf16_f32 v127, v96, v0
	v_lshl_or_b32 v0, v171, 12, s0
	v_or_b32_e32 v0, 0x1c0000, v0
	v_lshl_add_u64 v[94:95], v[118:119], 0, v[0:1]
	ds_read_b128 v[118:121], v170 offset:50688
	v_add_co_u32_e32 v96, vcc, s9, v94
	s_mov_b64 s[0:1], 0
	s_nop 0
	v_addc_co_u32_e32 v97, vcc, 0, v95, vcc
	global_store_dwordx4 v[96:97], v[124:127], off offset:2048
	ds_read_b128 v[126:129], v170 offset:50752
	s_waitcnt lgkmcnt(1)
	v_mfma_f32_16x16x32_bf16 v[122:125], v[74:77], v[118:121], 0
	v_mfma_f32_16x16x32_bf16 v[118:121], v[78:81], v[118:121], 0
	s_waitcnt lgkmcnt(0)
	v_mfma_f32_16x16x32_bf16 v[122:125], v[62:65], v[126:129], v[122:125]
	v_mfma_f32_16x16x32_bf16 v[118:121], v[70:73], v[126:129], v[118:121]
	ds_read_b128 v[126:129], v170 offset:50816
	s_waitcnt lgkmcnt(0)
	v_mfma_f32_16x16x32_bf16 v[122:125], v[58:61], v[126:129], v[122:125]
	v_mfma_f32_16x16x32_bf16 v[118:121], v[66:69], v[126:129], v[118:121]
	ds_read_b128 v[126:129], v170 offset:50880
	s_waitcnt lgkmcnt(0)
	v_mfma_f32_16x16x32_bf16 v[122:125], v[46:49], v[126:129], v[122:125]
	v_mfma_f32_16x16x32_bf16 v[118:121], v[54:57], v[126:129], v[118:121]
	ds_read_b128 v[126:129], v170 offset:50944
	s_waitcnt lgkmcnt(0)
	v_mfma_f32_16x16x32_bf16 v[122:125], v[42:45], v[126:129], v[122:125]
	v_mfma_f32_16x16x32_bf16 v[118:121], v[50:53], v[126:129], v[118:121]
	ds_read_b128 v[126:129], v170 offset:51008
	s_waitcnt lgkmcnt(0)
	v_mfma_f32_16x16x32_bf16 v[122:125], v[30:33], v[126:129], v[122:125]
	v_mfma_f32_16x16x32_bf16 v[118:121], v[38:41], v[126:129], v[118:121]
	ds_read_b128 v[126:129], v170 offset:51072
	s_waitcnt lgkmcnt(0)
	v_mfma_f32_16x16x32_bf16 v[122:125], v[26:29], v[126:129], v[122:125]
	v_mfma_f32_16x16x32_bf16 v[118:121], v[34:37], v[126:129], v[118:121]
	ds_read_b128 v[126:129], v170 offset:51136
	s_waitcnt lgkmcnt(0)
	v_mfma_f32_16x16x32_bf16 v[122:125], v[10:13], v[126:129], v[122:125]
	v_mfma_f32_16x16x32_bf16 v[118:121], v[14:17], v[126:129], v[118:121]
	s_nop 6
	v_add_f32_e32 v97, v23, v123
	s_waitcnt vmcnt(11)
	v_and_b32_e32 v123, 0xffff0000, v91
	v_add_f32_e32 v96, v22, v122
	v_add_f32_e32 v122, v24, v124
	v_mul_f32_e32 v124, 0xbfb8aa3b, v123
	v_exp_f32_e32 v124, v124
	v_add_f32_e32 v0, v25, v125
	v_mul_f32_e32 v0, v21, v0
	v_mul_f32_e32 v96, v18, v96
	v_add_f32_e32 v124, 1.0, v124
	v_rcp_f32_e32 v124, v124
	v_mul_f32_e32 v97, v19, v97
	v_lshlrev_b32_e32 v91, 16, v91
	v_mul_f32_e32 v122, v20, v122
	v_mul_f32_e32 v123, v124, v123
	v_mul_f32_e32 v0, v123, v0
	v_lshlrev_b32_e32 v123, 16, v90
	v_mul_f32_e32 v124, 0xbfb8aa3b, v123
	v_exp_f32_e32 v124, v124
	v_and_b32_e32 v90, 0xffff0000, v90
	v_add_f32_e32 v124, 1.0, v124
	v_rcp_f32_e32 v124, v124
	s_nop 0
	v_mul_f32_e32 v123, v124, v123
	v_mul_f32_e32 v96, v123, v96
	v_mul_f32_e32 v123, 0xbfb8aa3b, v90
	v_exp_f32_e32 v123, v123
	s_nop 0
	v_add_f32_e32 v123, 1.0, v123
	v_rcp_f32_e32 v123, v123
	s_nop 0
	v_mul_f32_e32 v90, v123, v90
	v_mul_f32_e32 v90, v90, v97
	v_mul_f32_e32 v97, 0xbfb8aa3b, v91
	v_exp_f32_e32 v97, v97
	v_cvt_pk_bf16_f32 v90, v96, v90
	v_add_f32_e32 v96, v6, v118
	v_add_f32_e32 v118, v8, v120
	v_add_f32_e32 v97, 1.0, v97
	v_rcp_f32_e32 v97, v97
	v_mul_f32_e32 v96, v2, v96
	v_mul_f32_e32 v118, v4, v118
	v_mul_f32_e32 v91, v97, v91
	v_add_f32_e32 v97, v7, v119
	v_and_b32_e32 v119, 0xffff0000, v93
	v_mul_f32_e32 v120, 0xbfb8aa3b, v119
	v_exp_f32_e32 v120, v120
	v_mul_f32_e32 v91, v91, v122
	v_cvt_pk_bf16_f32 v91, v91, v0
	v_add_f32_e32 v0, v9, v121
	v_add_f32_e32 v120, 1.0, v120
	v_rcp_f32_e32 v120, v120
	v_mul_f32_e32 v0, v5, v0
	v_mul_f32_e32 v97, v3, v97
	v_lshlrev_b32_e32 v93, 16, v93
	v_mul_f32_e32 v119, v120, v119
	v_mul_f32_e32 v0, v119, v0
	v_lshlrev_b32_e32 v119, 16, v92
	v_mul_f32_e32 v120, 0xbfb8aa3b, v119
	v_exp_f32_e32 v120, v120
	v_and_b32_e32 v92, 0xffff0000, v92
	v_add_f32_e32 v120, 1.0, v120
	v_rcp_f32_e32 v120, v120
	s_nop 0
	v_mul_f32_e32 v119, v120, v119
	v_mul_f32_e32 v96, v119, v96
	v_mul_f32_e32 v119, 0xbfb8aa3b, v92
	v_exp_f32_e32 v119, v119
	s_nop 0
	v_add_f32_e32 v119, 1.0, v119
	v_rcp_f32_e32 v119, v119
	s_nop 0
	v_mul_f32_e32 v92, v119, v92
	v_mul_f32_e32 v92, v92, v97
	v_mul_f32_e32 v97, 0xbfb8aa3b, v93
	v_exp_f32_e32 v97, v97
	v_cvt_pk_bf16_f32 v92, v96, v92
	v_add_co_u32_e32 v96, vcc, s24, v94
	v_add_f32_e32 v97, 1.0, v97
	v_rcp_f32_e32 v97, v97
	s_nop 0
	v_mul_f32_e32 v93, v97, v93
	v_mul_f32_e32 v93, v93, v118
	v_cvt_pk_bf16_f32 v93, v93, v0
	v_addc_co_u32_e32 v97, vcc, 0, v95, vcc
	global_store_dwordx4 v[96:97], v[90:93], off offset:2048
	ds_read_b128 v[90:93], v170 offset:59136
	ds_read_b128 v[122:125], v170 offset:59200
	s_waitcnt lgkmcnt(1)
	v_mfma_f32_16x16x32_bf16 v[118:121], v[74:77], v[90:93], 0
	v_mfma_f32_16x16x32_bf16 v[90:93], v[78:81], v[90:93], 0
	s_waitcnt lgkmcnt(0)
	v_mfma_f32_16x16x32_bf16 v[118:121], v[62:65], v[122:125], v[118:121]
	v_mfma_f32_16x16x32_bf16 v[90:93], v[70:73], v[122:125], v[90:93]
	ds_read_b128 v[122:125], v170 offset:59264
	s_waitcnt lgkmcnt(0)
	v_mfma_f32_16x16x32_bf16 v[118:121], v[58:61], v[122:125], v[118:121]
	v_mfma_f32_16x16x32_bf16 v[90:93], v[66:69], v[122:125], v[90:93]
	ds_read_b128 v[122:125], v170 offset:59328
	s_waitcnt lgkmcnt(0)
	v_mfma_f32_16x16x32_bf16 v[118:121], v[46:49], v[122:125], v[118:121]
	v_mfma_f32_16x16x32_bf16 v[90:93], v[54:57], v[122:125], v[90:93]
	ds_read_b128 v[122:125], v170 offset:59392
	s_waitcnt lgkmcnt(0)
	v_mfma_f32_16x16x32_bf16 v[118:121], v[42:45], v[122:125], v[118:121]
	v_mfma_f32_16x16x32_bf16 v[90:93], v[50:53], v[122:125], v[90:93]
	ds_read_b128 v[122:125], v170 offset:59456
	s_waitcnt lgkmcnt(0)
	v_mfma_f32_16x16x32_bf16 v[118:121], v[30:33], v[122:125], v[118:121]
	v_mfma_f32_16x16x32_bf16 v[90:93], v[38:41], v[122:125], v[90:93]
	ds_read_b128 v[122:125], v170 offset:59520
	s_waitcnt lgkmcnt(0)
	v_mfma_f32_16x16x32_bf16 v[118:121], v[26:29], v[122:125], v[118:121]
	v_mfma_f32_16x16x32_bf16 v[90:93], v[34:37], v[122:125], v[90:93]
	ds_read_b128 v[122:125], v170 offset:59584
	s_waitcnt lgkmcnt(0)
	v_mfma_f32_16x16x32_bf16 v[118:121], v[10:13], v[122:125], v[118:121]
	v_mfma_f32_16x16x32_bf16 v[90:93], v[14:17], v[122:125], v[90:93]
	s_nop 6
	v_add_f32_e32 v97, v23, v119
	s_waitcnt vmcnt(11)
	v_and_b32_e32 v119, 0xffff0000, v87
	v_add_f32_e32 v96, v22, v118
	v_add_f32_e32 v118, v24, v120
	v_mul_f32_e32 v120, 0xbfb8aa3b, v119
	v_exp_f32_e32 v120, v120
	v_add_f32_e32 v0, v25, v121
	v_mul_f32_e32 v0, v21, v0
	v_mul_f32_e32 v96, v18, v96
	v_add_f32_e32 v120, 1.0, v120
	v_rcp_f32_e32 v120, v120
	v_mul_f32_e32 v97, v19, v97
	v_lshlrev_b32_e32 v87, 16, v87
	v_mul_f32_e32 v118, v20, v118
	v_mul_f32_e32 v119, v120, v119
	v_mul_f32_e32 v0, v119, v0
	v_lshlrev_b32_e32 v119, 16, v86
	v_mul_f32_e32 v120, 0xbfb8aa3b, v119
	v_exp_f32_e32 v120, v120
	v_and_b32_e32 v86, 0xffff0000, v86
	v_add_f32_e32 v90, v6, v90
	v_mul_f32_e32 v90, v2, v90
	v_add_f32_e32 v120, 1.0, v120
	v_rcp_f32_e32 v120, v120
	v_add_f32_e32 v91, v7, v91
	v_mul_f32_e32 v91, v3, v91
	v_add_f32_e32 v92, v8, v92
	v_mul_f32_e32 v119, v120, v119
	v_mul_f32_e32 v96, v119, v96
	v_mul_f32_e32 v119, 0xbfb8aa3b, v86
	v_exp_f32_e32 v119, v119
	v_mul_f32_e32 v92, v4, v92
	v_add_f32_e32 v119, 1.0, v119
	v_rcp_f32_e32 v119, v119
	s_nop 0
	v_mul_f32_e32 v86, v119, v86
	v_mul_f32_e32 v86, v86, v97
	v_mul_f32_e32 v97, 0xbfb8aa3b, v87
	v_exp_f32_e32 v97, v97
	v_cvt_pk_bf16_f32 v86, v96, v86
	s_nop 0
	v_add_f32_e32 v97, 1.0, v97
	v_rcp_f32_e32 v97, v97
	s_nop 0
	v_mul_f32_e32 v87, v97, v87
	v_mul_f32_e32 v87, v87, v118
	v_cvt_pk_bf16_f32 v87, v87, v0
	v_add_f32_e32 v0, v9, v93
	v_and_b32_e32 v93, 0xffff0000, v89
	v_mul_f32_e32 v96, 0xbfb8aa3b, v93
	v_exp_f32_e32 v96, v96
	v_mul_f32_e32 v0, v5, v0
	v_lshlrev_b32_e32 v89, 16, v89
	v_add_f32_e32 v96, 1.0, v96
	v_rcp_f32_e32 v96, v96
	s_nop 0
	v_mul_f32_e32 v93, v96, v93
	v_mul_f32_e32 v0, v93, v0
	v_lshlrev_b32_e32 v93, 16, v88
	v_mul_f32_e32 v96, 0xbfb8aa3b, v93
	v_exp_f32_e32 v96, v96
	v_and_b32_e32 v88, 0xffff0000, v88
	v_add_f32_e32 v96, 1.0, v96
	v_rcp_f32_e32 v96, v96
	s_nop 0
	v_mul_f32_e32 v93, v96, v93
	v_mul_f32_e32 v90, v93, v90
	v_mul_f32_e32 v93, 0xbfb8aa3b, v88
	v_exp_f32_e32 v93, v93
	s_nop 0
	v_add_f32_e32 v93, 1.0, v93
	v_rcp_f32_e32 v93, v93
	s_nop 0
	v_mul_f32_e32 v88, v93, v88
	v_mul_f32_e32 v88, v88, v91
	v_mul_f32_e32 v91, 0xbfb8aa3b, v89
	v_exp_f32_e32 v91, v91
	v_cvt_pk_bf16_f32 v88, v90, v88
	v_add_co_u32_e32 v90, vcc, s25, v94
	v_add_f32_e32 v91, 1.0, v91
	v_rcp_f32_e32 v91, v91
	s_nop 0
	v_mul_f32_e32 v89, v91, v89
	v_mul_f32_e32 v89, v89, v92
	v_cvt_pk_bf16_f32 v89, v89, v0
	v_addc_co_u32_e32 v91, vcc, 0, v95, vcc
	global_store_dwordx4 v[90:91], v[86:89], off offset:2048
	ds_read_b128 v[86:89], v169 offset:25344
	s_waitcnt lgkmcnt(0)
	v_mfma_f32_16x16x32_bf16 v[74:77], v[74:77], v[86:89], 0
	v_mfma_f32_16x16x32_bf16 v[78:81], v[78:81], v[86:89], 0
	ds_read_b128 v[86:89], v169 offset:25408
	s_waitcnt lgkmcnt(0)
	v_mfma_f32_16x16x32_bf16 v[62:65], v[62:65], v[86:89], v[74:77]
	s_nop 3
	ds_read_b128 v[74:77], v169 offset:25472
	v_mfma_f32_16x16x32_bf16 v[70:73], v[70:73], v[86:89], v[78:81]
	s_waitcnt lgkmcnt(0)
	v_mfma_f32_16x16x32_bf16 v[58:61], v[58:61], v[74:77], v[62:65]
	v_mfma_f32_16x16x32_bf16 v[62:65], v[66:69], v[74:77], v[70:73]
	ds_read_b128 v[66:69], v169 offset:25536
	s_waitcnt lgkmcnt(0)
	v_mfma_f32_16x16x32_bf16 v[46:49], v[46:49], v[66:69], v[58:61]
	s_nop 3
	ds_read_b128 v[58:61], v169 offset:25600
	v_mfma_f32_16x16x32_bf16 v[54:57], v[54:57], v[66:69], v[62:65]
	s_waitcnt lgkmcnt(0)
	v_mfma_f32_16x16x32_bf16 v[42:45], v[42:45], v[58:61], v[46:49]
	v_mfma_f32_16x16x32_bf16 v[46:49], v[50:53], v[58:61], v[54:57]
	ds_read_b128 v[50:53], v169 offset:25664
	s_waitcnt lgkmcnt(0)
	v_mfma_f32_16x16x32_bf16 v[30:33], v[30:33], v[50:53], v[42:45]
	s_nop 3
	ds_read_b128 v[42:45], v169 offset:25728
	v_mfma_f32_16x16x32_bf16 v[38:41], v[38:41], v[50:53], v[46:49]
	s_waitcnt lgkmcnt(0)
	v_mfma_f32_16x16x32_bf16 v[26:29], v[26:29], v[42:45], v[30:33]
	v_mfma_f32_16x16x32_bf16 v[30:33], v[34:37], v[42:45], v[38:41]
	ds_read_b128 v[34:37], v169 offset:25792
	s_waitcnt lgkmcnt(0)
	v_mfma_f32_16x16x32_bf16 v[10:13], v[10:13], v[34:37], v[26:29]
	v_mfma_f32_16x16x32_bf16 v[14:17], v[14:17], v[34:37], v[30:33]
	s_nop 6
	v_add_f32_e32 v0, v25, v13
	v_add_f32_e32 v10, v22, v10
	s_waitcnt vmcnt(11)
	v_and_b32_e32 v13, 0xffff0000, v83
	v_mul_f32_e32 v10, v18, v10
	v_mul_f32_e32 v18, 0xbfb8aa3b, v13
	v_exp_f32_e32 v18, v18
	v_mul_f32_e32 v0, v21, v0
	v_add_f32_e32 v11, v23, v11
	v_mul_f32_e32 v11, v19, v11
	v_add_f32_e32 v18, 1.0, v18
	v_rcp_f32_e32 v18, v18
	v_add_f32_e32 v12, v24, v12
	v_mul_f32_e32 v12, v20, v12
	v_add_f32_e32 v6, v6, v14
	v_mul_f32_e32 v13, v18, v13
	v_mul_f32_e32 v0, v13, v0
	v_lshlrev_b32_e32 v13, 16, v82
	v_mul_f32_e32 v18, 0xbfb8aa3b, v13
	v_exp_f32_e32 v18, v18
	v_mul_f32_e32 v2, v2, v6
	v_add_f32_e32 v7, v7, v15
	v_mul_f32_e32 v3, v3, v7
	v_add_f32_e32 v18, 1.0, v18
	v_rcp_f32_e32 v18, v18
	v_add_f32_e32 v8, v8, v16
	v_mul_f32_e32 v4, v4, v8
	v_mul_f32_e32 v13, v18, v13
	v_mul_f32_e32 v10, v13, v10
	v_and_b32_e32 v13, 0xffff0000, v82
	v_mul_f32_e32 v18, 0xbfb8aa3b, v13
	v_exp_f32_e32 v18, v18
	s_nop 0
	v_add_f32_e32 v18, 1.0, v18
	v_rcp_f32_e32 v18, v18
	s_nop 0
	v_mul_f32_e32 v13, v18, v13
	v_mul_f32_e32 v11, v13, v11
	v_lshlrev_b32_e32 v13, 16, v83
	v_mul_f32_e32 v18, 0xbfb8aa3b, v13
	v_exp_f32_e32 v18, v18
	v_cvt_pk_bf16_f32 v10, v10, v11
	s_nop 0
	v_add_f32_e32 v18, 1.0, v18
	v_rcp_f32_e32 v18, v18
	s_nop 0
	v_mul_f32_e32 v13, v18, v13
	v_mul_f32_e32 v12, v13, v12
	v_cvt_pk_bf16_f32 v11, v12, v0
	v_add_f32_e32 v0, v9, v17
	v_mul_f32_e32 v0, v5, v0
	v_and_b32_e32 v5, 0xffff0000, v85
	v_mul_f32_e32 v6, 0xbfb8aa3b, v5
	v_exp_f32_e32 v6, v6
	s_nop 0
	v_add_f32_e32 v6, 1.0, v6
	v_rcp_f32_e32 v6, v6
	s_nop 0
	v_mul_f32_e32 v5, v6, v5
	v_mul_f32_e32 v0, v5, v0
	v_lshlrev_b32_e32 v5, 16, v84
	v_mul_f32_e32 v6, 0xbfb8aa3b, v5
	v_exp_f32_e32 v6, v6
	s_nop 0
	v_add_f32_e32 v6, 1.0, v6
	v_rcp_f32_e32 v6, v6
	s_nop 0
	v_mul_f32_e32 v5, v6, v5
	v_mul_f32_e32 v2, v5, v2
	v_and_b32_e32 v5, 0xffff0000, v84
	v_mul_f32_e32 v6, 0xbfb8aa3b, v5
	v_exp_f32_e32 v6, v6
	s_nop 0
	v_add_f32_e32 v6, 1.0, v6
	v_rcp_f32_e32 v6, v6
	s_nop 0
	v_mul_f32_e32 v5, v6, v5
	v_mul_f32_e32 v3, v5, v3
	v_lshlrev_b32_e32 v5, 16, v85
	v_mul_f32_e32 v6, 0xbfb8aa3b, v5
	v_exp_f32_e32 v6, v6
	v_cvt_pk_bf16_f32 v12, v2, v3
	v_add_co_u32_e32 v2, vcc, 0x6030000, v94
	v_add_f32_e32 v6, 1.0, v6
	v_rcp_f32_e32 v6, v6
	v_addc_co_u32_e32 v3, vcc, 0, v95, vcc
	v_mul_f32_e32 v5, v6, v5
	v_mul_f32_e32 v4, v5, v4
	v_cvt_pk_bf16_f32 v13, v4, v0
	global_store_dwordx4 v[2:3], v[10:13], off offset:2048
	s_waitcnt vmcnt(7)
	ds_write_b128 v164, v[98:101] offset:8448
	s_waitcnt vmcnt(6)
	ds_write_b128 v165, v[102:105] offset:8448
	s_waitcnt vmcnt(5)
	ds_write_b128 v166, v[106:109] offset:8448
	s_waitcnt vmcnt(4)
	ds_write_b128 v167, v[110:113] offset:8448
	ds_write_b128 v168, v[114:117]
	s_waitcnt lgkmcnt(0)
	s_barrier

.LBB0_144:
	s_waitcnt lgkmcnt(0)
	s_barrier
	ds_read_b128 v[122:125], v168 offset:33792
	ds_read_b128 v[134:137], v0 offset:6864
	s_and_b32 s6, s11, 0xfffff000
	s_ashr_i32 s7, s6, 31
	s_lshl_b64 s[6:7], s[6:7], 11
	s_add_u32 s2, s90, s0
	s_waitcnt lgkmcnt(0)
	v_lshlrev_b32_e32 v143, 16, v134
	v_and_b32_e32 v134, 0xffff0000, v134
	v_add_f32_e32 v177, 0, v134
	v_lshlrev_b32_e32 v134, 16, v135
	v_add_f32_e32 v178, 0, v134
	v_and_b32_e32 v134, 0xffff0000, v135
	v_add_f32_e32 v179, 0, v134
	v_lshlrev_b32_e32 v134, 16, v136
	v_add_f32_e32 v180, 0, v134
	v_and_b32_e32 v134, 0xffff0000, v136
	v_add_f32_e32 v181, 0, v134
	v_lshlrev_b32_e32 v134, 16, v137
	v_add_f32_e32 v182, 0, v134
	v_and_b32_e32 v134, 0xffff0000, v137
	v_add_f32_e32 v183, 0, v134
	ds_read_b128 v[134:137], v0 offset:7392
	v_add_f32_e32 v143, 0, v143
	s_addc_u32 s19, s91, s1
	s_add_u32 s18, s2, s6
	s_waitcnt vmcnt(4)
	v_mov_b64_e32 v[104:105], v[84:85]
	s_waitcnt lgkmcnt(0)
	v_lshlrev_b32_e32 v184, 16, v134
	v_and_b32_e32 v134, 0xffff0000, v134
	v_add_f32_e32 v177, v177, v134
	v_lshlrev_b32_e32 v134, 16, v135
	v_add_f32_e32 v178, v178, v134
	v_and_b32_e32 v134, 0xffff0000, v135
	v_add_f32_e32 v179, v179, v134
	v_lshlrev_b32_e32 v134, 16, v136
	v_add_f32_e32 v180, v180, v134
	v_and_b32_e32 v134, 0xffff0000, v136
	v_add_f32_e32 v181, v181, v134
	v_lshlrev_b32_e32 v134, 16, v137
	v_add_f32_e32 v182, v182, v134
	v_and_b32_e32 v134, 0xffff0000, v137
	v_add_f32_e32 v183, v183, v134
	ds_read_b128 v[134:137], v0 offset:7920
	v_add_f32_e32 v143, v143, v184
	s_addc_u32 s19, s19, s7
	v_mov_b64_e32 v[102:103], v[82:83]
	v_lshl_add_u64 v[82:83], s[18:19], 0, v[160:161]
	s_waitcnt lgkmcnt(0)
	v_lshlrev_b32_e32 v184, 16, v134
	v_and_b32_e32 v134, 0xffff0000, v134
	v_add_f32_e32 v177, v177, v134
	v_lshlrev_b32_e32 v134, 16, v135
	v_add_f32_e32 v178, v178, v134
	v_and_b32_e32 v134, 0xffff0000, v135
	v_add_f32_e32 v143, v143, v184
	v_add_f32_e32 v179, v179, v134
	v_lshlrev_b32_e32 v134, 16, v136
	v_add_u32_e32 v184, s10, v141
	global_load_dwordx4 v[106:109], v[82:83], off
	v_lshl_add_u64 v[82:83], s[18:19], 0, v[158:159]
	v_add_f32_e32 v180, v180, v134
	v_and_b32_e32 v134, 0xffff0000, v136
	v_min_i32_e32 v193, 3, v184
	global_load_dwordx4 v[110:113], v[82:83], off
	v_lshl_add_u64 v[82:83], s[18:19], 0, v[156:157]
	s_add_u32 s6, s0, s6
	v_add_f32_e32 v181, v181, v134
	v_lshlrev_b32_e32 v134, 16, v137
	v_add_u32_e32 v193, 1, v193
	global_load_dwordx4 v[114:117], v[82:83], off
	v_lshl_add_u64 v[82:83], s[18:19], 0, v[154:155]
	s_addc_u32 s7, s1, s7
	v_add_f32_e32 v182, v182, v134
	v_and_b32_e32 v134, 0xffff0000, v137
	v_cvt_f32_i32_e32 v193, v193
	global_load_dwordx4 v[118:121], v[82:83], off
	v_lshl_add_u64 v[82:83], s[6:7], 0, v[152:153]
	v_add_f32_e32 v183, v183, v134
	ds_read_b128 v[134:137], v173 offset:8448
	v_lshl_add_u64 v[82:83], v[146:147], 0, v[82:83]
	global_load_dwordx4 v[94:97], v[82:83], off
	v_lshl_add_u64 v[82:83], s[6:7], 0, v[150:151]
	v_mov_b64_e32 v[132:133], v[92:93]
	v_lshl_add_u64 v[82:83], v[146:147], 0, v[82:83]
	v_rcp_iflag_f32_e32 v193, v193
	v_mov_b64_e32 v[130:131], v[90:91]
	global_load_dwordx4 v[90:93], v[82:83], off
	v_lshl_add_u64 v[82:83], s[6:7], 0, v[148:149]
	v_mov_b64_e32 v[128:129], v[88:89]
	v_lshl_add_u64 v[82:83], v[146:147], 0, v[82:83]
	s_waitcnt lgkmcnt(0)
	v_lshlrev_b32_e32 v185, 16, v134
	v_and_b32_e32 v134, 0xffff0000, v134
	v_lshlrev_b32_e32 v190, 16, v135
	v_and_b32_e32 v135, 0xffff0000, v135
	v_lshlrev_b32_e32 v191, 16, v136
	v_and_b32_e32 v136, 0xffff0000, v136
	v_lshlrev_b32_e32 v192, 16, v137
	v_and_b32_e32 v137, 0xffff0000, v137
	v_mov_b64_e32 v[126:127], v[86:87]
	global_load_dwordx4 v[86:89], v[82:83], off
	v_lshl_add_u64 v[82:83], s[6:7], 0, v[144:145]
	v_add_f32_e32 v177, v177, v134
	v_add_f32_e32 v179, v179, v135
	v_add_f32_e32 v181, v181, v136
	v_add_f32_e32 v183, v183, v137
	v_lshl_add_u64 v[82:83], v[146:147], 0, v[82:83]
	v_add_f32_e32 v143, v143, v185
	v_fma_f32 v134, v177, v193, -v134
	v_add_f32_e32 v178, v178, v190
	v_fma_f32 v135, v179, v193, -v135
	v_add_f32_e32 v180, v180, v191
	v_fma_f32 v136, v181, v193, -v136
	v_add_f32_e32 v182, v182, v192
	v_fma_f32 v137, v183, v193, -v137
	global_load_dwordx4 v[82:85], v[82:83], off
	v_fma_f32 v185, v143, v193, -v185
	v_fma_f32 v190, v178, v193, -v190
	v_fma_f32 v191, v180, v193, -v191
	v_fma_f32 v192, v182, v193, -v192
	v_cvt_pk_bf16_f32 v134, v185, v134
	v_cvt_pk_bf16_f32 v135, v190, v135
	v_cvt_pk_bf16_f32 v136, v191, v136
	v_cvt_pk_bf16_f32 v137, v192, v137
	ds_write_b128 v0, v[134:137] offset:42240
	ds_read_b128 v[134:137], v173 offset:6864
	v_add_u32_e32 v193, 1, v184
	v_min_i32_e32 v193, 3, v193
	v_add_u32_e32 v193, 1, v193
	v_cvt_f32_i32_e32 v193, v193
	s_waitcnt lgkmcnt(0)
	v_lshlrev_b32_e32 v185, 16, v134
	v_and_b32_e32 v134, 0xffff0000, v134
	v_sub_f32_e32 v177, v177, v134
	v_lshlrev_b32_e32 v134, 16, v135
	v_sub_f32_e32 v178, v178, v134
	v_and_b32_e32 v134, 0xffff0000, v135
	v_sub_f32_e32 v179, v179, v134
	v_lshlrev_b32_e32 v134, 16, v136
	v_sub_f32_e32 v180, v180, v134
	v_and_b32_e32 v134, 0xffff0000, v136
	v_sub_f32_e32 v181, v181, v134
	v_lshlrev_b32_e32 v134, 16, v137
	v_sub_f32_e32 v182, v182, v134
	v_and_b32_e32 v134, 0xffff0000, v137
	v_sub_f32_e32 v183, v183, v134
	ds_read_b128 v[134:137], v173 offset:8976
	v_rcp_iflag_f32_e32 v193, v193
	v_sub_f32_e32 v143, v143, v185
	s_add_u32 s0, s0, 0x20000
	s_addc_u32 s1, s1, 0
	s_waitcnt lgkmcnt(0)
	v_lshlrev_b32_e32 v185, 16, v134
	v_and_b32_e32 v134, 0xffff0000, v134
	v_lshlrev_b32_e32 v190, 16, v135
	v_and_b32_e32 v135, 0xffff0000, v135
	v_lshlrev_b32_e32 v191, 16, v136
	v_and_b32_e32 v136, 0xffff0000, v136
	v_lshlrev_b32_e32 v192, 16, v137
	v_and_b32_e32 v137, 0xffff0000, v137
	v_add_f32_e32 v177, v177, v134
	v_add_f32_e32 v179, v179, v135
	v_add_f32_e32 v181, v181, v136
	v_add_f32_e32 v183, v183, v137
	v_add_f32_e32 v143, v143, v185
	v_fma_f32 v134, v177, v193, -v134
	v_add_f32_e32 v178, v178, v190
	v_fma_f32 v135, v179, v193, -v135
	v_add_f32_e32 v180, v180, v191
	v_fma_f32 v136, v181, v193, -v136
	v_add_f32_e32 v182, v182, v192
	v_fma_f32 v137, v183, v193, -v137
	v_fma_f32 v185, v143, v193, -v185
	v_fma_f32 v190, v178, v193, -v190
	v_fma_f32 v191, v180, v193, -v191
	v_fma_f32 v192, v182, v193, -v192
	v_cvt_pk_bf16_f32 v134, v185, v134
	v_cvt_pk_bf16_f32 v135, v190, v135
	v_cvt_pk_bf16_f32 v136, v191, v136
	v_cvt_pk_bf16_f32 v137, v192, v137
	ds_write_b128 v0, v[134:137] offset:42768
	ds_read_b128 v[134:137], v173 offset:7392
	v_add_u32_e32 v193, 2, v184
	v_min_i32_e32 v193, 3, v193
	v_add_u32_e32 v193, 1, v193
	v_cvt_f32_i32_e32 v193, v193
	s_waitcnt lgkmcnt(0)
	v_lshlrev_b32_e32 v185, 16, v134
	v_and_b32_e32 v134, 0xffff0000, v134
	v_sub_f32_e32 v177, v177, v134
	v_lshlrev_b32_e32 v134, 16, v135
	v_sub_f32_e32 v178, v178, v134
	v_and_b32_e32 v134, 0xffff0000, v135
	v_sub_f32_e32 v179, v179, v134
	v_lshlrev_b32_e32 v134, 16, v136
	v_sub_f32_e32 v180, v180, v134
	v_and_b32_e32 v134, 0xffff0000, v136
	v_sub_f32_e32 v181, v181, v134
	v_lshlrev_b32_e32 v134, 16, v137
	v_sub_f32_e32 v182, v182, v134
	v_and_b32_e32 v134, 0xffff0000, v137
	v_sub_f32_e32 v183, v183, v134
	ds_read_b128 v[134:137], v173 offset:9504
	v_rcp_iflag_f32_e32 v193, v193
	v_sub_f32_e32 v143, v143, v185
	v_add_u32_e32 v184, 3, v184
	v_min_i32_e32 v184, 3, v184
	s_waitcnt lgkmcnt(0)
	v_lshlrev_b32_e32 v185, 16, v134
	v_and_b32_e32 v134, 0xffff0000, v134
	v_lshlrev_b32_e32 v190, 16, v135
	v_and_b32_e32 v135, 0xffff0000, v135
	v_lshlrev_b32_e32 v191, 16, v136
	v_and_b32_e32 v136, 0xffff0000, v136
	v_lshlrev_b32_e32 v192, 16, v137
	v_and_b32_e32 v137, 0xffff0000, v137
	v_add_f32_e32 v177, v177, v134
	v_add_f32_e32 v179, v179, v135
	v_add_f32_e32 v181, v181, v136
	v_add_f32_e32 v183, v183, v137
	v_add_f32_e32 v143, v143, v185
	v_fma_f32 v134, v177, v193, -v134
	v_add_f32_e32 v178, v178, v190
	v_fma_f32 v135, v179, v193, -v135
	v_add_f32_e32 v180, v180, v191
	v_fma_f32 v136, v181, v193, -v136
	v_add_f32_e32 v182, v182, v192
	v_fma_f32 v137, v183, v193, -v137
	v_fma_f32 v185, v143, v193, -v185
	v_fma_f32 v190, v178, v193, -v190
	v_fma_f32 v191, v180, v193, -v191
	v_fma_f32 v192, v182, v193, -v192
	v_cvt_pk_bf16_f32 v134, v185, v134
	v_cvt_pk_bf16_f32 v135, v190, v135
	v_cvt_pk_bf16_f32 v136, v191, v136
	v_cvt_pk_bf16_f32 v137, v192, v137
	ds_write_b128 v0, v[134:137] offset:43296
	ds_read_b128 v[134:137], v173 offset:7920
	v_add_u32_e32 v184, 1, v184
	v_cvt_f32_i32_e32 v184, v184
	s_add_i32 s10, s10, 64
	s_add_i32 s11, s11, 64
	s_waitcnt lgkmcnt(0)
	v_lshlrev_b32_e32 v185, 16, v134
	v_and_b32_e32 v134, 0xffff0000, v134
	v_sub_f32_e32 v177, v177, v134
	v_lshlrev_b32_e32 v134, 16, v135
	v_sub_f32_e32 v178, v178, v134
	v_and_b32_e32 v134, 0xffff0000, v135
	v_sub_f32_e32 v179, v179, v134
	v_lshlrev_b32_e32 v134, 16, v136
	v_sub_f32_e32 v180, v180, v134
	v_and_b32_e32 v134, 0xffff0000, v136
	v_sub_f32_e32 v181, v181, v134
	v_lshlrev_b32_e32 v134, 16, v137
	v_sub_f32_e32 v182, v182, v134
	v_and_b32_e32 v134, 0xffff0000, v137
	v_sub_f32_e32 v183, v183, v134
	ds_read_b128 v[134:137], v173 offset:10032
	v_rcp_iflag_f32_e32 v184, v184
	v_sub_f32_e32 v143, v143, v185
	s_cmp_lg_u32 s0, 0xe0000
	s_waitcnt lgkmcnt(0)
	v_lshlrev_b32_e32 v185, 16, v134
	v_and_b32_e32 v134, 0xffff0000, v134
	v_lshlrev_b32_e32 v190, 16, v135
	v_and_b32_e32 v135, 0xffff0000, v135
	v_add_f32_e32 v177, v177, v134
	v_lshlrev_b32_e32 v191, 16, v136
	v_and_b32_e32 v136, 0xffff0000, v136
	v_lshlrev_b32_e32 v192, 16, v137
	v_and_b32_e32 v137, 0xffff0000, v137
	v_fma_f32 v134, v177, v184, -v134
	v_add_f32_e32 v177, v178, v190
	v_add_f32_e32 v178, v179, v135
	v_fma_f32 v135, v178, v184, -v135
	v_add_f32_e32 v178, v180, v191
	v_add_f32_e32 v179, v181, v136
	v_add_f32_e32 v180, v183, v137
	v_add_f32_e32 v143, v143, v185
	v_fma_f32 v136, v179, v184, -v136
	v_add_f32_e32 v179, v182, v192
	v_fma_f32 v137, v180, v184, -v137
	v_fma_f32 v143, v143, v184, -v185
	v_fma_f32 v177, v177, v184, -v190
	v_fma_f32 v178, v178, v184, -v191
	v_fma_f32 v179, v179, v184, -v192
	v_cvt_pk_bf16_f32 v134, v143, v134
	v_cvt_pk_bf16_f32 v135, v177, v135
	v_cvt_pk_bf16_f32 v136, v178, v136
	v_cvt_pk_bf16_f32 v137, v179, v137
	ds_write_b128 v0, v[134:137] offset:43824
	s_waitcnt lgkmcnt(0)
	s_barrier
	ds_read_b128 v[134:137], v170 offset:42240
	ds_read_b128 v[182:185], v170 offset:42304
	ds_read_b128 v[238:241], v170 offset:42368
	ds_read_b128 v[242:245], v170 offset:42432
	ds_read_b128 v[246:249], v170 offset:42496
	ds_read_b128 v[228:231], v170 offset:42560
	s_waitcnt lgkmcnt(5)
	v_mfma_f32_16x16x32_bf16 v[178:181], v[74:77], v[134:137], 0
	v_mfma_f32_16x16x32_bf16 v[134:137], v[78:81], v[134:137], 0
	s_waitcnt lgkmcnt(4)
	v_mfma_f32_16x16x32_bf16 v[178:181], v[62:65], v[182:185], v[178:181]
	v_mfma_f32_16x16x32_bf16 v[134:137], v[70:73], v[182:185], v[134:137]
	ds_read_b128 v[182:185], v170 offset:42624
	s_waitcnt lgkmcnt(4)
	v_mfma_f32_16x16x32_bf16 v[178:181], v[58:61], v[238:241], v[178:181]
	v_mfma_f32_16x16x32_bf16 v[134:137], v[66:69], v[238:241], v[134:137]
	ds_read_b128 v[238:241], v170 offset:42688
	s_waitcnt lgkmcnt(4)
	v_mfma_f32_16x16x32_bf16 v[178:181], v[46:49], v[242:245], v[178:181]
	v_mfma_f32_16x16x32_bf16 v[134:137], v[54:57], v[242:245], v[134:137]
	s_waitcnt lgkmcnt(3)
	v_mfma_f32_16x16x32_bf16 v[178:181], v[42:45], v[246:249], v[178:181]
	v_mfma_f32_16x16x32_bf16 v[134:137], v[50:53], v[246:249], v[134:137]
	s_waitcnt lgkmcnt(2)
	v_mfma_f32_16x16x32_bf16 v[178:181], v[30:33], v[228:231], v[178:181]
	v_mfma_f32_16x16x32_bf16 v[134:137], v[38:41], v[228:231], v[134:137]
	s_waitcnt lgkmcnt(1)
	v_mfma_f32_16x16x32_bf16 v[178:181], v[26:29], v[182:185], v[178:181]
	v_mfma_f32_16x16x32_bf16 v[134:137], v[34:37], v[182:185], v[134:137]
	s_waitcnt lgkmcnt(0)
	v_mfma_f32_16x16x32_bf16 v[178:181], v[10:13], v[238:241], v[178:181]
	v_mfma_f32_16x16x32_bf16 v[134:137], v[14:17], v[238:241], v[134:137]
	s_nop 6
	v_add_f32_e32 v181, v25, v181
	v_add_f32_e32 v143, v24, v180
	v_and_b32_e32 v180, 0xffff0000, v99
	v_add_f32_e32 v177, v23, v179
	v_mul_f32_e32 v179, v21, v181
	v_mul_f32_e32 v181, 0xbfb8aa3b, v180
	v_exp_f32_e32 v181, v181
	v_add_f32_e32 v178, v22, v178
	v_mul_f32_e32 v178, v18, v178
	v_mul_f32_e32 v177, v19, v177
	v_add_f32_e32 v181, 1.0, v181
	v_rcp_f32_e32 v181, v181
	v_lshlrev_b32_e32 v99, 16, v99
	v_mul_f32_e32 v143, v20, v143
	v_mul_f32_e32 v180, v181, v180
	v_mul_f32_e32 v179, v180, v179
	v_lshlrev_b32_e32 v180, 16, v98
	v_mul_f32_e32 v181, 0xbfb8aa3b, v180
	v_exp_f32_e32 v181, v181
	v_and_b32_e32 v98, 0xffff0000, v98
	v_add_f32_e32 v181, 1.0, v181
	v_rcp_f32_e32 v181, v181
	s_nop 0
	v_mul_f32_e32 v180, v181, v180
	v_mul_f32_e32 v178, v180, v178
	v_mul_f32_e32 v180, 0xbfb8aa3b, v98
	v_exp_f32_e32 v180, v180
	s_nop 0
	v_add_f32_e32 v180, 1.0, v180
	v_rcp_f32_e32 v180, v180
	s_nop 0
	v_mul_f32_e32 v98, v180, v98
	v_mul_f32_e32 v98, v98, v177
	v_mul_f32_e32 v177, 0xbfb8aa3b, v99
	v_exp_f32_e32 v177, v177
	v_cvt_pk_bf16_f32 v178, v178, v98
	v_add_f32_e32 v98, v9, v137
	v_mul_f32_e32 v98, v5, v98
	v_add_f32_e32 v177, 1.0, v177
	v_rcp_f32_e32 v177, v177
	s_nop 0
	v_mul_f32_e32 v99, v177, v99
	v_mul_f32_e32 v99, v99, v143
	v_cvt_pk_bf16_f32 v179, v99, v179
	v_add_f32_e32 v99, v6, v134
	v_add_f32_e32 v134, v7, v135
	v_add_f32_e32 v135, v8, v136
	v_and_b32_e32 v136, 0xffff0000, v101
	v_mul_f32_e32 v137, 0xbfb8aa3b, v136
	v_exp_f32_e32 v137, v137
	v_mul_f32_e32 v99, v2, v99
	v_mul_f32_e32 v134, v3, v134
	v_lshlrev_b32_e32 v101, 16, v101
	v_add_f32_e32 v137, 1.0, v137
	v_rcp_f32_e32 v137, v137
	v_mul_f32_e32 v135, v4, v135
	v_mul_f32_e32 v136, v137, v136
	v_mul_f32_e32 v98, v136, v98
	v_lshlrev_b32_e32 v136, 16, v100
	v_mul_f32_e32 v137, 0xbfb8aa3b, v136
	v_exp_f32_e32 v137, v137
	v_and_b32_e32 v100, 0xffff0000, v100
	v_add_f32_e32 v137, 1.0, v137
	v_rcp_f32_e32 v137, v137
	s_nop 0
	v_mul_f32_e32 v136, v137, v136
	v_mul_f32_e32 v99, v136, v99
	v_mul_f32_e32 v136, 0xbfb8aa3b, v100
	v_exp_f32_e32 v136, v136
	s_nop 0
	v_add_f32_e32 v136, 1.0, v136
	v_rcp_f32_e32 v136, v136
	s_nop 0
	v_mul_f32_e32 v100, v136, v100
	v_mul_f32_e32 v100, v100, v134
	v_mul_f32_e32 v134, 0xbfb8aa3b, v101
	v_exp_f32_e32 v134, v134
	v_cvt_pk_bf16_f32 v180, v99, v100
	s_nop 0
	v_add_f32_e32 v134, 1.0, v134
	v_rcp_f32_e32 v134, v134
	s_nop 0
	v_mul_f32_e32 v101, v134, v101
	v_mul_f32_e32 v101, v101, v135
	v_cvt_pk_bf16_f32 v181, v101, v98
	ds_read_b128 v[134:137], v170 offset:50688
	ds_read_b128 v[182:185], v170 offset:50752
	ds_read_b128 v[238:241], v170 offset:50816
	ds_read_b128 v[242:245], v170 offset:50880
	ds_read_b128 v[246:249], v170 offset:50944
	ds_read_b128 v[228:231], v170 offset:51008
	v_lshl_add_u64 v[98:99], s[90:91], 0, v[162:163]
	v_add_co_u32_e32 v100, vcc, s9, v98
	v_lshl_add_u64 v[162:163], v[162:163], 0, s[36:37]
	s_nop 0
	v_addc_co_u32_e32 v101, vcc, 0, v99, vcc
	global_store_dwordx4 v[100:101], v[178:181], off offset:2560
	s_nop 0
	s_waitcnt lgkmcnt(5)
	v_mfma_f32_16x16x32_bf16 v[178:181], v[74:77], v[134:137], 0
	v_mfma_f32_16x16x32_bf16 v[134:137], v[78:81], v[134:137], 0
	s_waitcnt lgkmcnt(4)
	v_mfma_f32_16x16x32_bf16 v[178:181], v[62:65], v[182:185], v[178:181]
	v_mfma_f32_16x16x32_bf16 v[134:137], v[70:73], v[182:185], v[134:137]
	ds_read_b128 v[182:185], v170 offset:51072
	s_waitcnt lgkmcnt(4)
	v_mfma_f32_16x16x32_bf16 v[178:181], v[58:61], v[238:241], v[178:181]
	v_mfma_f32_16x16x32_bf16 v[134:137], v[66:69], v[238:241], v[134:137]
	ds_read_b128 v[238:241], v170 offset:51136
	s_waitcnt lgkmcnt(4)
	v_mfma_f32_16x16x32_bf16 v[178:181], v[46:49], v[242:245], v[178:181]
	v_mfma_f32_16x16x32_bf16 v[134:137], v[54:57], v[242:245], v[134:137]
	s_waitcnt lgkmcnt(3)
	v_mfma_f32_16x16x32_bf16 v[178:181], v[42:45], v[246:249], v[178:181]
	v_mfma_f32_16x16x32_bf16 v[134:137], v[50:53], v[246:249], v[134:137]
	s_waitcnt lgkmcnt(2)
	v_mfma_f32_16x16x32_bf16 v[178:181], v[30:33], v[228:231], v[178:181]
	v_mfma_f32_16x16x32_bf16 v[134:137], v[38:41], v[228:231], v[134:137]
	s_waitcnt lgkmcnt(1)
	v_mfma_f32_16x16x32_bf16 v[178:181], v[26:29], v[182:185], v[178:181]
	v_mfma_f32_16x16x32_bf16 v[134:137], v[34:37], v[182:185], v[134:137]
	s_waitcnt lgkmcnt(0)
	v_mfma_f32_16x16x32_bf16 v[178:181], v[10:13], v[238:241], v[178:181]
	v_mfma_f32_16x16x32_bf16 v[134:137], v[14:17], v[238:241], v[134:137]
	s_nop 6
	v_add_f32_e32 v101, v22, v178
	v_and_b32_e32 v178, 0xffff0000, v131
	v_add_f32_e32 v143, v23, v179
	v_mul_f32_e32 v179, 0xbfb8aa3b, v178
	v_exp_f32_e32 v179, v179
	v_add_f32_e32 v100, v25, v181
	v_mul_f32_e32 v100, v21, v100
	v_mul_f32_e32 v101, v18, v101
	v_add_f32_e32 v179, 1.0, v179
	v_rcp_f32_e32 v179, v179
	v_mul_f32_e32 v143, v19, v143
	v_lshlrev_b32_e32 v131, 16, v131
	v_add_f32_e32 v177, v24, v180
	v_mul_f32_e32 v178, v179, v178
	v_mul_f32_e32 v100, v178, v100
	v_lshlrev_b32_e32 v178, 16, v130
	v_mul_f32_e32 v179, 0xbfb8aa3b, v178
	v_exp_f32_e32 v179, v179
	v_and_b32_e32 v130, 0xffff0000, v130
	v_mul_f32_e32 v177, v20, v177
	v_add_f32_e32 v179, 1.0, v179
	v_rcp_f32_e32 v179, v179
	s_nop 0
	v_mul_f32_e32 v178, v179, v178
	v_mul_f32_e32 v101, v178, v101
	v_mul_f32_e32 v178, 0xbfb8aa3b, v130
	v_exp_f32_e32 v178, v178
	s_nop 0
	v_add_f32_e32 v178, 1.0, v178
	v_rcp_f32_e32 v178, v178
	s_nop 0
	v_mul_f32_e32 v130, v178, v130
	v_mul_f32_e32 v130, v130, v143
	v_mul_f32_e32 v143, 0xbfb8aa3b, v131
	v_exp_f32_e32 v143, v143
	v_cvt_pk_bf16_f32 v130, v101, v130
	v_add_f32_e32 v101, v6, v134
	v_add_f32_e32 v134, v7, v135
	v_add_f32_e32 v143, 1.0, v143
	v_rcp_f32_e32 v143, v143
	v_add_f32_e32 v135, v8, v136
	v_and_b32_e32 v136, 0xffff0000, v133
	v_mul_f32_e32 v101, v2, v101
	v_mul_f32_e32 v131, v143, v131
	v_mul_f32_e32 v131, v131, v177
	v_cvt_pk_bf16_f32 v131, v131, v100
	v_add_f32_e32 v100, v9, v137
	v_mul_f32_e32 v137, 0xbfb8aa3b, v136
	v_exp_f32_e32 v137, v137
	v_mul_f32_e32 v100, v5, v100
	v_mul_f32_e32 v134, v3, v134
	v_lshlrev_b32_e32 v133, 16, v133
	v_add_f32_e32 v137, 1.0, v137
	v_rcp_f32_e32 v137, v137
	v_mul_f32_e32 v135, v4, v135
	v_mul_f32_e32 v136, v137, v136
	v_mul_f32_e32 v100, v136, v100
	v_lshlrev_b32_e32 v136, 16, v132
	v_mul_f32_e32 v137, 0xbfb8aa3b, v136
	v_exp_f32_e32 v137, v137
	v_and_b32_e32 v132, 0xffff0000, v132
	v_add_f32_e32 v137, 1.0, v137
	v_rcp_f32_e32 v137, v137
	s_nop 0
	v_mul_f32_e32 v136, v137, v136
	v_mul_f32_e32 v101, v136, v101
	v_mul_f32_e32 v136, 0xbfb8aa3b, v132
	v_exp_f32_e32 v136, v136
	s_nop 0
	v_add_f32_e32 v136, 1.0, v136
	v_rcp_f32_e32 v136, v136
	s_nop 0
	v_mul_f32_e32 v132, v136, v132
	v_mul_f32_e32 v132, v132, v134
	v_mul_f32_e32 v134, 0xbfb8aa3b, v133
	v_exp_f32_e32 v134, v134
	v_cvt_pk_bf16_f32 v132, v101, v132
	s_nop 0
	v_add_f32_e32 v134, 1.0, v134
	v_rcp_f32_e32 v134, v134
	s_nop 0
	v_mul_f32_e32 v133, v134, v133
	v_mul_f32_e32 v133, v133, v135
	v_cvt_pk_bf16_f32 v133, v133, v100
	v_add_co_u32_e32 v100, vcc, s24, v98
	ds_read_b128 v[178:181], v170 offset:59200
	s_nop 0
	v_addc_co_u32_e32 v101, vcc, 0, v99, vcc
	global_store_dwordx4 v[100:101], v[130:133], off offset:2560
	ds_read_b128 v[130:133], v170 offset:59136
	ds_read_b128 v[238:241], v170 offset:59264
	ds_read_b128 v[242:245], v170 offset:59328
	ds_read_b128 v[246:249], v170 offset:59392
	ds_read_b128 v[228:231], v170 offset:59456
	s_waitcnt lgkmcnt(4)
	v_mfma_f32_16x16x32_bf16 v[134:137], v[74:77], v[130:133], 0
	v_mfma_f32_16x16x32_bf16 v[130:133], v[78:81], v[130:133], 0
	s_waitcnt lgkmcnt(5)
	v_mfma_f32_16x16x32_bf16 v[134:137], v[62:65], v[178:181], v[134:137]
	v_mfma_f32_16x16x32_bf16 v[130:133], v[70:73], v[178:181], v[130:133]
	ds_read_b128 v[178:181], v170 offset:59520
	s_waitcnt lgkmcnt(4)
	v_mfma_f32_16x16x32_bf16 v[134:137], v[58:61], v[238:241], v[134:137]
	v_mfma_f32_16x16x32_bf16 v[130:133], v[66:69], v[238:241], v[130:133]
	ds_read_b128 v[238:241], v170 offset:59584
	s_waitcnt lgkmcnt(4)
	v_mfma_f32_16x16x32_bf16 v[134:137], v[46:49], v[242:245], v[134:137]
	v_mfma_f32_16x16x32_bf16 v[130:133], v[54:57], v[242:245], v[130:133]
	s_waitcnt lgkmcnt(3)
	v_mfma_f32_16x16x32_bf16 v[134:137], v[42:45], v[246:249], v[134:137]
	v_mfma_f32_16x16x32_bf16 v[130:133], v[50:53], v[246:249], v[130:133]
	s_waitcnt lgkmcnt(2)
	v_mfma_f32_16x16x32_bf16 v[134:137], v[30:33], v[228:231], v[134:137]
	v_mfma_f32_16x16x32_bf16 v[130:133], v[38:41], v[228:231], v[130:133]
	s_waitcnt lgkmcnt(1)
	v_mfma_f32_16x16x32_bf16 v[134:137], v[26:29], v[178:181], v[134:137]
	v_mfma_f32_16x16x32_bf16 v[130:133], v[34:37], v[178:181], v[130:133]
	s_waitcnt lgkmcnt(0)
	v_mfma_f32_16x16x32_bf16 v[134:137], v[10:13], v[238:241], v[134:137]
	v_mfma_f32_16x16x32_bf16 v[130:133], v[14:17], v[238:241], v[130:133]
	s_nop 6
	v_add_f32_e32 v101, v22, v134
	v_add_f32_e32 v134, v23, v135
	v_add_f32_e32 v135, v24, v136
	v_and_b32_e32 v136, 0xffff0000, v127
	v_add_f32_e32 v100, v25, v137
	v_mul_f32_e32 v137, 0xbfb8aa3b, v136
	v_exp_f32_e32 v137, v137
	v_mul_f32_e32 v100, v21, v100
	v_mul_f32_e32 v101, v18, v101
	v_mul_f32_e32 v134, v19, v134
	v_add_f32_e32 v137, 1.0, v137
	v_rcp_f32_e32 v137, v137
	v_lshlrev_b32_e32 v127, 16, v127
	v_mul_f32_e32 v135, v20, v135
	v_mul_f32_e32 v136, v137, v136
	v_mul_f32_e32 v100, v136, v100
	v_lshlrev_b32_e32 v136, 16, v126
	v_mul_f32_e32 v137, 0xbfb8aa3b, v136
	v_exp_f32_e32 v137, v137
	v_and_b32_e32 v126, 0xffff0000, v126
	v_add_f32_e32 v137, 1.0, v137
	v_rcp_f32_e32 v137, v137
	s_nop 0
	v_mul_f32_e32 v136, v137, v136
	v_mul_f32_e32 v101, v136, v101
	v_mul_f32_e32 v136, 0xbfb8aa3b, v126
	v_exp_f32_e32 v136, v136
	s_nop 0
	v_add_f32_e32 v136, 1.0, v136
	v_rcp_f32_e32 v136, v136
	s_nop 0
	v_mul_f32_e32 v126, v136, v126
	v_mul_f32_e32 v126, v126, v134
	v_mul_f32_e32 v134, 0xbfb8aa3b, v127
	v_exp_f32_e32 v134, v134
	v_cvt_pk_bf16_f32 v126, v101, v126
	v_add_f32_e32 v101, v6, v130
	v_add_f32_e32 v130, v7, v131
	v_add_f32_e32 v134, 1.0, v134
	v_rcp_f32_e32 v134, v134
	v_add_f32_e32 v131, v8, v132
	v_and_b32_e32 v132, 0xffff0000, v129
	v_mul_f32_e32 v101, v2, v101
	v_mul_f32_e32 v127, v134, v127
	v_mul_f32_e32 v127, v127, v135
	v_cvt_pk_bf16_f32 v127, v127, v100
	v_add_f32_e32 v100, v9, v133
	v_mul_f32_e32 v133, 0xbfb8aa3b, v132
	v_exp_f32_e32 v133, v133
	v_mul_f32_e32 v100, v5, v100
	v_mul_f32_e32 v130, v3, v130
	v_lshlrev_b32_e32 v129, 16, v129
	v_add_f32_e32 v133, 1.0, v133
	v_rcp_f32_e32 v133, v133
	v_mul_f32_e32 v131, v4, v131
	v_mul_f32_e32 v132, v133, v132
	v_mul_f32_e32 v100, v132, v100
	v_lshlrev_b32_e32 v132, 16, v128
	v_mul_f32_e32 v133, 0xbfb8aa3b, v132
	v_exp_f32_e32 v133, v133
	v_and_b32_e32 v128, 0xffff0000, v128
	v_add_f32_e32 v133, 1.0, v133
	v_rcp_f32_e32 v133, v133
	s_nop 0
	v_mul_f32_e32 v132, v133, v132
	v_mul_f32_e32 v101, v132, v101
	v_mul_f32_e32 v132, 0xbfb8aa3b, v128
	v_exp_f32_e32 v132, v132
	s_nop 0
	v_add_f32_e32 v132, 1.0, v132
	v_rcp_f32_e32 v132, v132
	s_nop 0
	v_mul_f32_e32 v128, v132, v128
	v_mul_f32_e32 v128, v128, v130
	v_mul_f32_e32 v130, 0xbfb8aa3b, v129
	v_exp_f32_e32 v130, v130
	v_cvt_pk_bf16_f32 v128, v101, v128
	s_nop 0
	v_add_f32_e32 v130, 1.0, v130
	v_rcp_f32_e32 v130, v130
	s_nop 0
	v_mul_f32_e32 v129, v130, v129
	v_mul_f32_e32 v129, v129, v131
	v_cvt_pk_bf16_f32 v129, v129, v100
	v_add_co_u32_e32 v100, vcc, s25, v98
	ds_read_b128 v[134:137], v169 offset:25408
	s_nop 0
	v_addc_co_u32_e32 v101, vcc, 0, v99, vcc
	global_store_dwordx4 v[100:101], v[126:129], off offset:2560
	ds_read_b128 v[126:129], v169 offset:25344
	ds_read_b128 v[238:241], v169 offset:25472
	ds_read_b128 v[242:245], v169 offset:25536
	ds_read_b128 v[246:249], v169 offset:25600
	ds_read_b128 v[228:231], v169 offset:25664
	s_waitcnt lgkmcnt(4)
	v_mfma_f32_16x16x32_bf16 v[130:133], v[74:77], v[126:129], 0
	v_add_co_u32_e32 v98, vcc, s14, v98
	v_mfma_f32_16x16x32_bf16 v[126:129], v[78:81], v[126:129], 0
	s_nop 0
	v_addc_co_u32_e32 v99, vcc, 0, v99, vcc
	s_waitcnt lgkmcnt(5)
	v_mfma_f32_16x16x32_bf16 v[130:133], v[62:65], v[134:137], v[130:133]
	v_mfma_f32_16x16x32_bf16 v[126:129], v[70:73], v[134:137], v[126:129]
	ds_read_b128 v[134:137], v169 offset:25728
	s_waitcnt lgkmcnt(4)
	v_mfma_f32_16x16x32_bf16 v[130:133], v[58:61], v[238:241], v[130:133]
	v_mfma_f32_16x16x32_bf16 v[126:129], v[66:69], v[238:241], v[126:129]
	ds_read_b128 v[238:241], v169 offset:25792
	s_waitcnt lgkmcnt(4)
	v_mfma_f32_16x16x32_bf16 v[130:133], v[46:49], v[242:245], v[130:133]
	v_mfma_f32_16x16x32_bf16 v[126:129], v[54:57], v[242:245], v[126:129]
	s_waitcnt lgkmcnt(3)
	v_mfma_f32_16x16x32_bf16 v[130:133], v[42:45], v[246:249], v[130:133]
	v_mfma_f32_16x16x32_bf16 v[126:129], v[50:53], v[246:249], v[126:129]
	s_waitcnt lgkmcnt(2)
	v_mfma_f32_16x16x32_bf16 v[130:133], v[30:33], v[228:231], v[130:133]
	v_mfma_f32_16x16x32_bf16 v[126:129], v[38:41], v[228:231], v[126:129]
	s_waitcnt lgkmcnt(1)
	v_mfma_f32_16x16x32_bf16 v[130:133], v[26:29], v[134:137], v[130:133]
	v_mfma_f32_16x16x32_bf16 v[126:129], v[34:37], v[134:137], v[126:129]
	s_waitcnt lgkmcnt(0)
	v_mfma_f32_16x16x32_bf16 v[130:133], v[10:13], v[238:241], v[130:133]
	v_mfma_f32_16x16x32_bf16 v[126:129], v[14:17], v[238:241], v[126:129]
	s_nop 6
	v_add_f32_e32 v101, v22, v130
	v_add_f32_e32 v130, v23, v131
	v_add_f32_e32 v131, v24, v132
	v_and_b32_e32 v132, 0xffff0000, v103
	v_add_f32_e32 v100, v25, v133
	v_mul_f32_e32 v133, 0xbfb8aa3b, v132
	v_exp_f32_e32 v133, v133
	v_mul_f32_e32 v100, v21, v100
	v_mul_f32_e32 v101, v18, v101
	v_mul_f32_e32 v131, v20, v131
	v_add_f32_e32 v133, 1.0, v133
	v_rcp_f32_e32 v133, v133
	v_mul_f32_e32 v130, v19, v130
	v_mul_f32_e32 v132, v133, v132
	v_mul_f32_e32 v132, v132, v100
	v_lshlrev_b32_e32 v100, 16, v102
	v_mul_f32_e32 v133, 0xbfb8aa3b, v100
	v_exp_f32_e32 v133, v133
	s_nop 0
	v_add_f32_e32 v133, 1.0, v133
	v_rcp_f32_e32 v133, v133
	s_nop 0
	v_mul_f32_e32 v100, v133, v100
	v_mul_f32_e32 v100, v100, v101
	v_and_b32_e32 v101, 0xffff0000, v102
	v_mul_f32_e32 v102, 0xbfb8aa3b, v101
	v_exp_f32_e32 v102, v102
	s_nop 0
	v_add_f32_e32 v102, 1.0, v102
	v_rcp_f32_e32 v102, v102
	s_nop 0
	v_mul_f32_e32 v101, v102, v101
	v_lshlrev_b32_e32 v102, 16, v103
	v_mul_f32_e32 v103, 0xbfb8aa3b, v102
	v_exp_f32_e32 v103, v103
	v_mul_f32_e32 v101, v101, v130
	v_cvt_pk_bf16_f32 v100, v100, v101
	v_add_f32_e32 v103, 1.0, v103
	v_rcp_f32_e32 v103, v103
	s_nop 0
	v_mul_f32_e32 v102, v103, v102
	v_mul_f32_e32 v102, v102, v131
	v_add_f32_e32 v103, v6, v126
	v_add_f32_e32 v126, v7, v127
	v_add_f32_e32 v127, v8, v128
	v_and_b32_e32 v128, 0xffff0000, v105
	v_cvt_pk_bf16_f32 v101, v102, v132
	v_add_f32_e32 v102, v9, v129
	v_mul_f32_e32 v129, 0xbfb8aa3b, v128
	v_exp_f32_e32 v129, v129
	v_mul_f32_e32 v102, v5, v102
	v_mul_f32_e32 v103, v2, v103
	v_mul_f32_e32 v126, v3, v126
	v_add_f32_e32 v129, 1.0, v129
	v_rcp_f32_e32 v129, v129
	v_mul_f32_e32 v127, v4, v127
	v_mul_f32_e32 v128, v129, v128
	v_mul_f32_e32 v128, v128, v102
	v_lshlrev_b32_e32 v102, 16, v104
	v_mul_f32_e32 v129, 0xbfb8aa3b, v102
	v_exp_f32_e32 v129, v129
	s_nop 0
	v_add_f32_e32 v129, 1.0, v129
	v_rcp_f32_e32 v129, v129
	s_nop 0
	v_mul_f32_e32 v102, v129, v102
	v_mul_f32_e32 v102, v102, v103
	v_and_b32_e32 v103, 0xffff0000, v104
	v_mul_f32_e32 v104, 0xbfb8aa3b, v103
	v_exp_f32_e32 v104, v104
	s_nop 0
	v_add_f32_e32 v104, 1.0, v104
	v_rcp_f32_e32 v104, v104
	s_nop 0
	v_mul_f32_e32 v103, v104, v103
	v_lshlrev_b32_e32 v104, 16, v105
	v_mul_f32_e32 v105, 0xbfb8aa3b, v104
	v_exp_f32_e32 v105, v105
	v_mul_f32_e32 v103, v103, v126
	v_cvt_pk_bf16_f32 v102, v102, v103
	v_add_f32_e32 v105, 1.0, v105
	v_rcp_f32_e32 v105, v105
	s_nop 0
	v_mul_f32_e32 v104, v105, v104
	v_mul_f32_e32 v104, v104, v127
	v_cvt_pk_bf16_f32 v103, v104, v128
	global_store_dwordx4 v[98:99], v[100:103], off offset:2560
	s_waitcnt vmcnt(11)
	ds_write_b128 v164, v[106:109] offset:8448
	s_waitcnt vmcnt(10)
	ds_write_b128 v165, v[110:113] offset:8448
	s_waitcnt vmcnt(9)
	ds_write_b128 v166, v[114:117] offset:8448
	s_waitcnt vmcnt(8)
	ds_write_b128 v167, v[118:121] offset:8448
	ds_write_b128 v168, v[122:125]
	s_waitcnt vmcnt(7)
	v_mov_b64_e32 v[100:101], v[96:97]
	v_mov_b64_e32 v[98:99], v[94:95]
	s_cbranch_scc1 .LBB0_144
	s_add_u32 s0, s90, s44
	s_addc_u32 s1, s91, s45
	v_lshl_add_u64 v[98:99], v[138:139], 1, s[0:1]
	s_or_b32 s2, s15, 0x1c0
	s_lshl_b64 s[0:1], s[42:43], 11
	v_readlane_b32 s6, v253, 40
	v_readlane_b32 s7, v253, 41
	s_add_u32 s0, s6, s0
	v_add_u32_e32 v124, s2, v172
	v_add_u32_e32 v102, s2, v175
	v_add_u32_e32 v106, s2, v176
	v_add_u32_e32 v112, s2, v174
	v_mov_b32_e32 v143, v1
	s_addc_u32 s1, s7, s1
	v_mov_b32_e32 v141, v1
	v_ashrrev_i32_e32 v125, 31, v124
	v_ashrrev_i32_e32 v103, 31, v102
	v_ashrrev_i32_e32 v107, 31, v106
	v_ashrrev_i32_e32 v113, 31, v112
	v_lshl_add_u64 v[118:119], v[98:99], 0, v[142:143]
	v_lshl_add_u64 v[110:111], s[0:1], 0, v[140:141]
	v_lshlrev_b64 v[98:99], 11, v[124:125]
	v_lshlrev_b64 v[102:103], 11, v[102:103]
	v_lshlrev_b64 v[106:107], 11, v[106:107]
	v_lshlrev_b64 v[112:113], 11, v[112:113]
	s_waitcnt lgkmcnt(0)
	s_barrier
	v_lshl_add_u64 v[98:99], v[110:111], 0, v[98:99]
	v_lshl_add_u64 v[102:103], v[110:111], 0, v[102:103]
	v_lshl_add_u64 v[106:107], v[110:111], 0, v[106:107]
	v_lshl_add_u64 v[110:111], v[110:111], 0, v[112:113]
	global_load_dwordx4 v[98:101], v[98:99], off offset:512
	s_nop 0
	global_load_dwordx4 v[102:105], v[102:103], off offset:512
	s_nop 0
	global_load_dwordx4 v[106:109], v[106:107], off offset:512
	s_nop 0
	global_load_dwordx4 v[110:113], v[110:111], off offset:512
	ds_read_b128 v[114:117], v168 offset:33792
	ds_read_b128 v[120:123], v0 offset:6864
	s_waitcnt lgkmcnt(0)
	v_lshlrev_b32_e32 v125, 16, v120
	v_and_b32_e32 v120, 0xffff0000, v120
	v_add_f32_e32 v126, 0, v120
	v_lshlrev_b32_e32 v120, 16, v121
	v_add_f32_e32 v127, 0, v120
	v_and_b32_e32 v120, 0xffff0000, v121
	v_add_f32_e32 v128, 0, v120
	v_lshlrev_b32_e32 v120, 16, v122
	v_add_f32_e32 v129, 0, v120
	v_and_b32_e32 v120, 0xffff0000, v122
	v_add_f32_e32 v130, 0, v120
	v_lshlrev_b32_e32 v120, 16, v123
	v_add_f32_e32 v131, 0, v120
	v_and_b32_e32 v120, 0xffff0000, v123
	v_add_f32_e32 v132, 0, v120
	ds_read_b128 v[120:123], v0 offset:7392
	v_add_f32_e32 v125, 0, v125
	s_waitcnt lgkmcnt(0)
	v_lshlrev_b32_e32 v133, 16, v120
	v_and_b32_e32 v120, 0xffff0000, v120
	v_add_f32_e32 v126, v126, v120
	v_lshlrev_b32_e32 v120, 16, v121
	v_add_f32_e32 v127, v127, v120
	v_and_b32_e32 v120, 0xffff0000, v121
	v_add_f32_e32 v128, v128, v120
	v_lshlrev_b32_e32 v120, 16, v122
	v_add_f32_e32 v129, v129, v120
	v_and_b32_e32 v120, 0xffff0000, v122
	v_add_f32_e32 v130, v130, v120
	v_lshlrev_b32_e32 v120, 16, v123
	v_add_f32_e32 v131, v131, v120
	v_and_b32_e32 v120, 0xffff0000, v123
	v_add_f32_e32 v132, v132, v120
	ds_read_b128 v[120:123], v0 offset:7920
	v_add_f32_e32 v125, v125, v133
	s_waitcnt lgkmcnt(0)
	v_lshlrev_b32_e32 v133, 16, v120
	v_and_b32_e32 v120, 0xffff0000, v120
	v_add_f32_e32 v126, v126, v120
	v_lshlrev_b32_e32 v120, 16, v121
	v_add_f32_e32 v127, v127, v120
	v_and_b32_e32 v120, 0xffff0000, v121
	v_add_f32_e32 v128, v128, v120
	v_lshlrev_b32_e32 v120, 16, v122
	v_add_f32_e32 v129, v129, v120
	v_and_b32_e32 v120, 0xffff0000, v122
	v_add_f32_e32 v130, v130, v120
	v_lshlrev_b32_e32 v120, 16, v123
	v_add_f32_e32 v131, v131, v120
	v_and_b32_e32 v120, 0xffff0000, v123
	v_add_f32_e32 v132, v132, v120
	v_mad_u64_u32 v[120:121], s[0:1], v172, 3, v[124:125]
	v_min_i32_e32 v137, 3, v120
	v_add_u32_e32 v137, 1, v137
	v_cvt_f32_i32_e32 v137, v137
	v_add_f32_e32 v133, v125, v133
	ds_read_b128 v[122:125], v173 offset:8448
	s_lshl_b32 s0, s20, 19
	v_rcp_iflag_f32_e32 v137, v137
	s_and_b32 s0, s0, 0xe00000
	s_waitcnt lgkmcnt(0)
	v_lshlrev_b32_e32 v121, 16, v122
	v_and_b32_e32 v122, 0xffff0000, v122
	v_lshlrev_b32_e32 v134, 16, v123
	v_and_b32_e32 v123, 0xffff0000, v123
	v_lshlrev_b32_e32 v135, 16, v124
	v_and_b32_e32 v124, 0xffff0000, v124
	v_lshlrev_b32_e32 v136, 16, v125
	v_and_b32_e32 v125, 0xffff0000, v125
	v_add_f32_e32 v126, v126, v122
	v_add_f32_e32 v128, v128, v123
	v_add_f32_e32 v130, v130, v124
	v_add_f32_e32 v132, v132, v125
	v_add_f32_e32 v133, v133, v121
	v_fma_f32 v122, v126, v137, -v122
	v_add_f32_e32 v127, v127, v134
	v_fma_f32 v123, v128, v137, -v123
	v_add_f32_e32 v129, v129, v135
	v_fma_f32 v124, v130, v137, -v124
	v_add_f32_e32 v131, v131, v136
	v_fma_f32 v125, v132, v137, -v125
	v_fma_f32 v121, v133, v137, -v121
	v_fma_f32 v134, v127, v137, -v134
	v_fma_f32 v135, v129, v137, -v135
	v_fma_f32 v136, v131, v137, -v136
	v_cvt_pk_bf16_f32 v122, v121, v122
	v_cvt_pk_bf16_f32 v123, v134, v123
	v_cvt_pk_bf16_f32 v124, v135, v124
	v_cvt_pk_bf16_f32 v125, v136, v125
	ds_write_b128 v0, v[122:125] offset:42240
	ds_read_b128 v[122:125], v173 offset:6864
	v_or_b32_e32 v137, 1, v120
	v_min_i32_e32 v137, 3, v137
	v_add_u32_e32 v137, 1, v137
	v_cvt_f32_i32_e32 v137, v137
	s_waitcnt lgkmcnt(0)
	v_lshlrev_b32_e32 v121, 16, v122
	v_and_b32_e32 v122, 0xffff0000, v122
	v_sub_f32_e32 v126, v126, v122
	v_lshlrev_b32_e32 v122, 16, v123
	v_sub_f32_e32 v127, v127, v122
	v_and_b32_e32 v122, 0xffff0000, v123
	v_sub_f32_e32 v128, v128, v122
	v_lshlrev_b32_e32 v122, 16, v124
	v_sub_f32_e32 v129, v129, v122
	v_and_b32_e32 v122, 0xffff0000, v124
	v_sub_f32_e32 v130, v130, v122
	v_lshlrev_b32_e32 v122, 16, v125
	v_sub_f32_e32 v131, v131, v122
	v_and_b32_e32 v122, 0xffff0000, v125
	v_sub_f32_e32 v132, v132, v122
	ds_read_b128 v[122:125], v173 offset:8976
	v_rcp_iflag_f32_e32 v137, v137
	v_sub_f32_e32 v121, v133, v121
	s_waitcnt lgkmcnt(0)
	v_lshlrev_b32_e32 v133, 16, v122
	v_and_b32_e32 v122, 0xffff0000, v122
	v_lshlrev_b32_e32 v134, 16, v123
	v_and_b32_e32 v123, 0xffff0000, v123
	v_lshlrev_b32_e32 v135, 16, v124
	v_and_b32_e32 v124, 0xffff0000, v124
	v_lshlrev_b32_e32 v136, 16, v125
	v_and_b32_e32 v125, 0xffff0000, v125
	v_add_f32_e32 v126, v126, v122
	v_add_f32_e32 v128, v128, v123
	v_add_f32_e32 v130, v130, v124
	v_add_f32_e32 v132, v132, v125
	v_add_f32_e32 v121, v121, v133
	v_fma_f32 v122, v126, v137, -v122
	v_add_f32_e32 v127, v127, v134
	v_fma_f32 v123, v128, v137, -v123
	v_add_f32_e32 v129, v129, v135
	v_fma_f32 v124, v130, v137, -v124
	v_add_f32_e32 v131, v131, v136
	v_fma_f32 v125, v132, v137, -v125
	v_fma_f32 v133, v121, v137, -v133
	v_fma_f32 v134, v127, v137, -v134
	v_fma_f32 v135, v129, v137, -v135
	v_fma_f32 v136, v131, v137, -v136
	v_cvt_pk_bf16_f32 v122, v133, v122
	v_cvt_pk_bf16_f32 v123, v134, v123
	v_cvt_pk_bf16_f32 v124, v135, v124
	v_cvt_pk_bf16_f32 v125, v136, v125
	ds_write_b128 v0, v[122:125] offset:42768
	ds_read_b128 v[122:125], v173 offset:7392
	v_or_b32_e32 v137, 2, v120
	v_min_i32_e32 v137, 3, v137
	v_add_u32_e32 v137, 1, v137
	v_cvt_f32_i32_e32 v137, v137
	s_waitcnt lgkmcnt(0)
	v_lshlrev_b32_e32 v133, 16, v122
	v_and_b32_e32 v122, 0xffff0000, v122
	v_sub_f32_e32 v126, v126, v122
	v_lshlrev_b32_e32 v122, 16, v123
	v_sub_f32_e32 v127, v127, v122
	v_and_b32_e32 v122, 0xffff0000, v123
	v_sub_f32_e32 v128, v128, v122
	v_lshlrev_b32_e32 v122, 16, v124
	v_sub_f32_e32 v129, v129, v122
	v_and_b32_e32 v122, 0xffff0000, v124
	v_sub_f32_e32 v130, v130, v122
	v_lshlrev_b32_e32 v122, 16, v125
	v_sub_f32_e32 v131, v131, v122
	v_and_b32_e32 v122, 0xffff0000, v125
	v_sub_f32_e32 v132, v132, v122
	ds_read_b128 v[122:125], v173 offset:9504
	v_rcp_iflag_f32_e32 v137, v137
	v_sub_f32_e32 v121, v121, v133
	v_or_b32_e32 v120, 3, v120
	v_min_i32_e32 v120, 3, v120
	s_waitcnt lgkmcnt(0)
	v_lshlrev_b32_e32 v133, 16, v122
	v_and_b32_e32 v122, 0xffff0000, v122
	v_lshlrev_b32_e32 v134, 16, v123
	v_and_b32_e32 v123, 0xffff0000, v123
	v_lshlrev_b32_e32 v135, 16, v124
	v_and_b32_e32 v124, 0xffff0000, v124
	v_lshlrev_b32_e32 v136, 16, v125
	v_and_b32_e32 v125, 0xffff0000, v125
	v_add_f32_e32 v126, v126, v122
	v_add_f32_e32 v128, v128, v123
	v_add_f32_e32 v130, v130, v124
	v_add_f32_e32 v132, v132, v125
	v_add_f32_e32 v121, v121, v133
	v_fma_f32 v122, v126, v137, -v122
	v_add_f32_e32 v127, v127, v134
	v_fma_f32 v123, v128, v137, -v123
	v_add_f32_e32 v129, v129, v135
	v_fma_f32 v124, v130, v137, -v124
	v_add_f32_e32 v131, v131, v136
	v_fma_f32 v125, v132, v137, -v125
	v_fma_f32 v133, v121, v137, -v133
	v_fma_f32 v134, v127, v137, -v134
	v_fma_f32 v135, v129, v137, -v135
	v_fma_f32 v136, v131, v137, -v136
	v_cvt_pk_bf16_f32 v122, v133, v122
	v_cvt_pk_bf16_f32 v123, v134, v123
	v_cvt_pk_bf16_f32 v124, v135, v124
	v_cvt_pk_bf16_f32 v125, v136, v125
	ds_write_b128 v0, v[122:125] offset:43296
	ds_read_b128 v[122:125], v173 offset:7920
	v_add_u32_e32 v120, 1, v120
	v_cvt_f32_i32_e32 v120, v120
	s_waitcnt lgkmcnt(0)
	v_lshlrev_b32_e32 v133, 16, v122
	v_and_b32_e32 v122, 0xffff0000, v122
	v_sub_f32_e32 v126, v126, v122
	v_lshlrev_b32_e32 v122, 16, v123
	v_sub_f32_e32 v127, v127, v122
	v_and_b32_e32 v122, 0xffff0000, v123
	v_sub_f32_e32 v128, v128, v122
	v_lshlrev_b32_e32 v122, 16, v124
	v_sub_f32_e32 v129, v129, v122
	v_and_b32_e32 v122, 0xffff0000, v124
	v_sub_f32_e32 v130, v130, v122
	v_lshlrev_b32_e32 v122, 16, v125
	v_sub_f32_e32 v131, v131, v122
	v_and_b32_e32 v122, 0xffff0000, v125
	v_sub_f32_e32 v132, v132, v122
	ds_read_b128 v[122:125], v173 offset:10032
	v_rcp_iflag_f32_e32 v120, v120
	v_sub_f32_e32 v121, v121, v133
	s_waitcnt lgkmcnt(0)
	v_lshlrev_b32_e32 v133, 16, v122
	v_and_b32_e32 v122, 0xffff0000, v122
	v_lshlrev_b32_e32 v134, 16, v123
	v_and_b32_e32 v123, 0xffff0000, v123
	v_lshlrev_b32_e32 v135, 16, v124
	v_and_b32_e32 v124, 0xffff0000, v124
	v_add_f32_e32 v126, v126, v122
	v_lshlrev_b32_e32 v136, 16, v125
	v_and_b32_e32 v125, 0xffff0000, v125
	v_add_f32_e32 v121, v121, v133
	v_fma_f32 v122, v126, v120, -v122
	v_add_f32_e32 v126, v127, v134
	v_add_f32_e32 v127, v128, v123
	v_add_f32_e32 v128, v130, v124
	v_fma_f32 v121, v121, v120, -v133
	v_fma_f32 v123, v127, v120, -v123
	v_add_f32_e32 v127, v129, v135
	v_fma_f32 v124, v128, v120, -v124
	v_add_f32_e32 v128, v131, v136
	v_add_f32_e32 v129, v132, v125
	v_fma_f32 v126, v126, v120, -v134
	v_fma_f32 v127, v127, v120, -v135
	v_fma_f32 v128, v128, v120, -v136
	v_fma_f32 v125, v129, v120, -v125
	v_cvt_pk_bf16_f32 v120, v121, v122
	v_cvt_pk_bf16_f32 v121, v126, v123
	v_cvt_pk_bf16_f32 v122, v127, v124
	v_cvt_pk_bf16_f32 v123, v128, v125
	ds_write_b128 v0, v[120:123] offset:43824
	s_waitcnt lgkmcnt(0)
	s_barrier
	ds_read_b128 v[120:123], v170 offset:42240
	ds_read_b128 v[128:131], v170 offset:42304
	s_waitcnt lgkmcnt(1)
	v_mfma_f32_16x16x32_bf16 v[124:127], v[74:77], v[120:123], 0
	v_mfma_f32_16x16x32_bf16 v[120:123], v[78:81], v[120:123], 0
	s_waitcnt lgkmcnt(0)
	v_mfma_f32_16x16x32_bf16 v[124:127], v[62:65], v[128:131], v[124:127]
	v_mfma_f32_16x16x32_bf16 v[120:123], v[70:73], v[128:131], v[120:123]
	ds_read_b128 v[128:131], v170 offset:42368
	s_waitcnt lgkmcnt(0)
	v_mfma_f32_16x16x32_bf16 v[124:127], v[58:61], v[128:131], v[124:127]
	v_mfma_f32_16x16x32_bf16 v[120:123], v[66:69], v[128:131], v[120:123]
	ds_read_b128 v[128:131], v170 offset:42432
	s_waitcnt lgkmcnt(0)
	v_mfma_f32_16x16x32_bf16 v[124:127], v[46:49], v[128:131], v[124:127]
	v_mfma_f32_16x16x32_bf16 v[120:123], v[54:57], v[128:131], v[120:123]
	ds_read_b128 v[128:131], v170 offset:42496
	s_waitcnt lgkmcnt(0)
	v_mfma_f32_16x16x32_bf16 v[124:127], v[42:45], v[128:131], v[124:127]
	v_mfma_f32_16x16x32_bf16 v[120:123], v[50:53], v[128:131], v[120:123]
	ds_read_b128 v[128:131], v170 offset:42560
	s_waitcnt lgkmcnt(0)
	v_mfma_f32_16x16x32_bf16 v[124:127], v[30:33], v[128:131], v[124:127]
	v_mfma_f32_16x16x32_bf16 v[120:123], v[38:41], v[128:131], v[120:123]
	ds_read_b128 v[128:131], v170 offset:42624
	s_waitcnt lgkmcnt(0)
	v_mfma_f32_16x16x32_bf16 v[124:127], v[26:29], v[128:131], v[124:127]
	v_mfma_f32_16x16x32_bf16 v[120:123], v[34:37], v[128:131], v[120:123]
	ds_read_b128 v[128:131], v170 offset:42688
	s_waitcnt lgkmcnt(0)
	v_mfma_f32_16x16x32_bf16 v[124:127], v[10:13], v[128:131], v[124:127]
	v_mfma_f32_16x16x32_bf16 v[120:123], v[14:17], v[128:131], v[120:123]
	s_nop 6
	v_add_f32_e32 v0, v25, v127
	v_and_b32_e32 v127, 0xffff0000, v95
	v_mul_f32_e32 v128, 0xbfb8aa3b, v127
	v_exp_f32_e32 v128, v128
	v_mul_f32_e32 v0, v21, v0
	v_add_f32_e32 v124, v22, v124
	v_mul_f32_e32 v124, v18, v124
	v_add_f32_e32 v128, 1.0, v128
	v_rcp_f32_e32 v128, v128
	v_add_f32_e32 v125, v23, v125
	v_mul_f32_e32 v125, v19, v125
	v_lshlrev_b32_e32 v95, 16, v95
	v_mul_f32_e32 v127, v128, v127
	v_mul_f32_e32 v0, v127, v0
	v_lshlrev_b32_e32 v127, 16, v94
	v_mul_f32_e32 v128, 0xbfb8aa3b, v127
	v_exp_f32_e32 v128, v128
	v_and_b32_e32 v94, 0xffff0000, v94
	v_add_f32_e32 v126, v24, v126
	v_mul_f32_e32 v126, v20, v126
	v_add_f32_e32 v128, 1.0, v128
	v_rcp_f32_e32 v128, v128
	s_nop 0
	v_mul_f32_e32 v127, v128, v127
	v_mul_f32_e32 v124, v127, v124
	v_mul_f32_e32 v127, 0xbfb8aa3b, v94
	v_exp_f32_e32 v127, v127
	s_nop 0
	v_add_f32_e32 v127, 1.0, v127
	v_rcp_f32_e32 v127, v127
	s_nop 0
	v_mul_f32_e32 v94, v127, v94
	v_mul_f32_e32 v94, v94, v125
	v_mul_f32_e32 v125, 0xbfb8aa3b, v95
	v_exp_f32_e32 v125, v125
	v_cvt_pk_bf16_f32 v124, v124, v94
	v_add_f32_e32 v94, v6, v120
	v_add_f32_e32 v120, v8, v122
	v_add_f32_e32 v125, 1.0, v125
	v_rcp_f32_e32 v125, v125
	v_mul_f32_e32 v94, v2, v94
	v_mul_f32_e32 v120, v4, v120
	v_mul_f32_e32 v95, v125, v95
	v_mul_f32_e32 v95, v95, v126
	v_cvt_pk_bf16_f32 v125, v95, v0
	v_add_f32_e32 v95, v7, v121
	v_and_b32_e32 v121, 0xffff0000, v97
	v_mul_f32_e32 v122, 0xbfb8aa3b, v121
	v_exp_f32_e32 v122, v122
	v_add_f32_e32 v0, v9, v123
	v_mul_f32_e32 v0, v5, v0
	v_mul_f32_e32 v95, v3, v95
	v_add_f32_e32 v122, 1.0, v122
	v_rcp_f32_e32 v122, v122
	s_nop 0
	v_mul_f32_e32 v121, v122, v121
	v_mul_f32_e32 v0, v121, v0
	v_lshlrev_b32_e32 v121, 16, v96
	v_mul_f32_e32 v122, 0xbfb8aa3b, v121
	v_exp_f32_e32 v122, v122
	v_and_b32_e32 v96, 0xffff0000, v96
	v_add_f32_e32 v122, 1.0, v122
	v_rcp_f32_e32 v122, v122
	s_nop 0
	v_mul_f32_e32 v121, v122, v121
	v_mul_f32_e32 v94, v121, v94
	v_mul_f32_e32 v121, 0xbfb8aa3b, v96
	v_exp_f32_e32 v121, v121
	s_nop 0
	v_add_f32_e32 v121, 1.0, v121
	v_rcp_f32_e32 v121, v121
	s_nop 0
	v_mul_f32_e32 v96, v121, v96
	v_mul_f32_e32 v95, v96, v95
	v_lshlrev_b32_e32 v96, 16, v97
	v_mul_f32_e32 v97, 0xbfb8aa3b, v96
	v_exp_f32_e32 v97, v97
	v_cvt_pk_bf16_f32 v126, v94, v95
	s_nop 0
	v_add_f32_e32 v97, 1.0, v97
	v_rcp_f32_e32 v97, v97
	s_nop 0
	v_mul_f32_e32 v96, v97, v96
	v_mul_f32_e32 v96, v96, v120
	v_cvt_pk_bf16_f32 v127, v96, v0
	v_lshl_or_b32 v0, v171, 12, s0
	v_or_b32_e32 v0, 0x1c0000, v0
	v_lshl_add_u64 v[94:95], v[118:119], 0, v[0:1]
	ds_read_b128 v[118:121], v170 offset:50688
	v_add_co_u32_e32 v96, vcc, s9, v94
	s_nop 1
	v_addc_co_u32_e32 v97, vcc, 0, v95, vcc
	global_store_dwordx4 v[96:97], v[124:127], off offset:2560
	ds_read_b128 v[126:129], v170 offset:50752
	s_waitcnt lgkmcnt(1)
	v_mfma_f32_16x16x32_bf16 v[122:125], v[74:77], v[118:121], 0
	v_mfma_f32_16x16x32_bf16 v[118:121], v[78:81], v[118:121], 0
	s_waitcnt lgkmcnt(0)
	v_mfma_f32_16x16x32_bf16 v[122:125], v[62:65], v[126:129], v[122:125]
	v_mfma_f32_16x16x32_bf16 v[118:121], v[70:73], v[126:129], v[118:121]
	ds_read_b128 v[126:129], v170 offset:50816
	s_waitcnt lgkmcnt(0)
	v_mfma_f32_16x16x32_bf16 v[122:125], v[58:61], v[126:129], v[122:125]
	v_mfma_f32_16x16x32_bf16 v[118:121], v[66:69], v[126:129], v[118:121]
	ds_read_b128 v[126:129], v170 offset:50880
	s_waitcnt lgkmcnt(0)
	v_mfma_f32_16x16x32_bf16 v[122:125], v[46:49], v[126:129], v[122:125]
	v_mfma_f32_16x16x32_bf16 v[118:121], v[54:57], v[126:129], v[118:121]
	ds_read_b128 v[126:129], v170 offset:50944
	s_waitcnt lgkmcnt(0)
	v_mfma_f32_16x16x32_bf16 v[122:125], v[42:45], v[126:129], v[122:125]
	v_mfma_f32_16x16x32_bf16 v[118:121], v[50:53], v[126:129], v[118:121]
	ds_read_b128 v[126:129], v170 offset:51008
	s_waitcnt lgkmcnt(0)
	v_mfma_f32_16x16x32_bf16 v[122:125], v[30:33], v[126:129], v[122:125]
	v_mfma_f32_16x16x32_bf16 v[118:121], v[38:41], v[126:129], v[118:121]
	ds_read_b128 v[126:129], v170 offset:51072
	s_waitcnt lgkmcnt(0)
	v_mfma_f32_16x16x32_bf16 v[122:125], v[26:29], v[126:129], v[122:125]
	v_mfma_f32_16x16x32_bf16 v[118:121], v[34:37], v[126:129], v[118:121]
	ds_read_b128 v[126:129], v170 offset:51136
	s_waitcnt lgkmcnt(0)
	v_mfma_f32_16x16x32_bf16 v[122:125], v[10:13], v[126:129], v[122:125]
	v_mfma_f32_16x16x32_bf16 v[118:121], v[14:17], v[126:129], v[118:121]
	s_nop 6
	v_add_f32_e32 v97, v23, v123
	s_waitcnt vmcnt(11)
	v_and_b32_e32 v123, 0xffff0000, v91
	v_add_f32_e32 v96, v22, v122
	v_add_f32_e32 v122, v24, v124
	v_mul_f32_e32 v124, 0xbfb8aa3b, v123
	v_exp_f32_e32 v124, v124
	v_add_f32_e32 v0, v25, v125
	v_mul_f32_e32 v0, v21, v0
	v_mul_f32_e32 v96, v18, v96
	v_add_f32_e32 v124, 1.0, v124
	v_rcp_f32_e32 v124, v124
	v_mul_f32_e32 v97, v19, v97
	v_lshlrev_b32_e32 v91, 16, v91
	v_mul_f32_e32 v122, v20, v122
	v_mul_f32_e32 v123, v124, v123
	v_mul_f32_e32 v0, v123, v0
	v_lshlrev_b32_e32 v123, 16, v90
	v_mul_f32_e32 v124, 0xbfb8aa3b, v123
	v_exp_f32_e32 v124, v124
	v_and_b32_e32 v90, 0xffff0000, v90
	v_add_f32_e32 v124, 1.0, v124
	v_rcp_f32_e32 v124, v124
	s_nop 0
	v_mul_f32_e32 v123, v124, v123
	v_mul_f32_e32 v96, v123, v96
	v_mul_f32_e32 v123, 0xbfb8aa3b, v90
	v_exp_f32_e32 v123, v123
	s_nop 0
	v_add_f32_e32 v123, 1.0, v123
	v_rcp_f32_e32 v123, v123
	s_nop 0
	v_mul_f32_e32 v90, v123, v90
	v_mul_f32_e32 v90, v90, v97
	v_mul_f32_e32 v97, 0xbfb8aa3b, v91
	v_exp_f32_e32 v97, v97
	v_cvt_pk_bf16_f32 v90, v96, v90
	v_add_f32_e32 v96, v6, v118
	v_add_f32_e32 v118, v8, v120
	v_add_f32_e32 v97, 1.0, v97
	v_rcp_f32_e32 v97, v97
	v_mul_f32_e32 v96, v2, v96
	v_mul_f32_e32 v118, v4, v118
	v_mul_f32_e32 v91, v97, v91
	v_add_f32_e32 v97, v7, v119
	v_and_b32_e32 v119, 0xffff0000, v93
	v_mul_f32_e32 v120, 0xbfb8aa3b, v119
	v_exp_f32_e32 v120, v120
	v_mul_f32_e32 v91, v91, v122
	v_cvt_pk_bf16_f32 v91, v91, v0
	v_add_f32_e32 v0, v9, v121
	v_add_f32_e32 v120, 1.0, v120
	v_rcp_f32_e32 v120, v120
	v_mul_f32_e32 v0, v5, v0
	v_mul_f32_e32 v97, v3, v97
	v_lshlrev_b32_e32 v93, 16, v93
	v_mul_f32_e32 v119, v120, v119
	v_mul_f32_e32 v0, v119, v0
	v_lshlrev_b32_e32 v119, 16, v92
	v_mul_f32_e32 v120, 0xbfb8aa3b, v119
	v_exp_f32_e32 v120, v120
	v_and_b32_e32 v92, 0xffff0000, v92
	v_add_f32_e32 v120, 1.0, v120
	v_rcp_f32_e32 v120, v120
	s_nop 0
	v_mul_f32_e32 v119, v120, v119
	v_mul_f32_e32 v96, v119, v96
	v_mul_f32_e32 v119, 0xbfb8aa3b, v92
	v_exp_f32_e32 v119, v119
	s_nop 0
	v_add_f32_e32 v119, 1.0, v119
	v_rcp_f32_e32 v119, v119
	s_nop 0
	v_mul_f32_e32 v92, v119, v92
	v_mul_f32_e32 v92, v92, v97
	v_mul_f32_e32 v97, 0xbfb8aa3b, v93
	v_exp_f32_e32 v97, v97
	v_cvt_pk_bf16_f32 v92, v96, v92
	v_add_co_u32_e32 v96, vcc, s24, v94
	v_add_f32_e32 v97, 1.0, v97
	v_rcp_f32_e32 v97, v97
	s_nop 0
	v_mul_f32_e32 v93, v97, v93
	v_mul_f32_e32 v93, v93, v118
	v_cvt_pk_bf16_f32 v93, v93, v0
	v_addc_co_u32_e32 v97, vcc, 0, v95, vcc
	global_store_dwordx4 v[96:97], v[90:93], off offset:2560
	ds_read_b128 v[90:93], v170 offset:59136
	ds_read_b128 v[122:125], v170 offset:59200
	s_waitcnt lgkmcnt(1)
	v_mfma_f32_16x16x32_bf16 v[118:121], v[74:77], v[90:93], 0
	v_mfma_f32_16x16x32_bf16 v[90:93], v[78:81], v[90:93], 0
	s_waitcnt lgkmcnt(0)
	v_mfma_f32_16x16x32_bf16 v[118:121], v[62:65], v[122:125], v[118:121]
	v_mfma_f32_16x16x32_bf16 v[90:93], v[70:73], v[122:125], v[90:93]
	ds_read_b128 v[122:125], v170 offset:59264
	s_waitcnt lgkmcnt(0)
	v_mfma_f32_16x16x32_bf16 v[118:121], v[58:61], v[122:125], v[118:121]
	v_mfma_f32_16x16x32_bf16 v[90:93], v[66:69], v[122:125], v[90:93]
	ds_read_b128 v[122:125], v170 offset:59328
	s_waitcnt lgkmcnt(0)
	v_mfma_f32_16x16x32_bf16 v[118:121], v[46:49], v[122:125], v[118:121]
	v_mfma_f32_16x16x32_bf16 v[90:93], v[54:57], v[122:125], v[90:93]
	ds_read_b128 v[122:125], v170 offset:59392
	s_waitcnt lgkmcnt(0)
	v_mfma_f32_16x16x32_bf16 v[118:121], v[42:45], v[122:125], v[118:121]
	v_mfma_f32_16x16x32_bf16 v[90:93], v[50:53], v[122:125], v[90:93]
	ds_read_b128 v[122:125], v170 offset:59456
	s_waitcnt lgkmcnt(0)
	v_mfma_f32_16x16x32_bf16 v[118:121], v[30:33], v[122:125], v[118:121]
	v_mfma_f32_16x16x32_bf16 v[90:93], v[38:41], v[122:125], v[90:93]
	ds_read_b128 v[122:125], v170 offset:59520
	s_waitcnt lgkmcnt(0)
	v_mfma_f32_16x16x32_bf16 v[118:121], v[26:29], v[122:125], v[118:121]
	v_mfma_f32_16x16x32_bf16 v[90:93], v[34:37], v[122:125], v[90:93]
	ds_read_b128 v[122:125], v170 offset:59584
	s_waitcnt lgkmcnt(0)
	v_mfma_f32_16x16x32_bf16 v[118:121], v[10:13], v[122:125], v[118:121]
	v_mfma_f32_16x16x32_bf16 v[90:93], v[14:17], v[122:125], v[90:93]
	s_nop 6
	v_add_f32_e32 v97, v23, v119
	s_waitcnt vmcnt(11)
	v_and_b32_e32 v119, 0xffff0000, v87
	v_add_f32_e32 v96, v22, v118
	v_add_f32_e32 v118, v24, v120
	v_mul_f32_e32 v120, 0xbfb8aa3b, v119
	v_exp_f32_e32 v120, v120
	v_add_f32_e32 v0, v25, v121
	v_mul_f32_e32 v0, v21, v0
	v_mul_f32_e32 v96, v18, v96
	v_add_f32_e32 v120, 1.0, v120
	v_rcp_f32_e32 v120, v120
	v_mul_f32_e32 v97, v19, v97
	v_lshlrev_b32_e32 v87, 16, v87
	v_mul_f32_e32 v118, v20, v118
	v_mul_f32_e32 v119, v120, v119
	v_mul_f32_e32 v0, v119, v0
	v_lshlrev_b32_e32 v119, 16, v86
	v_mul_f32_e32 v120, 0xbfb8aa3b, v119
	v_exp_f32_e32 v120, v120
	v_and_b32_e32 v86, 0xffff0000, v86
	v_add_f32_e32 v90, v6, v90
	v_mul_f32_e32 v90, v2, v90
	v_add_f32_e32 v120, 1.0, v120
	v_rcp_f32_e32 v120, v120
	v_add_f32_e32 v91, v7, v91
	v_mul_f32_e32 v91, v3, v91
	v_add_f32_e32 v92, v8, v92
	v_mul_f32_e32 v119, v120, v119
	v_mul_f32_e32 v96, v119, v96
	v_mul_f32_e32 v119, 0xbfb8aa3b, v86
	v_exp_f32_e32 v119, v119
	v_mul_f32_e32 v92, v4, v92
	v_add_f32_e32 v119, 1.0, v119
	v_rcp_f32_e32 v119, v119
	s_nop 0
	v_mul_f32_e32 v86, v119, v86
	v_mul_f32_e32 v86, v86, v97
	v_mul_f32_e32 v97, 0xbfb8aa3b, v87
	v_exp_f32_e32 v97, v97
	v_cvt_pk_bf16_f32 v86, v96, v86
	s_nop 0
	v_add_f32_e32 v97, 1.0, v97
	v_rcp_f32_e32 v97, v97
	s_nop 0
	v_mul_f32_e32 v87, v97, v87
	v_mul_f32_e32 v87, v87, v118
	v_cvt_pk_bf16_f32 v87, v87, v0
	v_add_f32_e32 v0, v9, v93
	v_and_b32_e32 v93, 0xffff0000, v89
	v_mul_f32_e32 v96, 0xbfb8aa3b, v93
	v_exp_f32_e32 v96, v96
	v_mul_f32_e32 v0, v5, v0
	v_lshlrev_b32_e32 v89, 16, v89
	v_add_f32_e32 v96, 1.0, v96
	v_rcp_f32_e32 v96, v96
	s_nop 0
	v_mul_f32_e32 v93, v96, v93
	v_mul_f32_e32 v0, v93, v0
	v_lshlrev_b32_e32 v93, 16, v88
	v_mul_f32_e32 v96, 0xbfb8aa3b, v93
	v_exp_f32_e32 v96, v96
	v_and_b32_e32 v88, 0xffff0000, v88
	v_add_f32_e32 v96, 1.0, v96
	v_rcp_f32_e32 v96, v96
	s_nop 0
	v_mul_f32_e32 v93, v96, v93
	v_mul_f32_e32 v90, v93, v90
	v_mul_f32_e32 v93, 0xbfb8aa3b, v88
	v_exp_f32_e32 v93, v93
	s_nop 0
	v_add_f32_e32 v93, 1.0, v93
	v_rcp_f32_e32 v93, v93
	s_nop 0
	v_mul_f32_e32 v88, v93, v88
	v_mul_f32_e32 v88, v88, v91
	v_mul_f32_e32 v91, 0xbfb8aa3b, v89
	v_exp_f32_e32 v91, v91
	v_cvt_pk_bf16_f32 v88, v90, v88
	v_add_co_u32_e32 v90, vcc, s25, v94
	v_add_f32_e32 v91, 1.0, v91
	v_rcp_f32_e32 v91, v91
	s_nop 0
	v_mul_f32_e32 v89, v91, v89
	v_mul_f32_e32 v89, v89, v92
	v_cvt_pk_bf16_f32 v89, v89, v0
	v_addc_co_u32_e32 v91, vcc, 0, v95, vcc
	global_store_dwordx4 v[90:91], v[86:89], off offset:2560
	ds_read_b128 v[86:89], v169 offset:25344
	s_waitcnt lgkmcnt(0)
	v_mfma_f32_16x16x32_bf16 v[74:77], v[74:77], v[86:89], 0
	v_mfma_f32_16x16x32_bf16 v[78:81], v[78:81], v[86:89], 0
	ds_read_b128 v[86:89], v169 offset:25408
	s_waitcnt lgkmcnt(0)
	v_mfma_f32_16x16x32_bf16 v[62:65], v[62:65], v[86:89], v[74:77]
	s_nop 3
	ds_read_b128 v[74:77], v169 offset:25472
	v_mfma_f32_16x16x32_bf16 v[70:73], v[70:73], v[86:89], v[78:81]
	s_waitcnt lgkmcnt(0)
	v_mfma_f32_16x16x32_bf16 v[58:61], v[58:61], v[74:77], v[62:65]
	v_mfma_f32_16x16x32_bf16 v[62:65], v[66:69], v[74:77], v[70:73]
	ds_read_b128 v[66:69], v169 offset:25536
	s_waitcnt lgkmcnt(0)
	v_mfma_f32_16x16x32_bf16 v[46:49], v[46:49], v[66:69], v[58:61]
	s_nop 3
	ds_read_b128 v[58:61], v169 offset:25600
	v_mfma_f32_16x16x32_bf16 v[54:57], v[54:57], v[66:69], v[62:65]
	s_waitcnt lgkmcnt(0)
	v_mfma_f32_16x16x32_bf16 v[42:45], v[42:45], v[58:61], v[46:49]
	v_mfma_f32_16x16x32_bf16 v[46:49], v[50:53], v[58:61], v[54:57]
	ds_read_b128 v[50:53], v169 offset:25664
	s_waitcnt lgkmcnt(0)
	v_mfma_f32_16x16x32_bf16 v[30:33], v[30:33], v[50:53], v[42:45]
	s_nop 3
	ds_read_b128 v[42:45], v169 offset:25728
	v_mfma_f32_16x16x32_bf16 v[38:41], v[38:41], v[50:53], v[46:49]
	s_waitcnt lgkmcnt(0)
	v_mfma_f32_16x16x32_bf16 v[26:29], v[26:29], v[42:45], v[30:33]
	v_mfma_f32_16x16x32_bf16 v[30:33], v[34:37], v[42:45], v[38:41]
	ds_read_b128 v[34:37], v169 offset:25792
	s_waitcnt lgkmcnt(0)
	v_mfma_f32_16x16x32_bf16 v[10:13], v[10:13], v[34:37], v[26:29]
	v_mfma_f32_16x16x32_bf16 v[14:17], v[14:17], v[34:37], v[30:33]
	s_nop 6
	v_add_f32_e32 v0, v25, v13
	v_add_f32_e32 v10, v22, v10
	s_waitcnt vmcnt(11)
	v_and_b32_e32 v13, 0xffff0000, v83
	v_mul_f32_e32 v10, v18, v10
	v_mul_f32_e32 v18, 0xbfb8aa3b, v13
	v_exp_f32_e32 v18, v18
	v_mul_f32_e32 v0, v21, v0
	v_add_f32_e32 v11, v23, v11
	v_mul_f32_e32 v11, v19, v11
	v_add_f32_e32 v18, 1.0, v18
	v_rcp_f32_e32 v18, v18
	v_add_f32_e32 v12, v24, v12
	v_mul_f32_e32 v12, v20, v12
	v_add_f32_e32 v6, v6, v14
	v_mul_f32_e32 v13, v18, v13
	v_mul_f32_e32 v0, v13, v0
	v_lshlrev_b32_e32 v13, 16, v82
	v_mul_f32_e32 v18, 0xbfb8aa3b, v13
	v_exp_f32_e32 v18, v18
	v_mul_f32_e32 v2, v2, v6
	v_add_f32_e32 v7, v7, v15
	v_mul_f32_e32 v3, v3, v7
	v_add_f32_e32 v18, 1.0, v18
	v_rcp_f32_e32 v18, v18
	v_add_f32_e32 v8, v8, v16
	v_mul_f32_e32 v4, v4, v8
	v_mul_f32_e32 v13, v18, v13
	v_mul_f32_e32 v10, v13, v10
	v_and_b32_e32 v13, 0xffff0000, v82
	v_mul_f32_e32 v18, 0xbfb8aa3b, v13
	v_exp_f32_e32 v18, v18
	s_nop 0
	v_add_f32_e32 v18, 1.0, v18
	v_rcp_f32_e32 v18, v18
	s_nop 0
	v_mul_f32_e32 v13, v18, v13
	v_mul_f32_e32 v11, v13, v11
	v_lshlrev_b32_e32 v13, 16, v83
	v_mul_f32_e32 v18, 0xbfb8aa3b, v13
	v_exp_f32_e32 v18, v18
	v_cvt_pk_bf16_f32 v10, v10, v11
	s_nop 0
	v_add_f32_e32 v18, 1.0, v18
	v_rcp_f32_e32 v18, v18
	s_nop 0
	v_mul_f32_e32 v13, v18, v13
	v_mul_f32_e32 v12, v13, v12
	v_cvt_pk_bf16_f32 v11, v12, v0
	v_add_f32_e32 v0, v9, v17
	v_mul_f32_e32 v0, v5, v0
	v_and_b32_e32 v5, 0xffff0000, v85
	v_mul_f32_e32 v6, 0xbfb8aa3b, v5
	v_exp_f32_e32 v6, v6
	s_nop 0
	v_add_f32_e32 v6, 1.0, v6
	v_rcp_f32_e32 v6, v6
	s_nop 0
	v_mul_f32_e32 v5, v6, v5
	v_mul_f32_e32 v0, v5, v0
	v_lshlrev_b32_e32 v5, 16, v84
	v_mul_f32_e32 v6, 0xbfb8aa3b, v5
	v_exp_f32_e32 v6, v6
	s_nop 0
	v_add_f32_e32 v6, 1.0, v6
	v_rcp_f32_e32 v6, v6
	s_nop 0
	v_mul_f32_e32 v5, v6, v5
	v_mul_f32_e32 v2, v5, v2
	v_and_b32_e32 v5, 0xffff0000, v84
	v_mul_f32_e32 v6, 0xbfb8aa3b, v5
	v_exp_f32_e32 v6, v6
	s_nop 0
	v_add_f32_e32 v6, 1.0, v6
	v_rcp_f32_e32 v6, v6
	s_nop 0
	v_mul_f32_e32 v5, v6, v5
	v_mul_f32_e32 v3, v5, v3
	v_lshlrev_b32_e32 v5, 16, v85
	v_mul_f32_e32 v6, 0xbfb8aa3b, v5
	v_exp_f32_e32 v6, v6
	v_cvt_pk_bf16_f32 v12, v2, v3
	v_add_co_u32_e32 v2, vcc, 0x6030000, v94
	v_add_f32_e32 v6, 1.0, v6
	v_rcp_f32_e32 v6, v6
	v_addc_co_u32_e32 v3, vcc, 0, v95, vcc
	v_mul_f32_e32 v5, v6, v5
	v_mul_f32_e32 v4, v5, v4
	v_cvt_pk_bf16_f32 v13, v4, v0
	global_store_dwordx4 v[2:3], v[10:13], off offset:2560
	s_waitcnt vmcnt(7)
	ds_write_b128 v164, v[98:101] offset:8448
	s_waitcnt vmcnt(6)
	ds_write_b128 v165, v[102:105] offset:8448
	s_waitcnt vmcnt(5)
	ds_write_b128 v166, v[106:109] offset:8448
	s_waitcnt vmcnt(4)
	ds_write_b128 v167, v[110:113] offset:8448
	ds_write_b128 v168, v[114:117]
	s_waitcnt lgkmcnt(0)
	s_barrier
	s_branch .LBB0_118
